# v4 + K-loop issue-slot trim: drop duplicate lgkmcnt(0) after pre-MFMA barrier, drop s_nop after m0 write by reordering address add; dtype comment
# baseline (speedup 1.0000x reference)
.LBB0_38:
	s_add_u32 s10, s8, 0x100
	s_addc_u32 s11, s9, 0
	s_add_i32 s48, 0, 0x10000
	s_cmp_eq_u32 s22, 40
	s_cselect_b32 s15, s1, s11
	s_cselect_b32 s14, s0, s10
	s_cselect_b32 s13, s37, s90
	s_cselect_b32 s12, s36, s21
	s_add_i32 s49, 0, 0x14000
	v_add_u32_e32 v154, s48, v143
	v_add_u32_e32 v158, s49, v143
	ds_read_b128 v[138:141], v154
	ds_read_b128 v[146:149], v154 offset:1024
	ds_read_b128 v[150:153], v154 offset:2048
	ds_read_b128 v[154:157], v154 offset:3072
	ds_read_b128 v[162:165], v158
	ds_read_b128 v[166:169], v158 offset:1024
	ds_read_b128 v[170:173], v158 offset:2048
	ds_read_b128 v[174:177], v158 offset:3072
	v_lshl_add_u64 v[158:159], s[8:9], 0, v[136:137]
	s_add_i32 m0, s29, 0xc000
	ds_read_b128 v[178:181], v145
	ds_read_b128 v[182:185], v145 offset:1024
	ds_read_b128 v[186:189], v145 offset:2048
	ds_read_b128 v[190:193], v145 offset:3072
	ds_read_b128 v[194:197], v145 offset:4096
	ds_read_b128 v[198:201], v145 offset:5120
	ds_read_b128 v[202:205], v145 offset:6144
	ds_read_b128 v[206:209], v145 offset:7168
	global_load_lds_dwordx4 v[158:159], off
	s_add_i32 m0, s29, 0xe000
	v_lshl_add_u64 v[158:159], s[8:9], 0, v[134:135]
	global_load_lds_dwordx4 v[158:159], off
	s_waitcnt vmcnt(8)
	s_waitcnt lgkmcnt(0)
	s_barrier
	v_mfma_f32_16x16x32_bf16 v[124:127], v[138:141], v[178:181], v[124:127]
	v_mfma_f32_16x16x32_bf16 v[120:123], v[150:153], v[178:181], v[120:123]
	v_mfma_f32_16x16x32_bf16 v[108:111], v[138:141], v[186:189], v[108:111]
	v_mfma_f32_16x16x32_bf16 v[104:107], v[150:153], v[186:189], v[104:107]
	v_mfma_f32_16x16x32_bf16 v[92:95], v[138:141], v[194:197], v[92:95]
	v_mfma_f32_16x16x32_bf16 v[88:91], v[150:153], v[194:197], v[88:91]
	v_mfma_f32_16x16x32_bf16 v[76:79], v[138:141], v[202:205], v[76:79]
	v_mfma_f32_16x16x32_bf16 v[72:75], v[150:153], v[202:205], v[72:75]
	v_mfma_f32_16x16x32_bf16 v[124:127], v[146:149], v[182:185], v[124:127]
	v_mfma_f32_16x16x32_bf16 v[120:123], v[154:157], v[182:185], v[120:123]
	v_mfma_f32_16x16x32_bf16 v[108:111], v[146:149], v[190:193], v[108:111]
	v_mfma_f32_16x16x32_bf16 v[104:107], v[154:157], v[190:193], v[104:107]
	v_mfma_f32_16x16x32_bf16 v[92:95], v[146:149], v[198:201], v[92:95]
	v_mfma_f32_16x16x32_bf16 v[88:91], v[154:157], v[198:201], v[88:91]
	v_mfma_f32_16x16x32_bf16 v[76:79], v[146:149], v[206:209], v[76:79]
	v_mfma_f32_16x16x32_bf16 v[72:75], v[154:157], v[206:209], v[72:75]
	v_mfma_f32_16x16x32_bf16 v[116:119], v[162:165], v[178:181], v[116:119]
	v_mfma_f32_16x16x32_bf16 v[112:115], v[170:173], v[178:181], v[112:115]
	v_mfma_f32_16x16x32_bf16 v[100:103], v[162:165], v[186:189], v[100:103]
	v_mfma_f32_16x16x32_bf16 v[96:99], v[170:173], v[186:189], v[96:99]
	v_mfma_f32_16x16x32_bf16 v[84:87], v[162:165], v[194:197], v[84:87]
	v_mfma_f32_16x16x32_bf16 v[80:83], v[170:173], v[194:197], v[80:83]
	v_mfma_f32_16x16x32_bf16 v[68:71], v[162:165], v[202:205], v[68:71]
	v_mfma_f32_16x16x32_bf16 v[64:67], v[170:173], v[202:205], v[64:67]
	v_mfma_f32_16x16x32_bf16 v[116:119], v[166:169], v[182:185], v[116:119]
	v_mfma_f32_16x16x32_bf16 v[112:115], v[174:177], v[182:185], v[112:115]
	v_mfma_f32_16x16x32_bf16 v[100:103], v[166:169], v[190:193], v[100:103]
	v_mfma_f32_16x16x32_bf16 v[96:99], v[174:177], v[190:193], v[96:99]
	v_mfma_f32_16x16x32_bf16 v[84:87], v[166:169], v[198:201], v[84:87]
	v_mfma_f32_16x16x32_bf16 v[80:83], v[174:177], v[198:201], v[80:83]
	v_mfma_f32_16x16x32_bf16 v[68:71], v[166:169], v[206:209], v[68:71]
	v_mfma_f32_16x16x32_bf16 v[64:67], v[174:177], v[206:209], v[64:67]
	s_barrier
	s_add_i32 s8, s48, s28
	v_lshl_add_u64 v[158:159], s[12:13], 0, v[160:161]
	s_mov_b32 m0, s8
	ds_read_b128 v[178:181], v145 offset:16384
	ds_read_b128 v[182:185], v145 offset:17408
	ds_read_b128 v[186:189], v145 offset:18432
	ds_read_b128 v[190:193], v145 offset:19456
	ds_read_b128 v[194:197], v145 offset:20480
	ds_read_b128 v[198:201], v145 offset:21504
	ds_read_b128 v[202:205], v145 offset:22528
	ds_read_b128 v[206:209], v145 offset:23552
	global_load_lds_dwordx4 v[158:159], off
	s_add_i32 m0, s8, 0x2000
	s_add_u32 s8, s12, 0xb0000
	v_lshl_add_u64 v[210:211], s[12:13], 0, v[132:133]
	s_addc_u32 s9, s13, 0
	s_add_i32 s48, s49, s28
	global_load_lds_dwordx4 v[210:211], off
	v_lshl_add_u64 v[212:213], s[8:9], 0, v[160:161]
	s_mov_b32 m0, s48
	v_lshl_add_u64 v[214:215], s[14:15], 0, v[130:131]
	global_load_lds_dwordx4 v[212:213], off
	s_add_i32 m0, s48, 0x2000
	v_lshl_add_u64 v[212:213], s[8:9], 0, v[132:133]
	global_load_lds_dwordx4 v[212:213], off
	s_mov_b32 m0, s29
	v_lshl_add_u64 v[212:213], s[14:15], 0, v[128:129]
	global_load_lds_dwordx4 v[212:213], off
	s_mov_b32 m0, s30
	s_nop 0
	global_load_lds_dwordx4 v[214:215], off
	s_waitcnt vmcnt(8)
	s_waitcnt lgkmcnt(0)
	s_barrier
	v_mfma_f32_16x16x32_bf16 v[60:63], v[138:141], v[178:181], v[60:63]
	v_mfma_f32_16x16x32_bf16 v[56:59], v[150:153], v[178:181], v[56:59]
	v_mfma_f32_16x16x32_bf16 v[44:47], v[138:141], v[186:189], v[44:47]
	v_mfma_f32_16x16x32_bf16 v[40:43], v[150:153], v[186:189], v[40:43]
	v_mfma_f32_16x16x32_bf16 v[28:31], v[138:141], v[194:197], v[28:31]
	v_mfma_f32_16x16x32_bf16 v[24:27], v[150:153], v[194:197], v[24:27]
	v_mfma_f32_16x16x32_bf16 v[12:15], v[138:141], v[202:205], v[12:15]
	v_mfma_f32_16x16x32_bf16 v[8:11], v[150:153], v[202:205], v[8:11]
	v_mfma_f32_16x16x32_bf16 v[60:63], v[146:149], v[182:185], v[60:63]
	v_mfma_f32_16x16x32_bf16 v[56:59], v[154:157], v[182:185], v[56:59]
	v_mfma_f32_16x16x32_bf16 v[44:47], v[146:149], v[190:193], v[44:47]
	v_mfma_f32_16x16x32_bf16 v[40:43], v[154:157], v[190:193], v[40:43]
	v_mfma_f32_16x16x32_bf16 v[28:31], v[146:149], v[198:201], v[28:31]
	v_mfma_f32_16x16x32_bf16 v[24:27], v[154:157], v[198:201], v[24:27]
	v_mfma_f32_16x16x32_bf16 v[12:15], v[146:149], v[206:209], v[12:15]
	v_mfma_f32_16x16x32_bf16 v[8:11], v[154:157], v[206:209], v[8:11]
	v_mfma_f32_16x16x32_bf16 v[52:55], v[162:165], v[178:181], v[52:55]
	v_mfma_f32_16x16x32_bf16 v[48:51], v[170:173], v[178:181], v[48:51]
	v_mfma_f32_16x16x32_bf16 v[36:39], v[162:165], v[186:189], v[36:39]
	v_mfma_f32_16x16x32_bf16 v[32:35], v[170:173], v[186:189], v[32:35]
	v_mfma_f32_16x16x32_bf16 v[20:23], v[162:165], v[194:197], v[20:23]
	v_mfma_f32_16x16x32_bf16 v[16:19], v[170:173], v[194:197], v[16:19]
	v_mfma_f32_16x16x32_bf16 v[4:7], v[162:165], v[202:205], v[4:7]
	v_mfma_f32_16x16x32_bf16 v[0:3], v[170:173], v[202:205], v[0:3]
	v_mfma_f32_16x16x32_bf16 v[52:55], v[166:169], v[182:185], v[52:55]
	v_mfma_f32_16x16x32_bf16 v[48:51], v[174:177], v[182:185], v[48:51]
	v_mfma_f32_16x16x32_bf16 v[36:39], v[166:169], v[190:193], v[36:39]
	v_mfma_f32_16x16x32_bf16 v[32:35], v[174:177], v[190:193], v[32:35]
	v_mfma_f32_16x16x32_bf16 v[20:23], v[166:169], v[198:201], v[20:23]
	v_mfma_f32_16x16x32_bf16 v[16:19], v[174:177], v[198:201], v[16:19]
	v_mfma_f32_16x16x32_bf16 v[4:7], v[166:169], v[206:209], v[4:7]
	v_mfma_f32_16x16x32_bf16 v[0:3], v[174:177], v[206:209], v[0:3]
	s_barrier
	s_add_i32 s48, 0, 0x18000
	s_add_i32 s49, 0, 0x1c000
	v_add_u32_e32 v154, s48, v143
	v_add_u32_e32 v174, s49, v143
	ds_read_b128 v[138:141], v154
	ds_read_b128 v[146:149], v154 offset:1024
	ds_read_b128 v[150:153], v154 offset:2048
	ds_read_b128 v[154:157], v154 offset:3072
	ds_read_b128 v[162:165], v174
	ds_read_b128 v[166:169], v174 offset:1024
	ds_read_b128 v[170:173], v174 offset:2048
	ds_read_b128 v[174:177], v174 offset:3072
	s_add_u32 s8, s14, 0xb0000
	s_addc_u32 s9, s15, 0
	s_mov_b32 m0, s31
	v_lshl_add_u64 v[216:217], s[8:9], 0, v[128:129]
	ds_read_b128 v[178:181], v145 offset:32768
	ds_read_b128 v[182:185], v145 offset:33792
	ds_read_b128 v[186:189], v145 offset:34816
	ds_read_b128 v[190:193], v145 offset:35840
	ds_read_b128 v[194:197], v145 offset:36864
	ds_read_b128 v[198:201], v145 offset:37888
	ds_read_b128 v[202:205], v145 offset:38912
	ds_read_b128 v[206:209], v145 offset:39936
	global_load_lds_dwordx4 v[216:217], off
	s_mov_b32 m0, s33
	v_lshl_add_u64 v[216:217], s[8:9], 0, v[130:131]
	global_load_lds_dwordx4 v[216:217], off
	s_waitcnt vmcnt(8)
	s_waitcnt lgkmcnt(0)
	s_barrier
	v_mfma_f32_16x16x32_bf16 v[124:127], v[138:141], v[178:181], v[124:127]
	v_mfma_f32_16x16x32_bf16 v[120:123], v[150:153], v[178:181], v[120:123]
	v_mfma_f32_16x16x32_bf16 v[108:111], v[138:141], v[186:189], v[108:111]
	v_mfma_f32_16x16x32_bf16 v[104:107], v[150:153], v[186:189], v[104:107]
	v_mfma_f32_16x16x32_bf16 v[92:95], v[138:141], v[194:197], v[92:95]
	v_mfma_f32_16x16x32_bf16 v[88:91], v[150:153], v[194:197], v[88:91]
	v_mfma_f32_16x16x32_bf16 v[76:79], v[138:141], v[202:205], v[76:79]
	v_mfma_f32_16x16x32_bf16 v[72:75], v[150:153], v[202:205], v[72:75]
	v_mfma_f32_16x16x32_bf16 v[124:127], v[146:149], v[182:185], v[124:127]
	v_mfma_f32_16x16x32_bf16 v[120:123], v[154:157], v[182:185], v[120:123]
	v_mfma_f32_16x16x32_bf16 v[108:111], v[146:149], v[190:193], v[108:111]
	v_mfma_f32_16x16x32_bf16 v[104:107], v[154:157], v[190:193], v[104:107]
	v_mfma_f32_16x16x32_bf16 v[92:95], v[146:149], v[198:201], v[92:95]
	v_mfma_f32_16x16x32_bf16 v[88:91], v[154:157], v[198:201], v[88:91]
	v_mfma_f32_16x16x32_bf16 v[76:79], v[146:149], v[206:209], v[76:79]
	v_mfma_f32_16x16x32_bf16 v[72:75], v[154:157], v[206:209], v[72:75]
	v_mfma_f32_16x16x32_bf16 v[116:119], v[162:165], v[178:181], v[116:119]
	v_mfma_f32_16x16x32_bf16 v[112:115], v[170:173], v[178:181], v[112:115]
	v_mfma_f32_16x16x32_bf16 v[100:103], v[162:165], v[186:189], v[100:103]
	v_mfma_f32_16x16x32_bf16 v[96:99], v[170:173], v[186:189], v[96:99]
	v_mfma_f32_16x16x32_bf16 v[84:87], v[162:165], v[194:197], v[84:87]
	v_mfma_f32_16x16x32_bf16 v[80:83], v[170:173], v[194:197], v[80:83]
	v_mfma_f32_16x16x32_bf16 v[68:71], v[162:165], v[202:205], v[68:71]
	v_mfma_f32_16x16x32_bf16 v[64:67], v[170:173], v[202:205], v[64:67]
	v_mfma_f32_16x16x32_bf16 v[116:119], v[166:169], v[182:185], v[116:119]
	v_mfma_f32_16x16x32_bf16 v[112:115], v[174:177], v[182:185], v[112:115]
	v_mfma_f32_16x16x32_bf16 v[100:103], v[166:169], v[190:193], v[100:103]
	v_mfma_f32_16x16x32_bf16 v[96:99], v[174:177], v[190:193], v[96:99]
	v_mfma_f32_16x16x32_bf16 v[84:87], v[166:169], v[198:201], v[84:87]
	v_mfma_f32_16x16x32_bf16 v[80:83], v[174:177], v[198:201], v[80:83]
	v_mfma_f32_16x16x32_bf16 v[68:71], v[166:169], v[206:209], v[68:71]
	v_mfma_f32_16x16x32_bf16 v[64:67], v[174:177], v[206:209], v[64:67]
	s_barrier
	s_add_i32 s8, s48, s28
	v_lshl_add_u64 v[158:159], v[158:159], 0, s[88:89]
	s_mov_b32 m0, s8
	ds_read_b128 v[178:181], v145 offset:49152
	ds_read_b128 v[182:185], v145 offset:50176
	ds_read_b128 v[186:189], v145 offset:51200
	ds_read_b128 v[190:193], v145 offset:52224
	ds_read_b128 v[194:197], v145 offset:53248
	ds_read_b128 v[198:201], v145 offset:54272
	ds_read_b128 v[202:205], v145 offset:55296
	ds_read_b128 v[206:209], v145 offset:56320
	global_load_lds_dwordx4 v[158:159], off
	s_add_i32 m0, s8, 0x2000
	s_add_u32 s8, s12, 0xb0080
	v_lshl_add_u64 v[158:159], v[210:211], 0, s[88:89]
	s_addc_u32 s9, s13, 0
	s_add_i32 s12, s49, s28
	global_load_lds_dwordx4 v[158:159], off
	s_mov_b32 m0, s12
	v_lshl_add_u64 v[158:159], s[8:9], 0, v[160:161]
	global_load_lds_dwordx4 v[158:159], off
	s_add_i32 m0, s12, 0x2000
	v_lshl_add_u64 v[158:159], s[8:9], 0, v[132:133]
	global_load_lds_dwordx4 v[158:159], off
	s_mov_b32 m0, s34
	v_lshl_add_u64 v[158:159], v[212:213], 0, s[88:89]
	global_load_lds_dwordx4 v[158:159], off
	s_mov_b32 m0, s35
	v_lshl_add_u64 v[158:159], v[214:215], 0, s[88:89]
	global_load_lds_dwordx4 v[158:159], off
	s_waitcnt vmcnt(8)
	s_waitcnt lgkmcnt(0)
	s_barrier
	v_mfma_f32_16x16x32_bf16 v[60:63], v[138:141], v[178:181], v[60:63]
	v_mfma_f32_16x16x32_bf16 v[56:59], v[150:153], v[178:181], v[56:59]
	v_mfma_f32_16x16x32_bf16 v[44:47], v[138:141], v[186:189], v[44:47]
	v_mfma_f32_16x16x32_bf16 v[40:43], v[150:153], v[186:189], v[40:43]
	v_mfma_f32_16x16x32_bf16 v[28:31], v[138:141], v[194:197], v[28:31]
	v_mfma_f32_16x16x32_bf16 v[24:27], v[150:153], v[194:197], v[24:27]
	v_mfma_f32_16x16x32_bf16 v[12:15], v[138:141], v[202:205], v[12:15]
	v_mfma_f32_16x16x32_bf16 v[8:11], v[150:153], v[202:205], v[8:11]
	v_mfma_f32_16x16x32_bf16 v[60:63], v[146:149], v[182:185], v[60:63]
	v_mfma_f32_16x16x32_bf16 v[56:59], v[154:157], v[182:185], v[56:59]
	v_mfma_f32_16x16x32_bf16 v[44:47], v[146:149], v[190:193], v[44:47]
	v_mfma_f32_16x16x32_bf16 v[40:43], v[154:157], v[190:193], v[40:43]
	v_mfma_f32_16x16x32_bf16 v[28:31], v[146:149], v[198:201], v[28:31]
	v_mfma_f32_16x16x32_bf16 v[24:27], v[154:157], v[198:201], v[24:27]
	v_mfma_f32_16x16x32_bf16 v[12:15], v[146:149], v[206:209], v[12:15]
	v_mfma_f32_16x16x32_bf16 v[8:11], v[154:157], v[206:209], v[8:11]
	v_mfma_f32_16x16x32_bf16 v[52:55], v[162:165], v[178:181], v[52:55]
	v_mfma_f32_16x16x32_bf16 v[48:51], v[170:173], v[178:181], v[48:51]
	v_mfma_f32_16x16x32_bf16 v[36:39], v[162:165], v[186:189], v[36:39]
	v_mfma_f32_16x16x32_bf16 v[32:35], v[170:173], v[186:189], v[32:35]
	v_mfma_f32_16x16x32_bf16 v[20:23], v[162:165], v[194:197], v[20:23]
	v_mfma_f32_16x16x32_bf16 v[16:19], v[170:173], v[194:197], v[16:19]
	v_mfma_f32_16x16x32_bf16 v[4:7], v[162:165], v[202:205], v[4:7]
	v_mfma_f32_16x16x32_bf16 v[0:3], v[170:173], v[202:205], v[0:3]
	v_mfma_f32_16x16x32_bf16 v[52:55], v[166:169], v[182:185], v[52:55]
	v_mfma_f32_16x16x32_bf16 v[48:51], v[174:177], v[182:185], v[48:51]
	v_mfma_f32_16x16x32_bf16 v[36:39], v[166:169], v[190:193], v[36:39]
	v_mfma_f32_16x16x32_bf16 v[32:35], v[174:177], v[190:193], v[32:35]
	v_mfma_f32_16x16x32_bf16 v[20:23], v[166:169], v[198:201], v[20:23]
	v_mfma_f32_16x16x32_bf16 v[16:19], v[174:177], v[198:201], v[16:19]
	v_mfma_f32_16x16x32_bf16 v[4:7], v[166:169], v[206:209], v[4:7]
	v_mfma_f32_16x16x32_bf16 v[0:3], v[174:177], v[206:209], v[0:3]
	s_barrier
	s_add_i32 s22, s22, 2
	s_add_u32 s21, s21, 0x100
	s_addc_u32 s90, s90, 0
	s_cmp_gt_u32 s22, 41
	s_mov_b64 s[8:9], s[10:11]
	s_cbranch_scc0 .LBB0_38
	v_lshl_add_u32 v140, s44, 8, v142
	v_lshl_or_b32 v138, s45, 8, v144
	v_lshlrev_b32_e32 v139, 12, v140
	v_lshl_add_u32 v139, v138, 2, v139
	v_lshlrev_b32_e32 v141, 11, v140
	v_lshl_add_u32 v138, v138, 1, v141
	s_mov_b64 s[8:9], s[4:5]
	global_load_dwordx4 v[146:149], v138, s[8:9]
	global_load_dwordx4 v[150:153], v138, s[8:9] offset:256
	s_add_u32 s8, s8, 0x8000
	s_addc_u32 s9, s9, 0
	global_load_dwordx4 v[154:157], v138, s[8:9]
	global_load_dwordx4 v[162:165], v138, s[8:9] offset:256
	s_add_u32 s8, s8, 0x8000
	s_addc_u32 s9, s9, 0
	global_load_dwordx4 v[166:169], v138, s[8:9]
	global_load_dwordx4 v[174:177], v138, s[8:9] offset:256
	s_add_u32 s8, s8, 0x8000
	s_addc_u32 s9, s9, 0
	global_load_dwordx4 v[178:181], v138, s[8:9]
	global_load_dwordx4 v[182:185], v138, s[8:9] offset:256
	s_add_u32 s8, s8, 0x28000
	s_addc_u32 s9, s9, 0
	global_load_dwordx4 v[186:189], v138, s[8:9]
	global_load_dwordx4 v[190:193], v138, s[8:9] offset:256
	s_add_u32 s8, s8, 0x8000
	s_addc_u32 s9, s9, 0
	global_load_dwordx4 v[194:197], v138, s[8:9]
	global_load_dwordx4 v[198:201], v138, s[8:9] offset:256
	s_add_u32 s8, s8, 0x8000
	s_addc_u32 s9, s9, 0
	global_load_dwordx4 v[202:205], v138, s[8:9]
	global_load_dwordx4 v[206:209], v138, s[8:9] offset:256
	s_add_u32 s8, s8, 0x8000
	s_addc_u32 s9, s9, 0
	global_load_dwordx4 v[210:213], v138, s[8:9]
	global_load_dwordx4 v[214:217], v138, s[8:9] offset:256
	s_and_b64 vcc, exec, s[6:7]
	s_cbranch_vccz .LBB0_41
	s_barrier

.LBB0_56:
	s_add_u32 s12, s10, 0xfffc0080
	s_addc_u32 s13, s11, -1
	s_add_i32 s48, 0, 0x10000
	s_cmp_eq_u32 s22, 12
	s_cselect_b32 s15, s20, s13
	s_cselect_b32 s14, s37, s12
	s_cselect_b32 s13, s41, s21
	s_cselect_b32 s12, s91, s96
	s_add_i32 s50, 0, 0x14000
	v_add_u32_e32 v154, s48, v147
	v_add_u32_e32 v158, s50, v147
	ds_read_b128 v[138:141], v154
	ds_read_b128 v[142:145], v154 offset:1024
	ds_read_b128 v[150:153], v154 offset:2048
	ds_read_b128 v[154:157], v154 offset:3072
	ds_read_b128 v[162:165], v158
	ds_read_b128 v[166:169], v158 offset:1024
	ds_read_b128 v[170:173], v158 offset:2048
	ds_read_b128 v[174:177], v158 offset:3072
	v_lshl_add_u64 v[158:159], s[10:11], 0, v[136:137]
	s_add_i32 m0, s30, 0xc000
	ds_read_b128 v[178:181], v149
	ds_read_b128 v[182:185], v149 offset:1024
	ds_read_b128 v[186:189], v149 offset:2048
	ds_read_b128 v[190:193], v149 offset:3072
	ds_read_b128 v[194:197], v149 offset:4096
	ds_read_b128 v[198:201], v149 offset:5120
	ds_read_b128 v[202:205], v149 offset:6144
	ds_read_b128 v[206:209], v149 offset:7168
	global_load_lds_dwordx4 v[158:159], off
	s_add_i32 m0, s30, 0xe000
	v_lshl_add_u64 v[158:159], s[10:11], 0, v[134:135]
	global_load_lds_dwordx4 v[158:159], off
	s_waitcnt vmcnt(8)
	s_waitcnt lgkmcnt(0)
	s_barrier
	v_mfma_f32_16x16x32_bf16 v[124:127], v[138:141], v[178:181], v[124:127]
	v_mfma_f32_16x16x32_bf16 v[116:119], v[150:153], v[178:181], v[116:119]
	v_mfma_f32_16x16x32_bf16 v[108:111], v[138:141], v[186:189], v[108:111]
	v_mfma_f32_16x16x32_bf16 v[100:103], v[150:153], v[186:189], v[100:103]
	v_mfma_f32_16x16x32_bf16 v[92:95], v[138:141], v[194:197], v[92:95]
	v_mfma_f32_16x16x32_bf16 v[84:87], v[150:153], v[194:197], v[84:87]
	v_mfma_f32_16x16x32_bf16 v[76:79], v[138:141], v[202:205], v[76:79]
	v_mfma_f32_16x16x32_bf16 v[64:67], v[150:153], v[202:205], v[64:67]
	v_mfma_f32_16x16x32_bf16 v[124:127], v[142:145], v[182:185], v[124:127]
	v_mfma_f32_16x16x32_bf16 v[116:119], v[154:157], v[182:185], v[116:119]
	v_mfma_f32_16x16x32_bf16 v[108:111], v[142:145], v[190:193], v[108:111]
	v_mfma_f32_16x16x32_bf16 v[100:103], v[154:157], v[190:193], v[100:103]
	v_mfma_f32_16x16x32_bf16 v[92:95], v[142:145], v[198:201], v[92:95]
	v_mfma_f32_16x16x32_bf16 v[84:87], v[154:157], v[198:201], v[84:87]
	v_mfma_f32_16x16x32_bf16 v[76:79], v[142:145], v[206:209], v[76:79]
	v_mfma_f32_16x16x32_bf16 v[64:67], v[154:157], v[206:209], v[64:67]
	v_mfma_f32_16x16x32_bf16 v[120:123], v[162:165], v[178:181], v[120:123]
	v_mfma_f32_16x16x32_bf16 v[112:115], v[170:173], v[178:181], v[112:115]
	v_mfma_f32_16x16x32_bf16 v[104:107], v[162:165], v[186:189], v[104:107]
	v_mfma_f32_16x16x32_bf16 v[96:99], v[170:173], v[186:189], v[96:99]
	v_mfma_f32_16x16x32_bf16 v[88:91], v[162:165], v[194:197], v[88:91]
	v_mfma_f32_16x16x32_bf16 v[80:83], v[170:173], v[194:197], v[80:83]
	v_mfma_f32_16x16x32_bf16 v[72:75], v[162:165], v[202:205], v[72:75]
	v_mfma_f32_16x16x32_bf16 v[68:71], v[170:173], v[202:205], v[68:71]
	v_mfma_f32_16x16x32_bf16 v[120:123], v[166:169], v[182:185], v[120:123]
	v_mfma_f32_16x16x32_bf16 v[112:115], v[174:177], v[182:185], v[112:115]
	v_mfma_f32_16x16x32_bf16 v[104:107], v[166:169], v[190:193], v[104:107]
	v_mfma_f32_16x16x32_bf16 v[96:99], v[174:177], v[190:193], v[96:99]
	v_mfma_f32_16x16x32_bf16 v[88:91], v[166:169], v[198:201], v[88:91]
	v_mfma_f32_16x16x32_bf16 v[80:83], v[174:177], v[198:201], v[80:83]
	v_mfma_f32_16x16x32_bf16 v[72:75], v[166:169], v[206:209], v[72:75]
	v_mfma_f32_16x16x32_bf16 v[68:71], v[174:177], v[206:209], v[68:71]
	s_barrier
	s_add_i32 s48, s48, s28
	v_lshl_add_u64 v[158:159], s[12:13], 0, v[160:161]
	s_mov_b32 m0, s48
	ds_read_b128 v[178:181], v149 offset:16384
	ds_read_b128 v[182:185], v149 offset:17408
	ds_read_b128 v[186:189], v149 offset:18432
	ds_read_b128 v[190:193], v149 offset:19456
	ds_read_b128 v[194:197], v149 offset:20480
	ds_read_b128 v[198:201], v149 offset:21504
	ds_read_b128 v[202:205], v149 offset:22528
	ds_read_b128 v[206:209], v149 offset:23552
	global_load_lds_dwordx4 v[158:159], off
	s_add_i32 m0, s48, 0x2000
	s_add_u32 s48, s12, 0x40000
	v_lshl_add_u64 v[210:211], s[12:13], 0, v[128:129]
	s_addc_u32 s49, s13, 0
	s_add_i32 s50, s50, s28
	global_load_lds_dwordx4 v[210:211], off
	v_lshl_add_u64 v[212:213], s[48:49], 0, v[160:161]
	s_mov_b32 m0, s50
	v_lshl_add_u64 v[214:215], s[14:15], 0, v[130:131]
	global_load_lds_dwordx4 v[212:213], off
	s_add_i32 m0, s50, 0x2000
	v_lshl_add_u64 v[212:213], s[48:49], 0, v[128:129]
	global_load_lds_dwordx4 v[212:213], off
	s_mov_b32 m0, s30
	v_lshl_add_u64 v[212:213], s[14:15], 0, v[132:133]
	global_load_lds_dwordx4 v[212:213], off
	s_mov_b32 m0, s31
	s_nop 0
	global_load_lds_dwordx4 v[214:215], off
	s_waitcnt vmcnt(8)
	s_waitcnt lgkmcnt(0)
	s_barrier
	v_mfma_f32_16x16x32_bf16 v[60:63], v[138:141], v[178:181], v[60:63]
	v_mfma_f32_16x16x32_bf16 v[48:51], v[150:153], v[178:181], v[48:51]
	v_mfma_f32_16x16x32_bf16 v[44:47], v[138:141], v[186:189], v[44:47]
	v_mfma_f32_16x16x32_bf16 v[32:35], v[150:153], v[186:189], v[32:35]
	v_mfma_f32_16x16x32_bf16 v[28:31], v[138:141], v[194:197], v[28:31]
	v_mfma_f32_16x16x32_bf16 v[16:19], v[150:153], v[194:197], v[16:19]
	v_mfma_f32_16x16x32_bf16 v[12:15], v[138:141], v[202:205], v[12:15]
	v_mfma_f32_16x16x32_bf16 v[0:3], v[150:153], v[202:205], v[0:3]
	v_mfma_f32_16x16x32_bf16 v[60:63], v[142:145], v[182:185], v[60:63]
	v_mfma_f32_16x16x32_bf16 v[48:51], v[154:157], v[182:185], v[48:51]
	v_mfma_f32_16x16x32_bf16 v[44:47], v[142:145], v[190:193], v[44:47]
	v_mfma_f32_16x16x32_bf16 v[32:35], v[154:157], v[190:193], v[32:35]
	v_mfma_f32_16x16x32_bf16 v[28:31], v[142:145], v[198:201], v[28:31]
	v_mfma_f32_16x16x32_bf16 v[16:19], v[154:157], v[198:201], v[16:19]
	v_mfma_f32_16x16x32_bf16 v[12:15], v[142:145], v[206:209], v[12:15]
	v_mfma_f32_16x16x32_bf16 v[0:3], v[154:157], v[206:209], v[0:3]
	v_mfma_f32_16x16x32_bf16 v[56:59], v[162:165], v[178:181], v[56:59]
	v_mfma_f32_16x16x32_bf16 v[52:55], v[170:173], v[178:181], v[52:55]
	v_mfma_f32_16x16x32_bf16 v[40:43], v[162:165], v[186:189], v[40:43]
	v_mfma_f32_16x16x32_bf16 v[36:39], v[170:173], v[186:189], v[36:39]
	v_mfma_f32_16x16x32_bf16 v[24:27], v[162:165], v[194:197], v[24:27]
	v_mfma_f32_16x16x32_bf16 v[20:23], v[170:173], v[194:197], v[20:23]
	v_mfma_f32_16x16x32_bf16 v[8:11], v[162:165], v[202:205], v[8:11]
	v_mfma_f32_16x16x32_bf16 v[4:7], v[170:173], v[202:205], v[4:7]
	v_mfma_f32_16x16x32_bf16 v[56:59], v[166:169], v[182:185], v[56:59]
	v_mfma_f32_16x16x32_bf16 v[52:55], v[174:177], v[182:185], v[52:55]
	v_mfma_f32_16x16x32_bf16 v[40:43], v[166:169], v[190:193], v[40:43]
	v_mfma_f32_16x16x32_bf16 v[36:39], v[174:177], v[190:193], v[36:39]
	v_mfma_f32_16x16x32_bf16 v[24:27], v[166:169], v[198:201], v[24:27]
	v_mfma_f32_16x16x32_bf16 v[20:23], v[174:177], v[198:201], v[20:23]
	v_mfma_f32_16x16x32_bf16 v[8:11], v[166:169], v[206:209], v[8:11]
	v_mfma_f32_16x16x32_bf16 v[4:7], v[174:177], v[206:209], v[4:7]
	s_barrier
	s_add_i32 s48, 0, 0x18000
	s_add_i32 s49, 0, 0x1c000
	v_add_u32_e32 v154, s48, v147
	v_add_u32_e32 v174, s49, v147
	ds_read_b128 v[138:141], v154
	ds_read_b128 v[142:145], v154 offset:1024
	ds_read_b128 v[150:153], v154 offset:2048
	ds_read_b128 v[154:157], v154 offset:3072
	ds_read_b128 v[162:165], v174
	ds_read_b128 v[166:169], v174 offset:1024
	ds_read_b128 v[170:173], v174 offset:2048
	ds_read_b128 v[174:177], v174 offset:3072
	s_add_u32 s14, s14, 0x40000
	s_addc_u32 s15, s15, 0
	s_mov_b32 m0, s33
	v_lshl_add_u64 v[216:217], s[14:15], 0, v[132:133]
	ds_read_b128 v[178:181], v149 offset:32768
	ds_read_b128 v[182:185], v149 offset:33792
	ds_read_b128 v[186:189], v149 offset:34816
	ds_read_b128 v[190:193], v149 offset:35840
	ds_read_b128 v[194:197], v149 offset:36864
	ds_read_b128 v[198:201], v149 offset:37888
	ds_read_b128 v[202:205], v149 offset:38912
	ds_read_b128 v[206:209], v149 offset:39936
	global_load_lds_dwordx4 v[216:217], off
	s_mov_b32 m0, s34
	v_lshl_add_u64 v[216:217], s[14:15], 0, v[130:131]
	global_load_lds_dwordx4 v[216:217], off
	s_waitcnt vmcnt(8)
	s_waitcnt lgkmcnt(0)
	s_barrier
	v_mfma_f32_16x16x32_bf16 v[124:127], v[138:141], v[178:181], v[124:127]
	v_mfma_f32_16x16x32_bf16 v[116:119], v[150:153], v[178:181], v[116:119]
	v_mfma_f32_16x16x32_bf16 v[108:111], v[138:141], v[186:189], v[108:111]
	v_mfma_f32_16x16x32_bf16 v[100:103], v[150:153], v[186:189], v[100:103]
	v_mfma_f32_16x16x32_bf16 v[92:95], v[138:141], v[194:197], v[92:95]
	v_mfma_f32_16x16x32_bf16 v[84:87], v[150:153], v[194:197], v[84:87]
	v_mfma_f32_16x16x32_bf16 v[76:79], v[138:141], v[202:205], v[76:79]
	v_mfma_f32_16x16x32_bf16 v[64:67], v[150:153], v[202:205], v[64:67]
	v_mfma_f32_16x16x32_bf16 v[124:127], v[142:145], v[182:185], v[124:127]
	v_mfma_f32_16x16x32_bf16 v[116:119], v[154:157], v[182:185], v[116:119]
	v_mfma_f32_16x16x32_bf16 v[108:111], v[142:145], v[190:193], v[108:111]
	v_mfma_f32_16x16x32_bf16 v[100:103], v[154:157], v[190:193], v[100:103]
	v_mfma_f32_16x16x32_bf16 v[92:95], v[142:145], v[198:201], v[92:95]
	v_mfma_f32_16x16x32_bf16 v[84:87], v[154:157], v[198:201], v[84:87]
	v_mfma_f32_16x16x32_bf16 v[76:79], v[142:145], v[206:209], v[76:79]
	v_mfma_f32_16x16x32_bf16 v[64:67], v[154:157], v[206:209], v[64:67]
	v_mfma_f32_16x16x32_bf16 v[120:123], v[162:165], v[178:181], v[120:123]
	v_mfma_f32_16x16x32_bf16 v[112:115], v[170:173], v[178:181], v[112:115]
	v_mfma_f32_16x16x32_bf16 v[104:107], v[162:165], v[186:189], v[104:107]
	v_mfma_f32_16x16x32_bf16 v[96:99], v[170:173], v[186:189], v[96:99]
	v_mfma_f32_16x16x32_bf16 v[88:91], v[162:165], v[194:197], v[88:91]
	v_mfma_f32_16x16x32_bf16 v[80:83], v[170:173], v[194:197], v[80:83]
	v_mfma_f32_16x16x32_bf16 v[72:75], v[162:165], v[202:205], v[72:75]
	v_mfma_f32_16x16x32_bf16 v[68:71], v[170:173], v[202:205], v[68:71]
	v_mfma_f32_16x16x32_bf16 v[120:123], v[166:169], v[182:185], v[120:123]
	v_mfma_f32_16x16x32_bf16 v[112:115], v[174:177], v[182:185], v[112:115]
	v_mfma_f32_16x16x32_bf16 v[104:107], v[166:169], v[190:193], v[104:107]
	v_mfma_f32_16x16x32_bf16 v[96:99], v[174:177], v[190:193], v[96:99]
	v_mfma_f32_16x16x32_bf16 v[88:91], v[166:169], v[198:201], v[88:91]
	v_mfma_f32_16x16x32_bf16 v[80:83], v[174:177], v[198:201], v[80:83]
	v_mfma_f32_16x16x32_bf16 v[72:75], v[166:169], v[206:209], v[72:75]
	v_mfma_f32_16x16x32_bf16 v[68:71], v[174:177], v[206:209], v[68:71]
	s_barrier
	s_add_i32 s14, s48, s28
	v_lshl_add_u64 v[158:159], v[158:159], 0, s[88:89]
	s_mov_b32 m0, s14
	ds_read_b128 v[178:181], v149 offset:49152
	ds_read_b128 v[182:185], v149 offset:50176
	ds_read_b128 v[186:189], v149 offset:51200
	ds_read_b128 v[190:193], v149 offset:52224
	ds_read_b128 v[194:197], v149 offset:53248
	ds_read_b128 v[198:201], v149 offset:54272
	ds_read_b128 v[202:205], v149 offset:55296
	ds_read_b128 v[206:209], v149 offset:56320
	global_load_lds_dwordx4 v[158:159], off
	s_add_i32 m0, s14, 0x2000
	s_add_u32 s12, s12, 0x40080
	v_lshl_add_u64 v[158:159], v[210:211], 0, s[88:89]
	s_addc_u32 s13, s13, 0
	s_add_i32 s14, s49, s28
	global_load_lds_dwordx4 v[158:159], off
	s_mov_b32 m0, s14
	v_lshl_add_u64 v[158:159], s[12:13], 0, v[160:161]
	global_load_lds_dwordx4 v[158:159], off
	s_add_i32 m0, s14, 0x2000
	v_lshl_add_u64 v[158:159], s[12:13], 0, v[128:129]
	global_load_lds_dwordx4 v[158:159], off
	s_mov_b32 m0, s35
	v_lshl_add_u64 v[158:159], v[212:213], 0, s[88:89]
	global_load_lds_dwordx4 v[158:159], off
	s_mov_b32 m0, s90
	v_lshl_add_u64 v[158:159], v[214:215], 0, s[88:89]
	global_load_lds_dwordx4 v[158:159], off
	s_waitcnt vmcnt(8)
	s_waitcnt lgkmcnt(0)
	s_barrier
	v_mfma_f32_16x16x32_bf16 v[60:63], v[138:141], v[178:181], v[60:63]
	v_mfma_f32_16x16x32_bf16 v[48:51], v[150:153], v[178:181], v[48:51]
	v_mfma_f32_16x16x32_bf16 v[44:47], v[138:141], v[186:189], v[44:47]
	v_mfma_f32_16x16x32_bf16 v[32:35], v[150:153], v[186:189], v[32:35]
	v_mfma_f32_16x16x32_bf16 v[28:31], v[138:141], v[194:197], v[28:31]
	v_mfma_f32_16x16x32_bf16 v[16:19], v[150:153], v[194:197], v[16:19]
	v_mfma_f32_16x16x32_bf16 v[12:15], v[138:141], v[202:205], v[12:15]
	v_mfma_f32_16x16x32_bf16 v[0:3], v[150:153], v[202:205], v[0:3]
	v_mfma_f32_16x16x32_bf16 v[60:63], v[142:145], v[182:185], v[60:63]
	v_mfma_f32_16x16x32_bf16 v[48:51], v[154:157], v[182:185], v[48:51]
	v_mfma_f32_16x16x32_bf16 v[44:47], v[142:145], v[190:193], v[44:47]
	v_mfma_f32_16x16x32_bf16 v[32:35], v[154:157], v[190:193], v[32:35]
	v_mfma_f32_16x16x32_bf16 v[28:31], v[142:145], v[198:201], v[28:31]
	v_mfma_f32_16x16x32_bf16 v[16:19], v[154:157], v[198:201], v[16:19]
	v_mfma_f32_16x16x32_bf16 v[12:15], v[142:145], v[206:209], v[12:15]
	v_mfma_f32_16x16x32_bf16 v[0:3], v[154:157], v[206:209], v[0:3]
	v_mfma_f32_16x16x32_bf16 v[56:59], v[162:165], v[178:181], v[56:59]
	v_mfma_f32_16x16x32_bf16 v[52:55], v[170:173], v[178:181], v[52:55]
	v_mfma_f32_16x16x32_bf16 v[40:43], v[162:165], v[186:189], v[40:43]
	v_mfma_f32_16x16x32_bf16 v[36:39], v[170:173], v[186:189], v[36:39]
	v_mfma_f32_16x16x32_bf16 v[24:27], v[162:165], v[194:197], v[24:27]
	v_mfma_f32_16x16x32_bf16 v[20:23], v[170:173], v[194:197], v[20:23]
	v_mfma_f32_16x16x32_bf16 v[8:11], v[162:165], v[202:205], v[8:11]
	v_mfma_f32_16x16x32_bf16 v[4:7], v[170:173], v[202:205], v[4:7]
	v_mfma_f32_16x16x32_bf16 v[56:59], v[166:169], v[182:185], v[56:59]
	v_mfma_f32_16x16x32_bf16 v[52:55], v[174:177], v[182:185], v[52:55]
	v_mfma_f32_16x16x32_bf16 v[40:43], v[166:169], v[190:193], v[40:43]
	v_mfma_f32_16x16x32_bf16 v[36:39], v[174:177], v[190:193], v[36:39]
	v_mfma_f32_16x16x32_bf16 v[24:27], v[166:169], v[198:201], v[24:27]
	v_mfma_f32_16x16x32_bf16 v[20:23], v[174:177], v[198:201], v[20:23]
	v_mfma_f32_16x16x32_bf16 v[8:11], v[166:169], v[206:209], v[8:11]
	v_mfma_f32_16x16x32_bf16 v[4:7], v[174:177], v[206:209], v[4:7]
	s_barrier
	s_add_i32 s22, s22, 2
	s_add_u32 s96, s96, 0x100
	s_addc_u32 s21, s21, 0
	s_add_u32 s10, s10, 0x100
	s_addc_u32 s11, s11, 0
	s_cmp_gt_u32 s22, 13
	s_cbranch_scc0 .LBB0_56
	v_lshl_add_u32 v192, s8, 8, v146
	v_lshlrev_b32_e32 v192, 3, v192
	global_load_dwordx2 v[176:177], v192, s[4:5]
	global_load_dwordx2 v[178:179], v192, s[4:5] offset:128
	global_load_dwordx2 v[180:181], v192, s[4:5] offset:256
	global_load_dwordx2 v[182:183], v192, s[4:5] offset:384
	global_load_dwordx2 v[184:185], v192, s[4:5] offset:1024
	global_load_dwordx2 v[186:187], v192, s[4:5] offset:1152
	global_load_dwordx2 v[188:189], v192, s[4:5] offset:1280
	global_load_dwordx2 v[190:191], v192, s[4:5] offset:1408
	s_and_b64 vcc, exec, s[6:7]
	s_cbranch_vccz .LBB0_59
	s_barrier

.LBB0_84:
	s_add_u32 s12, vcc_lo, 0xfffc0080
	s_addc_u32 s13, vcc_hi, -1
	s_add_i32 s48, 0, 0x10000
	s_cmp_eq_u32 s22, 12
	s_cselect_b32 s15, s9, s13
	s_cselect_b32 s14, s20, s12
	s_cselect_b32 s13, s37, s21
	s_cselect_b32 s12, s45, s90
	s_add_i32 s50, 0, 0x14000
	v_add_u32_e32 v154, s48, v143
	v_add_u32_e32 v158, s50, v143
	ds_read_b128 v[138:141], v154
	ds_read_b128 v[146:149], v154 offset:1024
	ds_read_b128 v[150:153], v154 offset:2048
	ds_read_b128 v[154:157], v154 offset:3072
	ds_read_b128 v[162:165], v158
	ds_read_b128 v[166:169], v158 offset:1024
	ds_read_b128 v[170:173], v158 offset:2048
	ds_read_b128 v[174:177], v158 offset:3072
	v_lshl_add_u64 v[158:159], vcc, 0, v[136:137]
	s_add_i32 m0, s11, 0xc000
	ds_read_b128 v[178:181], v145
	ds_read_b128 v[182:185], v145 offset:1024
	ds_read_b128 v[186:189], v145 offset:2048
	ds_read_b128 v[190:193], v145 offset:3072
	ds_read_b128 v[194:197], v145 offset:4096
	ds_read_b128 v[198:201], v145 offset:5120
	ds_read_b128 v[202:205], v145 offset:6144
	ds_read_b128 v[206:209], v145 offset:7168
	global_load_lds_dwordx4 v[158:159], off
	s_add_i32 m0, s11, 0xe000
	v_lshl_add_u64 v[158:159], vcc, 0, v[134:135]
	global_load_lds_dwordx4 v[158:159], off
	s_waitcnt vmcnt(8)
	s_waitcnt lgkmcnt(0)
	s_barrier
	v_mfma_f32_16x16x32_bf16 v[124:127], v[138:141], v[178:181], v[124:127]
	v_mfma_f32_16x16x32_bf16 v[120:123], v[150:153], v[178:181], v[120:123]
	v_mfma_f32_16x16x32_bf16 v[108:111], v[138:141], v[186:189], v[108:111]
	v_mfma_f32_16x16x32_bf16 v[104:107], v[150:153], v[186:189], v[104:107]
	v_mfma_f32_16x16x32_bf16 v[92:95], v[138:141], v[194:197], v[92:95]
	v_mfma_f32_16x16x32_bf16 v[88:91], v[150:153], v[194:197], v[88:91]
	v_mfma_f32_16x16x32_bf16 v[76:79], v[138:141], v[202:205], v[76:79]
	v_mfma_f32_16x16x32_bf16 v[72:75], v[150:153], v[202:205], v[72:75]
	v_mfma_f32_16x16x32_bf16 v[124:127], v[146:149], v[182:185], v[124:127]
	v_mfma_f32_16x16x32_bf16 v[120:123], v[154:157], v[182:185], v[120:123]
	v_mfma_f32_16x16x32_bf16 v[108:111], v[146:149], v[190:193], v[108:111]
	v_mfma_f32_16x16x32_bf16 v[104:107], v[154:157], v[190:193], v[104:107]
	v_mfma_f32_16x16x32_bf16 v[92:95], v[146:149], v[198:201], v[92:95]
	v_mfma_f32_16x16x32_bf16 v[88:91], v[154:157], v[198:201], v[88:91]
	v_mfma_f32_16x16x32_bf16 v[76:79], v[146:149], v[206:209], v[76:79]
	v_mfma_f32_16x16x32_bf16 v[72:75], v[154:157], v[206:209], v[72:75]
	v_mfma_f32_16x16x32_bf16 v[116:119], v[162:165], v[178:181], v[116:119]
	v_mfma_f32_16x16x32_bf16 v[112:115], v[170:173], v[178:181], v[112:115]
	v_mfma_f32_16x16x32_bf16 v[100:103], v[162:165], v[186:189], v[100:103]
	v_mfma_f32_16x16x32_bf16 v[96:99], v[170:173], v[186:189], v[96:99]
	v_mfma_f32_16x16x32_bf16 v[84:87], v[162:165], v[194:197], v[84:87]
	v_mfma_f32_16x16x32_bf16 v[80:83], v[170:173], v[194:197], v[80:83]
	v_mfma_f32_16x16x32_bf16 v[68:71], v[162:165], v[202:205], v[68:71]
	v_mfma_f32_16x16x32_bf16 v[64:67], v[170:173], v[202:205], v[64:67]
	v_mfma_f32_16x16x32_bf16 v[116:119], v[166:169], v[182:185], v[116:119]
	v_mfma_f32_16x16x32_bf16 v[112:115], v[174:177], v[182:185], v[112:115]
	v_mfma_f32_16x16x32_bf16 v[100:103], v[166:169], v[190:193], v[100:103]
	v_mfma_f32_16x16x32_bf16 v[96:99], v[174:177], v[190:193], v[96:99]
	v_mfma_f32_16x16x32_bf16 v[84:87], v[166:169], v[198:201], v[84:87]
	v_mfma_f32_16x16x32_bf16 v[80:83], v[174:177], v[198:201], v[80:83]
	v_mfma_f32_16x16x32_bf16 v[68:71], v[166:169], v[206:209], v[68:71]
	v_mfma_f32_16x16x32_bf16 v[64:67], v[174:177], v[206:209], v[64:67]
	s_barrier
	s_add_i32 s48, s48, s28
	v_lshl_add_u64 v[158:159], s[12:13], 0, v[160:161]
	s_mov_b32 m0, s48
	ds_read_b128 v[178:181], v145 offset:16384
	ds_read_b128 v[182:185], v145 offset:17408
	ds_read_b128 v[186:189], v145 offset:18432
	ds_read_b128 v[190:193], v145 offset:19456
	ds_read_b128 v[194:197], v145 offset:20480
	ds_read_b128 v[198:201], v145 offset:21504
	ds_read_b128 v[202:205], v145 offset:22528
	ds_read_b128 v[206:209], v145 offset:23552
	global_load_lds_dwordx4 v[158:159], off
	s_add_i32 m0, s48, 0x2000
	s_add_u32 s48, s12, 0x40000
	v_lshl_add_u64 v[210:211], s[12:13], 0, v[132:133]
	s_addc_u32 s49, s13, 0
	s_add_i32 s50, s50, s28
	global_load_lds_dwordx4 v[210:211], off
	v_lshl_add_u64 v[212:213], s[48:49], 0, v[160:161]
	s_mov_b32 m0, s50
	v_lshl_add_u64 v[214:215], s[14:15], 0, v[130:131]
	global_load_lds_dwordx4 v[212:213], off
	s_add_i32 m0, s50, 0x2000
	v_lshl_add_u64 v[212:213], s[48:49], 0, v[132:133]
	global_load_lds_dwordx4 v[212:213], off
	s_mov_b32 m0, s11
	v_lshl_add_u64 v[212:213], s[14:15], 0, v[128:129]
	global_load_lds_dwordx4 v[212:213], off
	s_mov_b32 m0, s29
	s_nop 0
	global_load_lds_dwordx4 v[214:215], off
	s_waitcnt vmcnt(8)
	s_waitcnt lgkmcnt(0)
	s_barrier
	v_mfma_f32_16x16x32_bf16 v[60:63], v[138:141], v[178:181], v[60:63]
	v_mfma_f32_16x16x32_bf16 v[56:59], v[150:153], v[178:181], v[56:59]
	v_mfma_f32_16x16x32_bf16 v[44:47], v[138:141], v[186:189], v[44:47]
	v_mfma_f32_16x16x32_bf16 v[40:43], v[150:153], v[186:189], v[40:43]
	v_mfma_f32_16x16x32_bf16 v[28:31], v[138:141], v[194:197], v[28:31]
	v_mfma_f32_16x16x32_bf16 v[24:27], v[150:153], v[194:197], v[24:27]
	v_mfma_f32_16x16x32_bf16 v[12:15], v[138:141], v[202:205], v[12:15]
	v_mfma_f32_16x16x32_bf16 v[8:11], v[150:153], v[202:205], v[8:11]
	v_mfma_f32_16x16x32_bf16 v[60:63], v[146:149], v[182:185], v[60:63]
	v_mfma_f32_16x16x32_bf16 v[56:59], v[154:157], v[182:185], v[56:59]
	v_mfma_f32_16x16x32_bf16 v[44:47], v[146:149], v[190:193], v[44:47]
	v_mfma_f32_16x16x32_bf16 v[40:43], v[154:157], v[190:193], v[40:43]
	v_mfma_f32_16x16x32_bf16 v[28:31], v[146:149], v[198:201], v[28:31]
	v_mfma_f32_16x16x32_bf16 v[24:27], v[154:157], v[198:201], v[24:27]
	v_mfma_f32_16x16x32_bf16 v[12:15], v[146:149], v[206:209], v[12:15]
	v_mfma_f32_16x16x32_bf16 v[8:11], v[154:157], v[206:209], v[8:11]
	v_mfma_f32_16x16x32_bf16 v[52:55], v[162:165], v[178:181], v[52:55]
	v_mfma_f32_16x16x32_bf16 v[48:51], v[170:173], v[178:181], v[48:51]
	v_mfma_f32_16x16x32_bf16 v[36:39], v[162:165], v[186:189], v[36:39]
	v_mfma_f32_16x16x32_bf16 v[32:35], v[170:173], v[186:189], v[32:35]
	v_mfma_f32_16x16x32_bf16 v[20:23], v[162:165], v[194:197], v[20:23]
	v_mfma_f32_16x16x32_bf16 v[16:19], v[170:173], v[194:197], v[16:19]
	v_mfma_f32_16x16x32_bf16 v[4:7], v[162:165], v[202:205], v[4:7]
	v_mfma_f32_16x16x32_bf16 v[0:3], v[170:173], v[202:205], v[0:3]
	v_mfma_f32_16x16x32_bf16 v[52:55], v[166:169], v[182:185], v[52:55]
	v_mfma_f32_16x16x32_bf16 v[48:51], v[174:177], v[182:185], v[48:51]
	v_mfma_f32_16x16x32_bf16 v[36:39], v[166:169], v[190:193], v[36:39]
	v_mfma_f32_16x16x32_bf16 v[32:35], v[174:177], v[190:193], v[32:35]
	v_mfma_f32_16x16x32_bf16 v[20:23], v[166:169], v[198:201], v[20:23]
	v_mfma_f32_16x16x32_bf16 v[16:19], v[174:177], v[198:201], v[16:19]
	v_mfma_f32_16x16x32_bf16 v[4:7], v[166:169], v[206:209], v[4:7]
	v_mfma_f32_16x16x32_bf16 v[0:3], v[174:177], v[206:209], v[0:3]
	s_barrier
	s_add_i32 s48, 0, 0x18000
	s_add_i32 s49, 0, 0x1c000
	v_add_u32_e32 v154, s48, v143
	v_add_u32_e32 v174, s49, v143
	ds_read_b128 v[138:141], v154
	ds_read_b128 v[146:149], v154 offset:1024
	ds_read_b128 v[150:153], v154 offset:2048
	ds_read_b128 v[154:157], v154 offset:3072
	ds_read_b128 v[162:165], v174
	ds_read_b128 v[166:169], v174 offset:1024
	ds_read_b128 v[170:173], v174 offset:2048
	ds_read_b128 v[174:177], v174 offset:3072
	s_add_u32 s14, s14, 0x40000
	s_addc_u32 s15, s15, 0
	s_mov_b32 m0, s30
	v_lshl_add_u64 v[216:217], s[14:15], 0, v[128:129]
	ds_read_b128 v[178:181], v145 offset:32768
	ds_read_b128 v[182:185], v145 offset:33792
	ds_read_b128 v[186:189], v145 offset:34816
	ds_read_b128 v[190:193], v145 offset:35840
	ds_read_b128 v[194:197], v145 offset:36864
	ds_read_b128 v[198:201], v145 offset:37888
	ds_read_b128 v[202:205], v145 offset:38912
	ds_read_b128 v[206:209], v145 offset:39936
	global_load_lds_dwordx4 v[216:217], off
	s_mov_b32 m0, s31
	v_lshl_add_u64 v[216:217], s[14:15], 0, v[130:131]
	global_load_lds_dwordx4 v[216:217], off
	s_waitcnt vmcnt(8)
	s_waitcnt lgkmcnt(0)
	s_barrier
	v_mfma_f32_16x16x32_bf16 v[124:127], v[138:141], v[178:181], v[124:127]
	v_mfma_f32_16x16x32_bf16 v[120:123], v[150:153], v[178:181], v[120:123]
	v_mfma_f32_16x16x32_bf16 v[108:111], v[138:141], v[186:189], v[108:111]
	v_mfma_f32_16x16x32_bf16 v[104:107], v[150:153], v[186:189], v[104:107]
	v_mfma_f32_16x16x32_bf16 v[92:95], v[138:141], v[194:197], v[92:95]
	v_mfma_f32_16x16x32_bf16 v[88:91], v[150:153], v[194:197], v[88:91]
	v_mfma_f32_16x16x32_bf16 v[76:79], v[138:141], v[202:205], v[76:79]
	v_mfma_f32_16x16x32_bf16 v[72:75], v[150:153], v[202:205], v[72:75]
	v_mfma_f32_16x16x32_bf16 v[124:127], v[146:149], v[182:185], v[124:127]
	v_mfma_f32_16x16x32_bf16 v[120:123], v[154:157], v[182:185], v[120:123]
	v_mfma_f32_16x16x32_bf16 v[108:111], v[146:149], v[190:193], v[108:111]
	v_mfma_f32_16x16x32_bf16 v[104:107], v[154:157], v[190:193], v[104:107]
	v_mfma_f32_16x16x32_bf16 v[92:95], v[146:149], v[198:201], v[92:95]
	v_mfma_f32_16x16x32_bf16 v[88:91], v[154:157], v[198:201], v[88:91]
	v_mfma_f32_16x16x32_bf16 v[76:79], v[146:149], v[206:209], v[76:79]
	v_mfma_f32_16x16x32_bf16 v[72:75], v[154:157], v[206:209], v[72:75]
	v_mfma_f32_16x16x32_bf16 v[116:119], v[162:165], v[178:181], v[116:119]
	v_mfma_f32_16x16x32_bf16 v[112:115], v[170:173], v[178:181], v[112:115]
	v_mfma_f32_16x16x32_bf16 v[100:103], v[162:165], v[186:189], v[100:103]
	v_mfma_f32_16x16x32_bf16 v[96:99], v[170:173], v[186:189], v[96:99]
	v_mfma_f32_16x16x32_bf16 v[84:87], v[162:165], v[194:197], v[84:87]
	v_mfma_f32_16x16x32_bf16 v[80:83], v[170:173], v[194:197], v[80:83]
	v_mfma_f32_16x16x32_bf16 v[68:71], v[162:165], v[202:205], v[68:71]
	v_mfma_f32_16x16x32_bf16 v[64:67], v[170:173], v[202:205], v[64:67]
	v_mfma_f32_16x16x32_bf16 v[116:119], v[166:169], v[182:185], v[116:119]
	v_mfma_f32_16x16x32_bf16 v[112:115], v[174:177], v[182:185], v[112:115]
	v_mfma_f32_16x16x32_bf16 v[100:103], v[166:169], v[190:193], v[100:103]
	v_mfma_f32_16x16x32_bf16 v[96:99], v[174:177], v[190:193], v[96:99]
	v_mfma_f32_16x16x32_bf16 v[84:87], v[166:169], v[198:201], v[84:87]
	v_mfma_f32_16x16x32_bf16 v[80:83], v[174:177], v[198:201], v[80:83]
	v_mfma_f32_16x16x32_bf16 v[68:71], v[166:169], v[206:209], v[68:71]
	v_mfma_f32_16x16x32_bf16 v[64:67], v[174:177], v[206:209], v[64:67]
	s_barrier
	s_add_i32 s14, s48, s28
	v_lshl_add_u64 v[158:159], v[158:159], 0, s[88:89]
	s_mov_b32 m0, s14
	ds_read_b128 v[178:181], v145 offset:49152
	ds_read_b128 v[182:185], v145 offset:50176
	ds_read_b128 v[186:189], v145 offset:51200
	ds_read_b128 v[190:193], v145 offset:52224
	ds_read_b128 v[194:197], v145 offset:53248
	ds_read_b128 v[198:201], v145 offset:54272
	ds_read_b128 v[202:205], v145 offset:55296
	ds_read_b128 v[206:209], v145 offset:56320
	global_load_lds_dwordx4 v[158:159], off
	s_add_i32 m0, s14, 0x2000
	s_add_u32 s12, s12, 0x40080
	v_lshl_add_u64 v[158:159], v[210:211], 0, s[88:89]
	s_addc_u32 s13, s13, 0
	s_add_i32 s14, s49, s28
	global_load_lds_dwordx4 v[158:159], off
	s_mov_b32 m0, s14
	v_lshl_add_u64 v[158:159], s[12:13], 0, v[160:161]
	global_load_lds_dwordx4 v[158:159], off
	s_add_i32 m0, s14, 0x2000
	v_lshl_add_u64 v[158:159], s[12:13], 0, v[132:133]
	global_load_lds_dwordx4 v[158:159], off
	s_mov_b32 m0, s33
	v_lshl_add_u64 v[158:159], v[212:213], 0, s[88:89]
	global_load_lds_dwordx4 v[158:159], off
	s_mov_b32 m0, s34
	v_lshl_add_u64 v[158:159], v[214:215], 0, s[88:89]
	global_load_lds_dwordx4 v[158:159], off
	s_waitcnt vmcnt(8)
	s_waitcnt lgkmcnt(0)
	s_barrier
	v_mfma_f32_16x16x32_bf16 v[60:63], v[138:141], v[178:181], v[60:63]
	v_mfma_f32_16x16x32_bf16 v[56:59], v[150:153], v[178:181], v[56:59]
	v_mfma_f32_16x16x32_bf16 v[44:47], v[138:141], v[186:189], v[44:47]
	v_mfma_f32_16x16x32_bf16 v[40:43], v[150:153], v[186:189], v[40:43]
	v_mfma_f32_16x16x32_bf16 v[28:31], v[138:141], v[194:197], v[28:31]
	v_mfma_f32_16x16x32_bf16 v[24:27], v[150:153], v[194:197], v[24:27]
	v_mfma_f32_16x16x32_bf16 v[12:15], v[138:141], v[202:205], v[12:15]
	v_mfma_f32_16x16x32_bf16 v[8:11], v[150:153], v[202:205], v[8:11]
	v_mfma_f32_16x16x32_bf16 v[60:63], v[146:149], v[182:185], v[60:63]
	v_mfma_f32_16x16x32_bf16 v[56:59], v[154:157], v[182:185], v[56:59]
	v_mfma_f32_16x16x32_bf16 v[44:47], v[146:149], v[190:193], v[44:47]
	v_mfma_f32_16x16x32_bf16 v[40:43], v[154:157], v[190:193], v[40:43]
	v_mfma_f32_16x16x32_bf16 v[28:31], v[146:149], v[198:201], v[28:31]
	v_mfma_f32_16x16x32_bf16 v[24:27], v[154:157], v[198:201], v[24:27]
	v_mfma_f32_16x16x32_bf16 v[12:15], v[146:149], v[206:209], v[12:15]
	v_mfma_f32_16x16x32_bf16 v[8:11], v[154:157], v[206:209], v[8:11]
	v_mfma_f32_16x16x32_bf16 v[52:55], v[162:165], v[178:181], v[52:55]
	v_mfma_f32_16x16x32_bf16 v[48:51], v[170:173], v[178:181], v[48:51]
	v_mfma_f32_16x16x32_bf16 v[36:39], v[162:165], v[186:189], v[36:39]
	v_mfma_f32_16x16x32_bf16 v[32:35], v[170:173], v[186:189], v[32:35]
	v_mfma_f32_16x16x32_bf16 v[20:23], v[162:165], v[194:197], v[20:23]
	v_mfma_f32_16x16x32_bf16 v[16:19], v[170:173], v[194:197], v[16:19]
	v_mfma_f32_16x16x32_bf16 v[4:7], v[162:165], v[202:205], v[4:7]
	v_mfma_f32_16x16x32_bf16 v[0:3], v[170:173], v[202:205], v[0:3]
	v_mfma_f32_16x16x32_bf16 v[52:55], v[166:169], v[182:185], v[52:55]
	v_mfma_f32_16x16x32_bf16 v[48:51], v[174:177], v[182:185], v[48:51]
	v_mfma_f32_16x16x32_bf16 v[36:39], v[166:169], v[190:193], v[36:39]
	v_mfma_f32_16x16x32_bf16 v[32:35], v[174:177], v[190:193], v[32:35]
	v_mfma_f32_16x16x32_bf16 v[20:23], v[166:169], v[198:201], v[20:23]
	v_mfma_f32_16x16x32_bf16 v[16:19], v[174:177], v[198:201], v[16:19]
	v_mfma_f32_16x16x32_bf16 v[4:7], v[166:169], v[206:209], v[4:7]
	v_mfma_f32_16x16x32_bf16 v[0:3], v[174:177], v[206:209], v[0:3]
	s_barrier
	s_add_i32 s22, s22, 2
	s_add_u32 s90, s90, 0x100
	s_addc_u32 s21, s21, 0
	s_add_u32 vcc_lo, vcc_lo, 0x100
	s_addc_u32 vcc_hi, vcc_hi, 0
	s_cmp_gt_u32 s22, 13
	s_cbranch_scc0 .LBB0_84
	v_lshl_add_u32 v140, s8, 8, v142
	v_lshl_or_b32 v138, s10, 8, v144
	v_lshlrev_b32_e32 v141, 11, v140
	v_lshl_add_u32 v138, v138, 1, v141
	v_lshlrev_b32_e32 v139, 3, v140
	s_mov_b64 s[8:9], s[2:3]
	global_load_dwordx4 v[146:149], v138, s[8:9]
	global_load_dwordx4 v[150:153], v138, s[8:9] offset:256
	s_add_u32 s8, s8, 0x8000
	s_addc_u32 s9, s9, 0
	global_load_dwordx4 v[154:157], v138, s[8:9]
	global_load_dwordx4 v[162:165], v138, s[8:9] offset:256
	s_add_u32 s8, s8, 0x8000
	s_addc_u32 s9, s9, 0
	global_load_dwordx4 v[166:169], v138, s[8:9]
	global_load_dwordx4 v[174:177], v138, s[8:9] offset:256
	s_add_u32 s8, s8, 0x8000
	s_addc_u32 s9, s9, 0
	global_load_dwordx4 v[178:181], v138, s[8:9]
	global_load_dwordx4 v[182:185], v138, s[8:9] offset:256
	s_add_u32 s8, s8, 0x28000
	s_addc_u32 s9, s9, 0
	global_load_dwordx4 v[186:189], v138, s[8:9]
	global_load_dwordx4 v[190:193], v138, s[8:9] offset:256
	s_add_u32 s8, s8, 0x8000
	s_addc_u32 s9, s9, 0
	global_load_dwordx4 v[194:197], v138, s[8:9]
	global_load_dwordx4 v[198:201], v138, s[8:9] offset:256
	s_add_u32 s8, s8, 0x8000
	s_addc_u32 s9, s9, 0
	global_load_dwordx4 v[202:205], v138, s[8:9]
	global_load_dwordx4 v[206:209], v138, s[8:9] offset:256
	s_add_u32 s8, s8, 0x8000
	s_addc_u32 s9, s9, 0
	global_load_dwordx4 v[210:213], v138, s[8:9]
	global_load_dwordx4 v[214:217], v138, s[8:9] offset:256
	s_and_b64 vcc, exec, s[6:7]
	s_cbranch_vccz .LBB0_87
	s_barrier

.LBB0_139:
	s_add_u32 s14, s10, 0xfffc0080
	s_addc_u32 s15, s11, -1
	s_add_i32 s48, 0, 0x10000
	s_cmp_eq_u32 s22, 12
	s_cselect_b32 s93, s9, s15
	s_cselect_b32 s92, s41, s14
	s_cselect_b32 s15, s45, s21
	s_cselect_b32 s14, vcc_lo, vcc_hi
	s_add_i32 s50, 0, 0x14000
	v_add_u32_e32 v140, s48, v202
	v_add_u32_e32 v156, s50, v202
	ds_read_b128 v[128:131], v140
	ds_read_b128 v[132:135], v140 offset:1024
	ds_read_b128 v[136:139], v140 offset:2048
	ds_read_b128 v[140:143], v140 offset:3072
	ds_read_b128 v[144:147], v156
	ds_read_b128 v[148:151], v156 offset:1024
	ds_read_b128 v[152:155], v156 offset:2048
	ds_read_b128 v[156:159], v156 offset:3072
	v_lshl_add_u64 v[162:163], s[10:11], 0, v[186:187]
	s_add_i32 m0, s31, 0xc000
	ds_read_b128 v[188:191], v204
	ds_read_b128 v[192:195], v204 offset:1024
	ds_read_b128 v[196:199], v204 offset:2048
	ds_read_b128 v[206:209], v204 offset:3072
	ds_read_b128 v[210:213], v204 offset:4096
	ds_read_b128 v[214:217], v204 offset:5120
	ds_read_b128 v[238:241], v204 offset:6144
	ds_read_b128 v[246:249], v204 offset:7168
	global_load_lds_dwordx4 v[162:163], off
	s_add_i32 m0, s31, 0xe000
	v_lshl_add_u64 v[162:163], s[10:11], 0, v[184:185]
	global_load_lds_dwordx4 v[162:163], off
	s_waitcnt vmcnt(8)
	s_waitcnt lgkmcnt(0)
	s_barrier
	v_mfma_f32_16x16x32_bf16 v[124:127], v[128:131], v[188:191], v[124:127]
	v_mfma_f32_16x16x32_bf16 v[120:123], v[136:139], v[188:191], v[120:123]
	v_mfma_f32_16x16x32_bf16 v[108:111], v[128:131], v[196:199], v[108:111]
	v_mfma_f32_16x16x32_bf16 v[104:107], v[136:139], v[196:199], v[104:107]
	v_mfma_f32_16x16x32_bf16 v[92:95], v[128:131], v[210:213], v[92:95]
	v_mfma_f32_16x16x32_bf16 v[88:91], v[136:139], v[210:213], v[88:91]
	v_mfma_f32_16x16x32_bf16 v[76:79], v[128:131], v[238:241], v[76:79]
	v_mfma_f32_16x16x32_bf16 v[72:75], v[136:139], v[238:241], v[72:75]
	v_mfma_f32_16x16x32_bf16 v[124:127], v[132:135], v[192:195], v[124:127]
	v_mfma_f32_16x16x32_bf16 v[120:123], v[140:143], v[192:195], v[120:123]
	v_mfma_f32_16x16x32_bf16 v[108:111], v[132:135], v[206:209], v[108:111]
	v_mfma_f32_16x16x32_bf16 v[104:107], v[140:143], v[206:209], v[104:107]
	v_mfma_f32_16x16x32_bf16 v[92:95], v[132:135], v[214:217], v[92:95]
	v_mfma_f32_16x16x32_bf16 v[88:91], v[140:143], v[214:217], v[88:91]
	v_mfma_f32_16x16x32_bf16 v[76:79], v[132:135], v[246:249], v[76:79]
	v_mfma_f32_16x16x32_bf16 v[72:75], v[140:143], v[246:249], v[72:75]
	v_mfma_f32_16x16x32_bf16 v[116:119], v[144:147], v[188:191], v[116:119]
	v_mfma_f32_16x16x32_bf16 v[112:115], v[152:155], v[188:191], v[112:115]
	v_mfma_f32_16x16x32_bf16 v[100:103], v[144:147], v[196:199], v[100:103]
	v_mfma_f32_16x16x32_bf16 v[96:99], v[152:155], v[196:199], v[96:99]
	v_mfma_f32_16x16x32_bf16 v[84:87], v[144:147], v[210:213], v[84:87]
	v_mfma_f32_16x16x32_bf16 v[80:83], v[152:155], v[210:213], v[80:83]
	v_mfma_f32_16x16x32_bf16 v[68:71], v[144:147], v[238:241], v[68:71]
	v_mfma_f32_16x16x32_bf16 v[64:67], v[152:155], v[238:241], v[64:67]
	v_mfma_f32_16x16x32_bf16 v[116:119], v[148:151], v[192:195], v[116:119]
	v_mfma_f32_16x16x32_bf16 v[112:115], v[156:159], v[192:195], v[112:115]
	v_mfma_f32_16x16x32_bf16 v[100:103], v[148:151], v[206:209], v[100:103]
	v_mfma_f32_16x16x32_bf16 v[96:99], v[156:159], v[206:209], v[96:99]
	v_mfma_f32_16x16x32_bf16 v[84:87], v[148:151], v[214:217], v[84:87]
	v_mfma_f32_16x16x32_bf16 v[80:83], v[156:159], v[214:217], v[80:83]
	v_mfma_f32_16x16x32_bf16 v[68:71], v[148:151], v[246:249], v[68:71]
	v_mfma_f32_16x16x32_bf16 v[64:67], v[156:159], v[246:249], v[64:67]
	s_barrier
	s_add_i32 s48, s48, s29
	v_lshl_add_u64 v[162:163], s[14:15], 0, v[178:179]
	s_mov_b32 m0, s48
	ds_read_b128 v[188:191], v204 offset:16384
	ds_read_b128 v[192:195], v204 offset:17408
	ds_read_b128 v[196:199], v204 offset:18432
	ds_read_b128 v[206:209], v204 offset:19456
	ds_read_b128 v[210:213], v204 offset:20480
	ds_read_b128 v[214:217], v204 offset:21504
	ds_read_b128 v[238:241], v204 offset:22528
	ds_read_b128 v[246:249], v204 offset:23552
	global_load_lds_dwordx4 v[162:163], off
	s_add_i32 m0, s48, 0x2000
	s_add_u32 s48, s14, 0x40000
	v_lshl_add_u64 v[164:165], s[14:15], 0, v[174:175]
	s_addc_u32 s49, s15, 0
	s_add_i32 s50, s50, s29
	global_load_lds_dwordx4 v[164:165], off
	v_lshl_add_u64 v[166:167], s[48:49], 0, v[178:179]
	s_mov_b32 m0, s50
	v_lshl_add_u64 v[168:169], s[92:93], 0, v[176:177]
	global_load_lds_dwordx4 v[166:167], off
	s_add_i32 m0, s50, 0x2000
	v_lshl_add_u64 v[166:167], s[48:49], 0, v[174:175]
	global_load_lds_dwordx4 v[166:167], off
	s_mov_b32 m0, s31
	v_lshl_add_u64 v[166:167], s[92:93], 0, v[180:181]
	global_load_lds_dwordx4 v[166:167], off
	s_mov_b32 m0, s34
	s_nop 0
	global_load_lds_dwordx4 v[168:169], off
	s_waitcnt vmcnt(8)
	s_waitcnt lgkmcnt(0)
	s_barrier
	v_mfma_f32_16x16x32_bf16 v[60:63], v[128:131], v[188:191], v[60:63]
	v_mfma_f32_16x16x32_bf16 v[56:59], v[136:139], v[188:191], v[56:59]
	v_mfma_f32_16x16x32_bf16 v[44:47], v[128:131], v[196:199], v[44:47]
	v_mfma_f32_16x16x32_bf16 v[40:43], v[136:139], v[196:199], v[40:43]
	v_mfma_f32_16x16x32_bf16 v[28:31], v[128:131], v[210:213], v[28:31]
	v_mfma_f32_16x16x32_bf16 v[24:27], v[136:139], v[210:213], v[24:27]
	v_mfma_f32_16x16x32_bf16 v[12:15], v[128:131], v[238:241], v[12:15]
	v_mfma_f32_16x16x32_bf16 v[8:11], v[136:139], v[238:241], v[8:11]
	v_mfma_f32_16x16x32_bf16 v[60:63], v[132:135], v[192:195], v[60:63]
	v_mfma_f32_16x16x32_bf16 v[56:59], v[140:143], v[192:195], v[56:59]
	v_mfma_f32_16x16x32_bf16 v[44:47], v[132:135], v[206:209], v[44:47]
	v_mfma_f32_16x16x32_bf16 v[40:43], v[140:143], v[206:209], v[40:43]
	v_mfma_f32_16x16x32_bf16 v[28:31], v[132:135], v[214:217], v[28:31]
	v_mfma_f32_16x16x32_bf16 v[24:27], v[140:143], v[214:217], v[24:27]
	v_mfma_f32_16x16x32_bf16 v[12:15], v[132:135], v[246:249], v[12:15]
	v_mfma_f32_16x16x32_bf16 v[8:11], v[140:143], v[246:249], v[8:11]
	v_mfma_f32_16x16x32_bf16 v[52:55], v[144:147], v[188:191], v[52:55]
	v_mfma_f32_16x16x32_bf16 v[48:51], v[152:155], v[188:191], v[48:51]
	v_mfma_f32_16x16x32_bf16 v[36:39], v[144:147], v[196:199], v[36:39]
	v_mfma_f32_16x16x32_bf16 v[32:35], v[152:155], v[196:199], v[32:35]
	v_mfma_f32_16x16x32_bf16 v[20:23], v[144:147], v[210:213], v[20:23]
	v_mfma_f32_16x16x32_bf16 v[16:19], v[152:155], v[210:213], v[16:19]
	v_mfma_f32_16x16x32_bf16 v[4:7], v[144:147], v[238:241], v[4:7]
	v_mfma_f32_16x16x32_bf16 v[0:3], v[152:155], v[238:241], v[0:3]
	v_mfma_f32_16x16x32_bf16 v[52:55], v[148:151], v[192:195], v[52:55]
	v_mfma_f32_16x16x32_bf16 v[48:51], v[156:159], v[192:195], v[48:51]
	v_mfma_f32_16x16x32_bf16 v[36:39], v[148:151], v[206:209], v[36:39]
	v_mfma_f32_16x16x32_bf16 v[32:35], v[156:159], v[206:209], v[32:35]
	v_mfma_f32_16x16x32_bf16 v[20:23], v[148:151], v[214:217], v[20:23]
	v_mfma_f32_16x16x32_bf16 v[16:19], v[156:159], v[214:217], v[16:19]
	v_mfma_f32_16x16x32_bf16 v[4:7], v[148:151], v[246:249], v[4:7]
	v_mfma_f32_16x16x32_bf16 v[0:3], v[156:159], v[246:249], v[0:3]
	s_barrier
	s_add_i32 s50, 0, 0x18000
	s_add_i32 s51, 0, 0x1c000
	v_add_u32_e32 v140, s50, v202
	v_add_u32_e32 v156, s51, v202
	ds_read_b128 v[128:131], v140
	ds_read_b128 v[132:135], v140 offset:1024
	ds_read_b128 v[136:139], v140 offset:2048
	ds_read_b128 v[140:143], v140 offset:3072
	ds_read_b128 v[144:147], v156
	ds_read_b128 v[148:151], v156 offset:1024
	ds_read_b128 v[152:155], v156 offset:2048
	ds_read_b128 v[156:159], v156 offset:3072
	s_add_u32 s48, s92, 0x40000
	s_addc_u32 s49, s93, 0
	s_mov_b32 m0, s35
	v_lshl_add_u64 v[170:171], s[48:49], 0, v[180:181]
	ds_read_b128 v[188:191], v204 offset:32768
	ds_read_b128 v[192:195], v204 offset:33792
	ds_read_b128 v[196:199], v204 offset:34816
	ds_read_b128 v[206:209], v204 offset:35840
	ds_read_b128 v[210:213], v204 offset:36864
	ds_read_b128 v[214:217], v204 offset:37888
	ds_read_b128 v[238:241], v204 offset:38912
	ds_read_b128 v[246:249], v204 offset:39936
	global_load_lds_dwordx4 v[170:171], off
	s_mov_b32 m0, s90
	v_lshl_add_u64 v[170:171], s[48:49], 0, v[176:177]
	global_load_lds_dwordx4 v[170:171], off
	s_waitcnt vmcnt(8)
	s_waitcnt lgkmcnt(0)
	s_barrier
	v_mfma_f32_16x16x32_bf16 v[124:127], v[128:131], v[188:191], v[124:127]
	v_mfma_f32_16x16x32_bf16 v[120:123], v[136:139], v[188:191], v[120:123]
	v_mfma_f32_16x16x32_bf16 v[108:111], v[128:131], v[196:199], v[108:111]
	v_mfma_f32_16x16x32_bf16 v[104:107], v[136:139], v[196:199], v[104:107]
	v_mfma_f32_16x16x32_bf16 v[92:95], v[128:131], v[210:213], v[92:95]
	v_mfma_f32_16x16x32_bf16 v[88:91], v[136:139], v[210:213], v[88:91]
	v_mfma_f32_16x16x32_bf16 v[76:79], v[128:131], v[238:241], v[76:79]
	v_mfma_f32_16x16x32_bf16 v[72:75], v[136:139], v[238:241], v[72:75]
	v_mfma_f32_16x16x32_bf16 v[124:127], v[132:135], v[192:195], v[124:127]
	v_mfma_f32_16x16x32_bf16 v[120:123], v[140:143], v[192:195], v[120:123]
	v_mfma_f32_16x16x32_bf16 v[108:111], v[132:135], v[206:209], v[108:111]
	v_mfma_f32_16x16x32_bf16 v[104:107], v[140:143], v[206:209], v[104:107]
	v_mfma_f32_16x16x32_bf16 v[92:95], v[132:135], v[214:217], v[92:95]
	v_mfma_f32_16x16x32_bf16 v[88:91], v[140:143], v[214:217], v[88:91]
	v_mfma_f32_16x16x32_bf16 v[76:79], v[132:135], v[246:249], v[76:79]
	v_mfma_f32_16x16x32_bf16 v[72:75], v[140:143], v[246:249], v[72:75]
	v_mfma_f32_16x16x32_bf16 v[116:119], v[144:147], v[188:191], v[116:119]
	v_mfma_f32_16x16x32_bf16 v[112:115], v[152:155], v[188:191], v[112:115]
	v_mfma_f32_16x16x32_bf16 v[100:103], v[144:147], v[196:199], v[100:103]
	v_mfma_f32_16x16x32_bf16 v[96:99], v[152:155], v[196:199], v[96:99]
	v_mfma_f32_16x16x32_bf16 v[84:87], v[144:147], v[210:213], v[84:87]
	v_mfma_f32_16x16x32_bf16 v[80:83], v[152:155], v[210:213], v[80:83]
	v_mfma_f32_16x16x32_bf16 v[68:71], v[144:147], v[238:241], v[68:71]
	v_mfma_f32_16x16x32_bf16 v[64:67], v[152:155], v[238:241], v[64:67]
	v_mfma_f32_16x16x32_bf16 v[116:119], v[148:151], v[192:195], v[116:119]
	v_mfma_f32_16x16x32_bf16 v[112:115], v[156:159], v[192:195], v[112:115]
	v_mfma_f32_16x16x32_bf16 v[100:103], v[148:151], v[206:209], v[100:103]
	v_mfma_f32_16x16x32_bf16 v[96:99], v[156:159], v[206:209], v[96:99]
	v_mfma_f32_16x16x32_bf16 v[84:87], v[148:151], v[214:217], v[84:87]
	v_mfma_f32_16x16x32_bf16 v[80:83], v[156:159], v[214:217], v[80:83]
	v_mfma_f32_16x16x32_bf16 v[68:71], v[148:151], v[246:249], v[68:71]
	v_mfma_f32_16x16x32_bf16 v[64:67], v[156:159], v[246:249], v[64:67]
	s_barrier
	s_add_i32 s48, s50, s29
	v_lshl_add_u64 v[162:163], v[162:163], 0, s[88:89]
	s_mov_b32 m0, s48
	ds_read_b128 v[188:191], v204 offset:49152
	ds_read_b128 v[192:195], v204 offset:50176
	ds_read_b128 v[196:199], v204 offset:51200
	ds_read_b128 v[206:209], v204 offset:52224
	ds_read_b128 v[210:213], v204 offset:53248
	ds_read_b128 v[214:217], v204 offset:54272
	ds_read_b128 v[238:241], v204 offset:55296
	ds_read_b128 v[246:249], v204 offset:56320
	global_load_lds_dwordx4 v[162:163], off
	s_add_i32 m0, s48, 0x2000
	s_add_u32 s14, s14, 0x40080
	v_lshl_add_u64 v[162:163], v[164:165], 0, s[88:89]
	s_addc_u32 s15, s15, 0
	s_add_i32 s48, s51, s29
	global_load_lds_dwordx4 v[162:163], off
	s_mov_b32 m0, s48
	v_lshl_add_u64 v[162:163], s[14:15], 0, v[178:179]
	global_load_lds_dwordx4 v[162:163], off
	s_add_i32 m0, s48, 0x2000
	v_lshl_add_u64 v[162:163], s[14:15], 0, v[174:175]
	global_load_lds_dwordx4 v[162:163], off
	s_mov_b32 m0, s19
	v_lshl_add_u64 v[162:163], v[166:167], 0, s[88:89]
	global_load_lds_dwordx4 v[162:163], off
	s_mov_b32 m0, s33
	v_lshl_add_u64 v[162:163], v[168:169], 0, s[88:89]
	global_load_lds_dwordx4 v[162:163], off
	s_waitcnt vmcnt(8)
	s_waitcnt lgkmcnt(0)
	s_barrier
	v_mfma_f32_16x16x32_bf16 v[60:63], v[128:131], v[188:191], v[60:63]
	v_mfma_f32_16x16x32_bf16 v[56:59], v[136:139], v[188:191], v[56:59]
	v_mfma_f32_16x16x32_bf16 v[44:47], v[128:131], v[196:199], v[44:47]
	v_mfma_f32_16x16x32_bf16 v[40:43], v[136:139], v[196:199], v[40:43]
	v_mfma_f32_16x16x32_bf16 v[28:31], v[128:131], v[210:213], v[28:31]
	v_mfma_f32_16x16x32_bf16 v[24:27], v[136:139], v[210:213], v[24:27]
	v_mfma_f32_16x16x32_bf16 v[12:15], v[128:131], v[238:241], v[12:15]
	v_mfma_f32_16x16x32_bf16 v[8:11], v[136:139], v[238:241], v[8:11]
	v_mfma_f32_16x16x32_bf16 v[60:63], v[132:135], v[192:195], v[60:63]
	v_mfma_f32_16x16x32_bf16 v[56:59], v[140:143], v[192:195], v[56:59]
	v_mfma_f32_16x16x32_bf16 v[44:47], v[132:135], v[206:209], v[44:47]
	v_mfma_f32_16x16x32_bf16 v[40:43], v[140:143], v[206:209], v[40:43]
	v_mfma_f32_16x16x32_bf16 v[28:31], v[132:135], v[214:217], v[28:31]
	v_mfma_f32_16x16x32_bf16 v[24:27], v[140:143], v[214:217], v[24:27]
	v_mfma_f32_16x16x32_bf16 v[12:15], v[132:135], v[246:249], v[12:15]
	v_mfma_f32_16x16x32_bf16 v[8:11], v[140:143], v[246:249], v[8:11]
	v_mfma_f32_16x16x32_bf16 v[52:55], v[144:147], v[188:191], v[52:55]
	v_mfma_f32_16x16x32_bf16 v[48:51], v[152:155], v[188:191], v[48:51]
	v_mfma_f32_16x16x32_bf16 v[36:39], v[144:147], v[196:199], v[36:39]
	v_mfma_f32_16x16x32_bf16 v[32:35], v[152:155], v[196:199], v[32:35]
	v_mfma_f32_16x16x32_bf16 v[20:23], v[144:147], v[210:213], v[20:23]
	v_mfma_f32_16x16x32_bf16 v[16:19], v[152:155], v[210:213], v[16:19]
	v_mfma_f32_16x16x32_bf16 v[4:7], v[144:147], v[238:241], v[4:7]
	v_mfma_f32_16x16x32_bf16 v[0:3], v[152:155], v[238:241], v[0:3]
	v_mfma_f32_16x16x32_bf16 v[52:55], v[148:151], v[192:195], v[52:55]
	v_mfma_f32_16x16x32_bf16 v[48:51], v[156:159], v[192:195], v[48:51]
	v_mfma_f32_16x16x32_bf16 v[36:39], v[148:151], v[206:209], v[36:39]
	v_mfma_f32_16x16x32_bf16 v[32:35], v[156:159], v[206:209], v[32:35]
	v_mfma_f32_16x16x32_bf16 v[20:23], v[148:151], v[214:217], v[20:23]
	v_mfma_f32_16x16x32_bf16 v[16:19], v[156:159], v[214:217], v[16:19]
	v_mfma_f32_16x16x32_bf16 v[4:7], v[148:151], v[246:249], v[4:7]
	v_mfma_f32_16x16x32_bf16 v[0:3], v[156:159], v[246:249], v[0:3]
	s_barrier
	s_add_i32 s22, s22, 2
	s_add_u32 vcc_hi, vcc_hi, 0x100
	s_addc_u32 s21, s21, 0
	s_add_u32 s10, s10, 0x100
	s_addc_u32 s11, s11, 0
	s_cmp_gt_u32 s22, 13
	s_cbranch_scc0 .LBB0_139
	s_and_b64 vcc, exec, s[36:37]
	s_cbranch_vccz .LBB0_142
	s_barrier

.LBB0_178:
	s_add_u32 s10, s8, 0x100
	s_addc_u32 s11, s9, 0
	s_add_i32 s48, 0, 0x10000
	s_cmp_eq_u32 s22, 40
	s_cselect_b32 s15, s1, s11
	s_cselect_b32 s14, s0, s10
	s_cselect_b32 s13, s45, s96
	s_cselect_b32 s12, s44, s21
	s_add_i32 s49, 0, 0x14000
	v_add_u32_e32 v154, s48, v143
	v_add_u32_e32 v158, s49, v143
	ds_read_b128 v[138:141], v154
	ds_read_b128 v[146:149], v154 offset:1024
	ds_read_b128 v[150:153], v154 offset:2048
	ds_read_b128 v[154:157], v154 offset:3072
	ds_read_b128 v[174:177], v158
	ds_read_b128 v[178:181], v158 offset:1024
	ds_read_b128 v[182:185], v158 offset:2048
	ds_read_b128 v[186:189], v158 offset:3072
	v_lshl_add_u64 v[158:159], s[8:9], 0, v[136:137]
	s_add_i32 m0, s29, 0xc000
	ds_read_b128 v[190:193], v145
	ds_read_b128 v[194:197], v145 offset:1024
	ds_read_b128 v[198:201], v145 offset:2048
	ds_read_b128 v[202:205], v145 offset:3072
	ds_read_b128 v[206:209], v145 offset:4096
	ds_read_b128 v[210:213], v145 offset:5120
	ds_read_b128 v[214:217], v145 offset:6144
	ds_read_b128 v[238:241], v145 offset:7168
	global_load_lds_dwordx4 v[158:159], off
	s_add_i32 m0, s29, 0xe000
	v_lshl_add_u64 v[158:159], s[8:9], 0, v[134:135]
	global_load_lds_dwordx4 v[158:159], off
	s_waitcnt vmcnt(8)
	s_waitcnt lgkmcnt(0)
	s_barrier
	v_mfma_f32_16x16x32_bf16 v[124:127], v[138:141], v[190:193], v[124:127]
	v_mfma_f32_16x16x32_bf16 v[120:123], v[150:153], v[190:193], v[120:123]
	v_mfma_f32_16x16x32_bf16 v[108:111], v[138:141], v[198:201], v[108:111]
	v_mfma_f32_16x16x32_bf16 v[104:107], v[150:153], v[198:201], v[104:107]
	v_mfma_f32_16x16x32_bf16 v[92:95], v[138:141], v[206:209], v[92:95]
	v_mfma_f32_16x16x32_bf16 v[88:91], v[150:153], v[206:209], v[88:91]
	v_mfma_f32_16x16x32_bf16 v[76:79], v[138:141], v[214:217], v[76:79]
	v_mfma_f32_16x16x32_bf16 v[72:75], v[150:153], v[214:217], v[72:75]
	v_mfma_f32_16x16x32_bf16 v[124:127], v[146:149], v[194:197], v[124:127]
	v_mfma_f32_16x16x32_bf16 v[120:123], v[154:157], v[194:197], v[120:123]
	v_mfma_f32_16x16x32_bf16 v[108:111], v[146:149], v[202:205], v[108:111]
	v_mfma_f32_16x16x32_bf16 v[104:107], v[154:157], v[202:205], v[104:107]
	v_mfma_f32_16x16x32_bf16 v[92:95], v[146:149], v[210:213], v[92:95]
	v_mfma_f32_16x16x32_bf16 v[88:91], v[154:157], v[210:213], v[88:91]
	v_mfma_f32_16x16x32_bf16 v[76:79], v[146:149], v[238:241], v[76:79]
	v_mfma_f32_16x16x32_bf16 v[72:75], v[154:157], v[238:241], v[72:75]
	v_mfma_f32_16x16x32_bf16 v[116:119], v[174:177], v[190:193], v[116:119]
	v_mfma_f32_16x16x32_bf16 v[112:115], v[182:185], v[190:193], v[112:115]
	v_mfma_f32_16x16x32_bf16 v[100:103], v[174:177], v[198:201], v[100:103]
	v_mfma_f32_16x16x32_bf16 v[96:99], v[182:185], v[198:201], v[96:99]
	v_mfma_f32_16x16x32_bf16 v[84:87], v[174:177], v[206:209], v[84:87]
	v_mfma_f32_16x16x32_bf16 v[80:83], v[182:185], v[206:209], v[80:83]
	v_mfma_f32_16x16x32_bf16 v[68:71], v[174:177], v[214:217], v[68:71]
	v_mfma_f32_16x16x32_bf16 v[64:67], v[182:185], v[214:217], v[64:67]
	v_mfma_f32_16x16x32_bf16 v[116:119], v[178:181], v[194:197], v[116:119]
	v_mfma_f32_16x16x32_bf16 v[112:115], v[186:189], v[194:197], v[112:115]
	v_mfma_f32_16x16x32_bf16 v[100:103], v[178:181], v[202:205], v[100:103]
	v_mfma_f32_16x16x32_bf16 v[96:99], v[186:189], v[202:205], v[96:99]
	v_mfma_f32_16x16x32_bf16 v[84:87], v[178:181], v[210:213], v[84:87]
	v_mfma_f32_16x16x32_bf16 v[80:83], v[186:189], v[210:213], v[80:83]
	v_mfma_f32_16x16x32_bf16 v[68:71], v[178:181], v[238:241], v[68:71]
	v_mfma_f32_16x16x32_bf16 v[64:67], v[186:189], v[238:241], v[64:67]
	s_barrier
	s_add_i32 s8, s48, s28
	v_lshl_add_u64 v[158:159], s[12:13], 0, v[160:161]
	s_mov_b32 m0, s8
	ds_read_b128 v[190:193], v145 offset:16384
	ds_read_b128 v[194:197], v145 offset:17408
	ds_read_b128 v[198:201], v145 offset:18432
	ds_read_b128 v[202:205], v145 offset:19456
	ds_read_b128 v[206:209], v145 offset:20480
	ds_read_b128 v[210:213], v145 offset:21504
	ds_read_b128 v[214:217], v145 offset:22528
	ds_read_b128 v[238:241], v145 offset:23552
	global_load_lds_dwordx4 v[158:159], off
	s_add_i32 m0, s8, 0x2000
	s_add_u32 s8, s12, 0xb0000
	v_lshl_add_u64 v[162:163], s[12:13], 0, v[132:133]
	s_addc_u32 s9, s13, 0
	s_add_i32 s48, s49, s28
	global_load_lds_dwordx4 v[162:163], off
	v_lshl_add_u64 v[164:165], s[8:9], 0, v[160:161]
	s_mov_b32 m0, s48
	v_lshl_add_u64 v[166:167], s[14:15], 0, v[130:131]
	global_load_lds_dwordx4 v[164:165], off
	s_add_i32 m0, s48, 0x2000
	v_lshl_add_u64 v[164:165], s[8:9], 0, v[132:133]
	global_load_lds_dwordx4 v[164:165], off
	s_mov_b32 m0, s29
	v_lshl_add_u64 v[164:165], s[14:15], 0, v[128:129]
	global_load_lds_dwordx4 v[164:165], off
	s_mov_b32 m0, s30
	s_nop 0
	global_load_lds_dwordx4 v[166:167], off
	s_waitcnt vmcnt(8)
	s_waitcnt lgkmcnt(0)
	s_barrier
	v_mfma_f32_16x16x32_bf16 v[60:63], v[138:141], v[190:193], v[60:63]
	v_mfma_f32_16x16x32_bf16 v[56:59], v[150:153], v[190:193], v[56:59]
	v_mfma_f32_16x16x32_bf16 v[44:47], v[138:141], v[198:201], v[44:47]
	v_mfma_f32_16x16x32_bf16 v[40:43], v[150:153], v[198:201], v[40:43]
	v_mfma_f32_16x16x32_bf16 v[28:31], v[138:141], v[206:209], v[28:31]
	v_mfma_f32_16x16x32_bf16 v[24:27], v[150:153], v[206:209], v[24:27]
	v_mfma_f32_16x16x32_bf16 v[12:15], v[138:141], v[214:217], v[12:15]
	v_mfma_f32_16x16x32_bf16 v[8:11], v[150:153], v[214:217], v[8:11]
	v_mfma_f32_16x16x32_bf16 v[60:63], v[146:149], v[194:197], v[60:63]
	v_mfma_f32_16x16x32_bf16 v[56:59], v[154:157], v[194:197], v[56:59]
	v_mfma_f32_16x16x32_bf16 v[44:47], v[146:149], v[202:205], v[44:47]
	v_mfma_f32_16x16x32_bf16 v[40:43], v[154:157], v[202:205], v[40:43]
	v_mfma_f32_16x16x32_bf16 v[28:31], v[146:149], v[210:213], v[28:31]
	v_mfma_f32_16x16x32_bf16 v[24:27], v[154:157], v[210:213], v[24:27]
	v_mfma_f32_16x16x32_bf16 v[12:15], v[146:149], v[238:241], v[12:15]
	v_mfma_f32_16x16x32_bf16 v[8:11], v[154:157], v[238:241], v[8:11]
	v_mfma_f32_16x16x32_bf16 v[52:55], v[174:177], v[190:193], v[52:55]
	v_mfma_f32_16x16x32_bf16 v[48:51], v[182:185], v[190:193], v[48:51]
	v_mfma_f32_16x16x32_bf16 v[36:39], v[174:177], v[198:201], v[36:39]
	v_mfma_f32_16x16x32_bf16 v[32:35], v[182:185], v[198:201], v[32:35]
	v_mfma_f32_16x16x32_bf16 v[20:23], v[174:177], v[206:209], v[20:23]
	v_mfma_f32_16x16x32_bf16 v[16:19], v[182:185], v[206:209], v[16:19]
	v_mfma_f32_16x16x32_bf16 v[4:7], v[174:177], v[214:217], v[4:7]
	v_mfma_f32_16x16x32_bf16 v[0:3], v[182:185], v[214:217], v[0:3]
	v_mfma_f32_16x16x32_bf16 v[52:55], v[178:181], v[194:197], v[52:55]
	v_mfma_f32_16x16x32_bf16 v[48:51], v[186:189], v[194:197], v[48:51]
	v_mfma_f32_16x16x32_bf16 v[36:39], v[178:181], v[202:205], v[36:39]
	v_mfma_f32_16x16x32_bf16 v[32:35], v[186:189], v[202:205], v[32:35]
	v_mfma_f32_16x16x32_bf16 v[20:23], v[178:181], v[210:213], v[20:23]
	v_mfma_f32_16x16x32_bf16 v[16:19], v[186:189], v[210:213], v[16:19]
	v_mfma_f32_16x16x32_bf16 v[4:7], v[178:181], v[238:241], v[4:7]
	v_mfma_f32_16x16x32_bf16 v[0:3], v[186:189], v[238:241], v[0:3]
	s_barrier
	s_add_i32 s48, 0, 0x18000
	s_add_i32 s49, 0, 0x1c000
	v_add_u32_e32 v154, s48, v143
	v_add_u32_e32 v168, s49, v143
	ds_read_b128 v[138:141], v154
	ds_read_b128 v[146:149], v154 offset:1024
	ds_read_b128 v[150:153], v154 offset:2048
	ds_read_b128 v[154:157], v154 offset:3072
	ds_read_b128 v[174:177], v168
	ds_read_b128 v[178:181], v168 offset:1024
	ds_read_b128 v[182:185], v168 offset:2048
	ds_read_b128 v[186:189], v168 offset:3072
	s_add_u32 s8, s14, 0xb0000
	s_addc_u32 s9, s15, 0
	s_mov_b32 m0, s31
	v_lshl_add_u64 v[168:169], s[8:9], 0, v[128:129]
	ds_read_b128 v[190:193], v145 offset:32768
	ds_read_b128 v[194:197], v145 offset:33792
	ds_read_b128 v[198:201], v145 offset:34816
	ds_read_b128 v[202:205], v145 offset:35840
	ds_read_b128 v[206:209], v145 offset:36864
	ds_read_b128 v[210:213], v145 offset:37888
	ds_read_b128 v[214:217], v145 offset:38912
	ds_read_b128 v[238:241], v145 offset:39936
	global_load_lds_dwordx4 v[168:169], off
	s_mov_b32 m0, s33
	v_lshl_add_u64 v[168:169], s[8:9], 0, v[130:131]
	global_load_lds_dwordx4 v[168:169], off
	s_waitcnt vmcnt(8)
	s_waitcnt lgkmcnt(0)
	s_barrier
	v_mfma_f32_16x16x32_bf16 v[124:127], v[138:141], v[190:193], v[124:127]
	v_mfma_f32_16x16x32_bf16 v[120:123], v[150:153], v[190:193], v[120:123]
	v_mfma_f32_16x16x32_bf16 v[108:111], v[138:141], v[198:201], v[108:111]
	v_mfma_f32_16x16x32_bf16 v[104:107], v[150:153], v[198:201], v[104:107]
	v_mfma_f32_16x16x32_bf16 v[92:95], v[138:141], v[206:209], v[92:95]
	v_mfma_f32_16x16x32_bf16 v[88:91], v[150:153], v[206:209], v[88:91]
	v_mfma_f32_16x16x32_bf16 v[76:79], v[138:141], v[214:217], v[76:79]
	v_mfma_f32_16x16x32_bf16 v[72:75], v[150:153], v[214:217], v[72:75]
	v_mfma_f32_16x16x32_bf16 v[124:127], v[146:149], v[194:197], v[124:127]
	v_mfma_f32_16x16x32_bf16 v[120:123], v[154:157], v[194:197], v[120:123]
	v_mfma_f32_16x16x32_bf16 v[108:111], v[146:149], v[202:205], v[108:111]
	v_mfma_f32_16x16x32_bf16 v[104:107], v[154:157], v[202:205], v[104:107]
	v_mfma_f32_16x16x32_bf16 v[92:95], v[146:149], v[210:213], v[92:95]
	v_mfma_f32_16x16x32_bf16 v[88:91], v[154:157], v[210:213], v[88:91]
	v_mfma_f32_16x16x32_bf16 v[76:79], v[146:149], v[238:241], v[76:79]
	v_mfma_f32_16x16x32_bf16 v[72:75], v[154:157], v[238:241], v[72:75]
	v_mfma_f32_16x16x32_bf16 v[116:119], v[174:177], v[190:193], v[116:119]
	v_mfma_f32_16x16x32_bf16 v[112:115], v[182:185], v[190:193], v[112:115]
	v_mfma_f32_16x16x32_bf16 v[100:103], v[174:177], v[198:201], v[100:103]
	v_mfma_f32_16x16x32_bf16 v[96:99], v[182:185], v[198:201], v[96:99]
	v_mfma_f32_16x16x32_bf16 v[84:87], v[174:177], v[206:209], v[84:87]
	v_mfma_f32_16x16x32_bf16 v[80:83], v[182:185], v[206:209], v[80:83]
	v_mfma_f32_16x16x32_bf16 v[68:71], v[174:177], v[214:217], v[68:71]
	v_mfma_f32_16x16x32_bf16 v[64:67], v[182:185], v[214:217], v[64:67]
	v_mfma_f32_16x16x32_bf16 v[116:119], v[178:181], v[194:197], v[116:119]
	v_mfma_f32_16x16x32_bf16 v[112:115], v[186:189], v[194:197], v[112:115]
	v_mfma_f32_16x16x32_bf16 v[100:103], v[178:181], v[202:205], v[100:103]
	v_mfma_f32_16x16x32_bf16 v[96:99], v[186:189], v[202:205], v[96:99]
	v_mfma_f32_16x16x32_bf16 v[84:87], v[178:181], v[210:213], v[84:87]
	v_mfma_f32_16x16x32_bf16 v[80:83], v[186:189], v[210:213], v[80:83]
	v_mfma_f32_16x16x32_bf16 v[68:71], v[178:181], v[238:241], v[68:71]
	v_mfma_f32_16x16x32_bf16 v[64:67], v[186:189], v[238:241], v[64:67]
	s_barrier
	s_add_i32 s8, s48, s28
	v_lshl_add_u64 v[158:159], v[158:159], 0, s[88:89]
	s_mov_b32 m0, s8
	ds_read_b128 v[190:193], v145 offset:49152
	ds_read_b128 v[194:197], v145 offset:50176
	ds_read_b128 v[198:201], v145 offset:51200
	ds_read_b128 v[202:205], v145 offset:52224
	ds_read_b128 v[206:209], v145 offset:53248
	ds_read_b128 v[210:213], v145 offset:54272
	ds_read_b128 v[214:217], v145 offset:55296
	ds_read_b128 v[238:241], v145 offset:56320
	global_load_lds_dwordx4 v[158:159], off
	s_add_i32 m0, s8, 0x2000
	s_add_u32 s8, s12, 0xb0080
	v_lshl_add_u64 v[158:159], v[162:163], 0, s[88:89]
	s_addc_u32 s9, s13, 0
	s_add_i32 s12, s49, s28
	global_load_lds_dwordx4 v[158:159], off
	s_mov_b32 m0, s12
	v_lshl_add_u64 v[158:159], s[8:9], 0, v[160:161]
	global_load_lds_dwordx4 v[158:159], off
	s_add_i32 m0, s12, 0x2000
	v_lshl_add_u64 v[158:159], s[8:9], 0, v[132:133]
	global_load_lds_dwordx4 v[158:159], off
	s_mov_b32 m0, s34
	v_lshl_add_u64 v[158:159], v[164:165], 0, s[88:89]
	global_load_lds_dwordx4 v[158:159], off
	s_mov_b32 m0, s35
	v_lshl_add_u64 v[158:159], v[166:167], 0, s[88:89]
	global_load_lds_dwordx4 v[158:159], off
	s_waitcnt vmcnt(8)
	s_waitcnt lgkmcnt(0)
	s_barrier
	v_mfma_f32_16x16x32_bf16 v[60:63], v[138:141], v[190:193], v[60:63]
	v_mfma_f32_16x16x32_bf16 v[56:59], v[150:153], v[190:193], v[56:59]
	v_mfma_f32_16x16x32_bf16 v[44:47], v[138:141], v[198:201], v[44:47]
	v_mfma_f32_16x16x32_bf16 v[40:43], v[150:153], v[198:201], v[40:43]
	v_mfma_f32_16x16x32_bf16 v[28:31], v[138:141], v[206:209], v[28:31]
	v_mfma_f32_16x16x32_bf16 v[24:27], v[150:153], v[206:209], v[24:27]
	v_mfma_f32_16x16x32_bf16 v[12:15], v[138:141], v[214:217], v[12:15]
	v_mfma_f32_16x16x32_bf16 v[8:11], v[150:153], v[214:217], v[8:11]
	v_mfma_f32_16x16x32_bf16 v[60:63], v[146:149], v[194:197], v[60:63]
	v_mfma_f32_16x16x32_bf16 v[56:59], v[154:157], v[194:197], v[56:59]
	v_mfma_f32_16x16x32_bf16 v[44:47], v[146:149], v[202:205], v[44:47]
	v_mfma_f32_16x16x32_bf16 v[40:43], v[154:157], v[202:205], v[40:43]
	v_mfma_f32_16x16x32_bf16 v[28:31], v[146:149], v[210:213], v[28:31]
	v_mfma_f32_16x16x32_bf16 v[24:27], v[154:157], v[210:213], v[24:27]
	v_mfma_f32_16x16x32_bf16 v[12:15], v[146:149], v[238:241], v[12:15]
	v_mfma_f32_16x16x32_bf16 v[8:11], v[154:157], v[238:241], v[8:11]
	v_mfma_f32_16x16x32_bf16 v[52:55], v[174:177], v[190:193], v[52:55]
	v_mfma_f32_16x16x32_bf16 v[48:51], v[182:185], v[190:193], v[48:51]
	v_mfma_f32_16x16x32_bf16 v[36:39], v[174:177], v[198:201], v[36:39]
	v_mfma_f32_16x16x32_bf16 v[32:35], v[182:185], v[198:201], v[32:35]
	v_mfma_f32_16x16x32_bf16 v[20:23], v[174:177], v[206:209], v[20:23]
	v_mfma_f32_16x16x32_bf16 v[16:19], v[182:185], v[206:209], v[16:19]
	v_mfma_f32_16x16x32_bf16 v[4:7], v[174:177], v[214:217], v[4:7]
	v_mfma_f32_16x16x32_bf16 v[0:3], v[182:185], v[214:217], v[0:3]
	v_mfma_f32_16x16x32_bf16 v[52:55], v[178:181], v[194:197], v[52:55]
	v_mfma_f32_16x16x32_bf16 v[48:51], v[186:189], v[194:197], v[48:51]
	v_mfma_f32_16x16x32_bf16 v[36:39], v[178:181], v[202:205], v[36:39]
	v_mfma_f32_16x16x32_bf16 v[32:35], v[186:189], v[202:205], v[32:35]
	v_mfma_f32_16x16x32_bf16 v[20:23], v[178:181], v[210:213], v[20:23]
	v_mfma_f32_16x16x32_bf16 v[16:19], v[186:189], v[210:213], v[16:19]
	v_mfma_f32_16x16x32_bf16 v[4:7], v[178:181], v[238:241], v[4:7]
	v_mfma_f32_16x16x32_bf16 v[0:3], v[186:189], v[238:241], v[0:3]
	s_barrier
	s_add_i32 s22, s22, 2
	s_add_u32 s21, s21, 0x100
	s_addc_u32 s96, s96, 0
	s_cmp_gt_u32 s22, 41
	s_mov_b64 s[8:9], s[10:11]
	s_cbranch_scc0 .LBB0_178
	v_lshl_add_u32 v140, s20, 8, v142
	v_lshl_or_b32 v138, s93, 8, v144
	v_lshlrev_b32_e32 v141, 11, v140
	v_lshl_add_u32 v138, v138, 1, v141
	v_lshlrev_b32_e32 v139, 3, v140
	s_mov_b64 s[8:9], s[4:5]
	global_load_dwordx4 v[146:149], v138, s[8:9]
	global_load_dwordx4 v[150:153], v138, s[8:9] offset:256
	s_add_u32 s8, s8, 0x8000
	s_addc_u32 s9, s9, 0
	global_load_dwordx4 v[154:157], v138, s[8:9]
	global_load_dwordx4 v[162:165], v138, s[8:9] offset:256
	s_add_u32 s8, s8, 0x8000
	s_addc_u32 s9, s9, 0
	global_load_dwordx4 v[166:169], v138, s[8:9]
	global_load_dwordx4 v[174:177], v138, s[8:9] offset:256
	s_add_u32 s8, s8, 0x8000
	s_addc_u32 s9, s9, 0
	global_load_dwordx4 v[178:181], v138, s[8:9]
	global_load_dwordx4 v[182:185], v138, s[8:9] offset:256
	s_add_u32 s8, s8, 0x28000
	s_addc_u32 s9, s9, 0
	global_load_dwordx4 v[186:189], v138, s[8:9]
	global_load_dwordx4 v[190:193], v138, s[8:9] offset:256
	s_add_u32 s8, s8, 0x8000
	s_addc_u32 s9, s9, 0
	global_load_dwordx4 v[194:197], v138, s[8:9]
	global_load_dwordx4 v[198:201], v138, s[8:9] offset:256
	s_add_u32 s8, s8, 0x8000
	s_addc_u32 s9, s9, 0
	global_load_dwordx4 v[202:205], v138, s[8:9]
	global_load_dwordx4 v[206:209], v138, s[8:9] offset:256
	s_add_u32 s8, s8, 0x8000
	s_addc_u32 s9, s9, 0
	global_load_dwordx4 v[210:213], v138, s[8:9]
	global_load_dwordx4 v[214:217], v138, s[8:9] offset:256
	s_and_b64 vcc, exec, s[36:37]
	s_cbranch_vccz .LBB0_181
	s_barrier

.LBB0_212:
	s_add_u32 s12, s10, 0xfffc0080
	s_addc_u32 s13, s11, -1
	s_add_i32 s22, 0, 0x10000
	s_cmp_eq_u32 s21, 12
	s_cselect_b32 s15, s20, s13
	s_cselect_b32 s14, s37, s12
	s_cselect_b32 s13, s41, s97
	s_cselect_b32 s12, s91, s96
	s_add_i32 s50, 0, 0x14000
	v_add_u32_e32 v154, s22, v147
	v_add_u32_e32 v158, s50, v147
	ds_read_b128 v[138:141], v154
	ds_read_b128 v[142:145], v154 offset:1024
	ds_read_b128 v[150:153], v154 offset:2048
	ds_read_b128 v[154:157], v154 offset:3072
	ds_read_b128 v[174:177], v158
	ds_read_b128 v[178:181], v158 offset:1024
	ds_read_b128 v[182:185], v158 offset:2048
	ds_read_b128 v[186:189], v158 offset:3072
	v_lshl_add_u64 v[158:159], s[10:11], 0, v[136:137]
	s_add_i32 m0, s30, 0xc000
	ds_read_b128 v[190:193], v149
	ds_read_b128 v[194:197], v149 offset:1024
	ds_read_b128 v[198:201], v149 offset:2048
	ds_read_b128 v[202:205], v149 offset:3072
	ds_read_b128 v[206:209], v149 offset:4096
	ds_read_b128 v[210:213], v149 offset:5120
	ds_read_b128 v[214:217], v149 offset:6144
	ds_read_b128 v[238:241], v149 offset:7168
	global_load_lds_dwordx4 v[158:159], off
	s_add_i32 m0, s30, 0xe000
	v_lshl_add_u64 v[158:159], s[10:11], 0, v[134:135]
	global_load_lds_dwordx4 v[158:159], off
	s_waitcnt vmcnt(8)
	s_waitcnt lgkmcnt(0)
	s_barrier
	v_mfma_f32_16x16x32_bf16 v[124:127], v[138:141], v[190:193], v[124:127]
	v_mfma_f32_16x16x32_bf16 v[116:119], v[150:153], v[190:193], v[116:119]
	v_mfma_f32_16x16x32_bf16 v[108:111], v[138:141], v[198:201], v[108:111]
	v_mfma_f32_16x16x32_bf16 v[100:103], v[150:153], v[198:201], v[100:103]
	v_mfma_f32_16x16x32_bf16 v[92:95], v[138:141], v[206:209], v[92:95]
	v_mfma_f32_16x16x32_bf16 v[84:87], v[150:153], v[206:209], v[84:87]
	v_mfma_f32_16x16x32_bf16 v[76:79], v[138:141], v[214:217], v[76:79]
	v_mfma_f32_16x16x32_bf16 v[64:67], v[150:153], v[214:217], v[64:67]
	v_mfma_f32_16x16x32_bf16 v[124:127], v[142:145], v[194:197], v[124:127]
	v_mfma_f32_16x16x32_bf16 v[116:119], v[154:157], v[194:197], v[116:119]
	v_mfma_f32_16x16x32_bf16 v[108:111], v[142:145], v[202:205], v[108:111]
	v_mfma_f32_16x16x32_bf16 v[100:103], v[154:157], v[202:205], v[100:103]
	v_mfma_f32_16x16x32_bf16 v[92:95], v[142:145], v[210:213], v[92:95]
	v_mfma_f32_16x16x32_bf16 v[84:87], v[154:157], v[210:213], v[84:87]
	v_mfma_f32_16x16x32_bf16 v[76:79], v[142:145], v[238:241], v[76:79]
	v_mfma_f32_16x16x32_bf16 v[64:67], v[154:157], v[238:241], v[64:67]
	v_mfma_f32_16x16x32_bf16 v[120:123], v[174:177], v[190:193], v[120:123]
	v_mfma_f32_16x16x32_bf16 v[112:115], v[182:185], v[190:193], v[112:115]
	v_mfma_f32_16x16x32_bf16 v[104:107], v[174:177], v[198:201], v[104:107]
	v_mfma_f32_16x16x32_bf16 v[96:99], v[182:185], v[198:201], v[96:99]
	v_mfma_f32_16x16x32_bf16 v[88:91], v[174:177], v[206:209], v[88:91]
	v_mfma_f32_16x16x32_bf16 v[80:83], v[182:185], v[206:209], v[80:83]
	v_mfma_f32_16x16x32_bf16 v[72:75], v[174:177], v[214:217], v[72:75]
	v_mfma_f32_16x16x32_bf16 v[68:71], v[182:185], v[214:217], v[68:71]
	v_mfma_f32_16x16x32_bf16 v[120:123], v[178:181], v[194:197], v[120:123]
	v_mfma_f32_16x16x32_bf16 v[112:115], v[186:189], v[194:197], v[112:115]
	v_mfma_f32_16x16x32_bf16 v[104:107], v[178:181], v[202:205], v[104:107]
	v_mfma_f32_16x16x32_bf16 v[96:99], v[186:189], v[202:205], v[96:99]
	v_mfma_f32_16x16x32_bf16 v[88:91], v[178:181], v[210:213], v[88:91]
	v_mfma_f32_16x16x32_bf16 v[80:83], v[186:189], v[210:213], v[80:83]
	v_mfma_f32_16x16x32_bf16 v[72:75], v[178:181], v[238:241], v[72:75]
	v_mfma_f32_16x16x32_bf16 v[68:71], v[186:189], v[238:241], v[68:71]
	s_barrier
	s_add_i32 s22, s22, s28
	v_lshl_add_u64 v[158:159], s[12:13], 0, v[160:161]
	s_mov_b32 m0, s22
	ds_read_b128 v[190:193], v149 offset:16384
	ds_read_b128 v[194:197], v149 offset:17408
	ds_read_b128 v[198:201], v149 offset:18432
	ds_read_b128 v[202:205], v149 offset:19456
	ds_read_b128 v[206:209], v149 offset:20480
	ds_read_b128 v[210:213], v149 offset:21504
	ds_read_b128 v[214:217], v149 offset:22528
	ds_read_b128 v[238:241], v149 offset:23552
	global_load_lds_dwordx4 v[158:159], off
	s_add_i32 m0, s22, 0x2000
	s_add_u32 s48, s12, 0x40000
	v_lshl_add_u64 v[162:163], s[12:13], 0, v[128:129]
	s_addc_u32 s49, s13, 0
	s_add_i32 s22, s50, s28
	global_load_lds_dwordx4 v[162:163], off
	v_lshl_add_u64 v[164:165], s[48:49], 0, v[160:161]
	s_mov_b32 m0, s22
	v_lshl_add_u64 v[166:167], s[14:15], 0, v[130:131]
	global_load_lds_dwordx4 v[164:165], off
	s_add_i32 m0, s22, 0x2000
	v_lshl_add_u64 v[164:165], s[48:49], 0, v[128:129]
	global_load_lds_dwordx4 v[164:165], off
	s_mov_b32 m0, s30
	v_lshl_add_u64 v[164:165], s[14:15], 0, v[132:133]
	global_load_lds_dwordx4 v[164:165], off
	s_mov_b32 m0, s31
	s_nop 0
	global_load_lds_dwordx4 v[166:167], off
	s_waitcnt vmcnt(8)
	s_waitcnt lgkmcnt(0)
	s_barrier
	v_mfma_f32_16x16x32_bf16 v[60:63], v[138:141], v[190:193], v[60:63]
	v_mfma_f32_16x16x32_bf16 v[48:51], v[150:153], v[190:193], v[48:51]
	v_mfma_f32_16x16x32_bf16 v[44:47], v[138:141], v[198:201], v[44:47]
	v_mfma_f32_16x16x32_bf16 v[32:35], v[150:153], v[198:201], v[32:35]
	v_mfma_f32_16x16x32_bf16 v[28:31], v[138:141], v[206:209], v[28:31]
	v_mfma_f32_16x16x32_bf16 v[16:19], v[150:153], v[206:209], v[16:19]
	v_mfma_f32_16x16x32_bf16 v[12:15], v[138:141], v[214:217], v[12:15]
	v_mfma_f32_16x16x32_bf16 v[0:3], v[150:153], v[214:217], v[0:3]
	v_mfma_f32_16x16x32_bf16 v[60:63], v[142:145], v[194:197], v[60:63]
	v_mfma_f32_16x16x32_bf16 v[48:51], v[154:157], v[194:197], v[48:51]
	v_mfma_f32_16x16x32_bf16 v[44:47], v[142:145], v[202:205], v[44:47]
	v_mfma_f32_16x16x32_bf16 v[32:35], v[154:157], v[202:205], v[32:35]
	v_mfma_f32_16x16x32_bf16 v[28:31], v[142:145], v[210:213], v[28:31]
	v_mfma_f32_16x16x32_bf16 v[16:19], v[154:157], v[210:213], v[16:19]
	v_mfma_f32_16x16x32_bf16 v[12:15], v[142:145], v[238:241], v[12:15]
	v_mfma_f32_16x16x32_bf16 v[0:3], v[154:157], v[238:241], v[0:3]
	v_mfma_f32_16x16x32_bf16 v[56:59], v[174:177], v[190:193], v[56:59]
	v_mfma_f32_16x16x32_bf16 v[52:55], v[182:185], v[190:193], v[52:55]
	v_mfma_f32_16x16x32_bf16 v[40:43], v[174:177], v[198:201], v[40:43]
	v_mfma_f32_16x16x32_bf16 v[36:39], v[182:185], v[198:201], v[36:39]
	v_mfma_f32_16x16x32_bf16 v[24:27], v[174:177], v[206:209], v[24:27]
	v_mfma_f32_16x16x32_bf16 v[20:23], v[182:185], v[206:209], v[20:23]
	v_mfma_f32_16x16x32_bf16 v[8:11], v[174:177], v[214:217], v[8:11]
	v_mfma_f32_16x16x32_bf16 v[4:7], v[182:185], v[214:217], v[4:7]
	v_mfma_f32_16x16x32_bf16 v[56:59], v[178:181], v[194:197], v[56:59]
	v_mfma_f32_16x16x32_bf16 v[52:55], v[186:189], v[194:197], v[52:55]
	v_mfma_f32_16x16x32_bf16 v[40:43], v[178:181], v[202:205], v[40:43]
	v_mfma_f32_16x16x32_bf16 v[36:39], v[186:189], v[202:205], v[36:39]
	v_mfma_f32_16x16x32_bf16 v[24:27], v[178:181], v[210:213], v[24:27]
	v_mfma_f32_16x16x32_bf16 v[20:23], v[186:189], v[210:213], v[20:23]
	v_mfma_f32_16x16x32_bf16 v[8:11], v[178:181], v[238:241], v[8:11]
	v_mfma_f32_16x16x32_bf16 v[4:7], v[186:189], v[238:241], v[4:7]
	s_barrier
	s_add_i32 s22, 0, 0x18000
	s_add_i32 s48, 0, 0x1c000
	v_add_u32_e32 v154, s22, v147
	v_add_u32_e32 v168, s48, v147
	ds_read_b128 v[138:141], v154
	ds_read_b128 v[142:145], v154 offset:1024
	ds_read_b128 v[150:153], v154 offset:2048
	ds_read_b128 v[154:157], v154 offset:3072
	ds_read_b128 v[174:177], v168
	ds_read_b128 v[178:181], v168 offset:1024
	ds_read_b128 v[182:185], v168 offset:2048
	ds_read_b128 v[186:189], v168 offset:3072
	s_add_u32 s14, s14, 0x40000
	s_addc_u32 s15, s15, 0
	s_mov_b32 m0, s33
	v_lshl_add_u64 v[168:169], s[14:15], 0, v[132:133]
	ds_read_b128 v[190:193], v149 offset:32768
	ds_read_b128 v[194:197], v149 offset:33792
	ds_read_b128 v[198:201], v149 offset:34816
	ds_read_b128 v[202:205], v149 offset:35840
	ds_read_b128 v[206:209], v149 offset:36864
	ds_read_b128 v[210:213], v149 offset:37888
	ds_read_b128 v[214:217], v149 offset:38912
	ds_read_b128 v[238:241], v149 offset:39936
	global_load_lds_dwordx4 v[168:169], off
	s_mov_b32 m0, s34
	v_lshl_add_u64 v[168:169], s[14:15], 0, v[130:131]
	global_load_lds_dwordx4 v[168:169], off
	s_waitcnt vmcnt(8)
	s_waitcnt lgkmcnt(0)
	s_barrier
	v_mfma_f32_16x16x32_bf16 v[124:127], v[138:141], v[190:193], v[124:127]
	v_mfma_f32_16x16x32_bf16 v[116:119], v[150:153], v[190:193], v[116:119]
	v_mfma_f32_16x16x32_bf16 v[108:111], v[138:141], v[198:201], v[108:111]
	v_mfma_f32_16x16x32_bf16 v[100:103], v[150:153], v[198:201], v[100:103]
	v_mfma_f32_16x16x32_bf16 v[92:95], v[138:141], v[206:209], v[92:95]
	v_mfma_f32_16x16x32_bf16 v[84:87], v[150:153], v[206:209], v[84:87]
	v_mfma_f32_16x16x32_bf16 v[76:79], v[138:141], v[214:217], v[76:79]
	v_mfma_f32_16x16x32_bf16 v[64:67], v[150:153], v[214:217], v[64:67]
	v_mfma_f32_16x16x32_bf16 v[124:127], v[142:145], v[194:197], v[124:127]
	v_mfma_f32_16x16x32_bf16 v[116:119], v[154:157], v[194:197], v[116:119]
	v_mfma_f32_16x16x32_bf16 v[108:111], v[142:145], v[202:205], v[108:111]
	v_mfma_f32_16x16x32_bf16 v[100:103], v[154:157], v[202:205], v[100:103]
	v_mfma_f32_16x16x32_bf16 v[92:95], v[142:145], v[210:213], v[92:95]
	v_mfma_f32_16x16x32_bf16 v[84:87], v[154:157], v[210:213], v[84:87]
	v_mfma_f32_16x16x32_bf16 v[76:79], v[142:145], v[238:241], v[76:79]
	v_mfma_f32_16x16x32_bf16 v[64:67], v[154:157], v[238:241], v[64:67]
	v_mfma_f32_16x16x32_bf16 v[120:123], v[174:177], v[190:193], v[120:123]
	v_mfma_f32_16x16x32_bf16 v[112:115], v[182:185], v[190:193], v[112:115]
	v_mfma_f32_16x16x32_bf16 v[104:107], v[174:177], v[198:201], v[104:107]
	v_mfma_f32_16x16x32_bf16 v[96:99], v[182:185], v[198:201], v[96:99]
	v_mfma_f32_16x16x32_bf16 v[88:91], v[174:177], v[206:209], v[88:91]
	v_mfma_f32_16x16x32_bf16 v[80:83], v[182:185], v[206:209], v[80:83]
	v_mfma_f32_16x16x32_bf16 v[72:75], v[174:177], v[214:217], v[72:75]
	v_mfma_f32_16x16x32_bf16 v[68:71], v[182:185], v[214:217], v[68:71]
	v_mfma_f32_16x16x32_bf16 v[120:123], v[178:181], v[194:197], v[120:123]
	v_mfma_f32_16x16x32_bf16 v[112:115], v[186:189], v[194:197], v[112:115]
	v_mfma_f32_16x16x32_bf16 v[104:107], v[178:181], v[202:205], v[104:107]
	v_mfma_f32_16x16x32_bf16 v[96:99], v[186:189], v[202:205], v[96:99]
	v_mfma_f32_16x16x32_bf16 v[88:91], v[178:181], v[210:213], v[88:91]
	v_mfma_f32_16x16x32_bf16 v[80:83], v[186:189], v[210:213], v[80:83]
	v_mfma_f32_16x16x32_bf16 v[72:75], v[178:181], v[238:241], v[72:75]
	v_mfma_f32_16x16x32_bf16 v[68:71], v[186:189], v[238:241], v[68:71]
	s_barrier
	s_add_i32 s14, s22, s28
	v_lshl_add_u64 v[158:159], v[158:159], 0, s[88:89]
	s_mov_b32 m0, s14
	ds_read_b128 v[190:193], v149 offset:49152
	ds_read_b128 v[194:197], v149 offset:50176
	ds_read_b128 v[198:201], v149 offset:51200
	ds_read_b128 v[202:205], v149 offset:52224
	ds_read_b128 v[206:209], v149 offset:53248
	ds_read_b128 v[210:213], v149 offset:54272
	ds_read_b128 v[214:217], v149 offset:55296
	ds_read_b128 v[238:241], v149 offset:56320
	global_load_lds_dwordx4 v[158:159], off
	s_add_i32 m0, s14, 0x2000
	s_add_u32 s12, s12, 0x40080
	v_lshl_add_u64 v[158:159], v[162:163], 0, s[88:89]
	s_addc_u32 s13, s13, 0
	s_add_i32 s14, s48, s28
	global_load_lds_dwordx4 v[158:159], off
	s_mov_b32 m0, s14
	v_lshl_add_u64 v[158:159], s[12:13], 0, v[160:161]
	global_load_lds_dwordx4 v[158:159], off
	s_add_i32 m0, s14, 0x2000
	v_lshl_add_u64 v[158:159], s[12:13], 0, v[128:129]
	global_load_lds_dwordx4 v[158:159], off
	s_mov_b32 m0, s35
	v_lshl_add_u64 v[158:159], v[164:165], 0, s[88:89]
	global_load_lds_dwordx4 v[158:159], off
	s_mov_b32 m0, s90
	v_lshl_add_u64 v[158:159], v[166:167], 0, s[88:89]
	global_load_lds_dwordx4 v[158:159], off
	s_waitcnt vmcnt(8)
	s_waitcnt lgkmcnt(0)
	s_barrier
	v_mfma_f32_16x16x32_bf16 v[60:63], v[138:141], v[190:193], v[60:63]
	v_mfma_f32_16x16x32_bf16 v[48:51], v[150:153], v[190:193], v[48:51]
	v_mfma_f32_16x16x32_bf16 v[44:47], v[138:141], v[198:201], v[44:47]
	v_mfma_f32_16x16x32_bf16 v[32:35], v[150:153], v[198:201], v[32:35]
	v_mfma_f32_16x16x32_bf16 v[28:31], v[138:141], v[206:209], v[28:31]
	v_mfma_f32_16x16x32_bf16 v[16:19], v[150:153], v[206:209], v[16:19]
	v_mfma_f32_16x16x32_bf16 v[12:15], v[138:141], v[214:217], v[12:15]
	v_mfma_f32_16x16x32_bf16 v[0:3], v[150:153], v[214:217], v[0:3]
	v_mfma_f32_16x16x32_bf16 v[60:63], v[142:145], v[194:197], v[60:63]
	v_mfma_f32_16x16x32_bf16 v[48:51], v[154:157], v[194:197], v[48:51]
	v_mfma_f32_16x16x32_bf16 v[44:47], v[142:145], v[202:205], v[44:47]
	v_mfma_f32_16x16x32_bf16 v[32:35], v[154:157], v[202:205], v[32:35]
	v_mfma_f32_16x16x32_bf16 v[28:31], v[142:145], v[210:213], v[28:31]
	v_mfma_f32_16x16x32_bf16 v[16:19], v[154:157], v[210:213], v[16:19]
	v_mfma_f32_16x16x32_bf16 v[12:15], v[142:145], v[238:241], v[12:15]
	v_mfma_f32_16x16x32_bf16 v[0:3], v[154:157], v[238:241], v[0:3]
	v_mfma_f32_16x16x32_bf16 v[56:59], v[174:177], v[190:193], v[56:59]
	v_mfma_f32_16x16x32_bf16 v[52:55], v[182:185], v[190:193], v[52:55]
	v_mfma_f32_16x16x32_bf16 v[40:43], v[174:177], v[198:201], v[40:43]
	v_mfma_f32_16x16x32_bf16 v[36:39], v[182:185], v[198:201], v[36:39]
	v_mfma_f32_16x16x32_bf16 v[24:27], v[174:177], v[206:209], v[24:27]
	v_mfma_f32_16x16x32_bf16 v[20:23], v[182:185], v[206:209], v[20:23]
	v_mfma_f32_16x16x32_bf16 v[8:11], v[174:177], v[214:217], v[8:11]
	v_mfma_f32_16x16x32_bf16 v[4:7], v[182:185], v[214:217], v[4:7]
	v_mfma_f32_16x16x32_bf16 v[56:59], v[178:181], v[194:197], v[56:59]
	v_mfma_f32_16x16x32_bf16 v[52:55], v[186:189], v[194:197], v[52:55]
	v_mfma_f32_16x16x32_bf16 v[40:43], v[178:181], v[202:205], v[40:43]
	v_mfma_f32_16x16x32_bf16 v[36:39], v[186:189], v[202:205], v[36:39]
	v_mfma_f32_16x16x32_bf16 v[24:27], v[178:181], v[210:213], v[24:27]
	v_mfma_f32_16x16x32_bf16 v[20:23], v[186:189], v[210:213], v[20:23]
	v_mfma_f32_16x16x32_bf16 v[8:11], v[178:181], v[238:241], v[8:11]
	v_mfma_f32_16x16x32_bf16 v[4:7], v[186:189], v[238:241], v[4:7]
	s_barrier
	s_add_i32 s21, s21, 2
	s_add_u32 s96, s96, 0x100
	s_addc_u32 s97, s97, 0
	s_add_u32 s10, s10, 0x100
	s_addc_u32 s11, s11, 0
	s_cmp_gt_u32 s21, 13
	s_cbranch_scc0 .LBB0_212
	v_lshl_add_u32 v192, s8, 8, v146
	v_lshlrev_b32_e32 v192, 3, v192
	global_load_dwordx2 v[176:177], v192, s[4:5]
	global_load_dwordx2 v[178:179], v192, s[4:5] offset:128
	global_load_dwordx2 v[180:181], v192, s[4:5] offset:256
	global_load_dwordx2 v[182:183], v192, s[4:5] offset:384
	global_load_dwordx2 v[184:185], v192, s[4:5] offset:1024
	global_load_dwordx2 v[186:187], v192, s[4:5] offset:1152
	global_load_dwordx2 v[188:189], v192, s[4:5] offset:1280
	global_load_dwordx2 v[190:191], v192, s[4:5] offset:1408
	s_and_b64 vcc, exec, s[6:7]
	s_cbranch_vccz .LBB0_215
	s_barrier

.LBB0_310:
	s_add_u32 s12, vcc_lo, 0xfffc0080
	s_addc_u32 s13, vcc_hi, -1
	s_add_i32 s22, 0, 0x10000
	s_cmp_eq_u32 s21, 12
	s_cselect_b32 s93, s9, s13
	s_cselect_b32 s92, s20, s12
	s_cselect_b32 s13, s11, s91
	s_cselect_b32 s12, s45, s90
	s_add_i32 s50, 0, 0x14000
	v_add_u32_e32 v154, s22, v143
	v_add_u32_e32 v158, s50, v143
	ds_read_b128 v[138:141], v154
	ds_read_b128 v[146:149], v154 offset:1024
	ds_read_b128 v[150:153], v154 offset:2048
	ds_read_b128 v[154:157], v154 offset:3072
	ds_read_b128 v[174:177], v158
	ds_read_b128 v[178:181], v158 offset:1024
	ds_read_b128 v[182:185], v158 offset:2048
	ds_read_b128 v[186:189], v158 offset:3072
	v_lshl_add_u64 v[158:159], vcc, 0, v[136:137]
	s_add_i32 m0, s29, 0xc000
	ds_read_b128 v[190:193], v145
	ds_read_b128 v[194:197], v145 offset:1024
	ds_read_b128 v[198:201], v145 offset:2048
	ds_read_b128 v[202:205], v145 offset:3072
	ds_read_b128 v[206:209], v145 offset:4096
	ds_read_b128 v[210:213], v145 offset:5120
	ds_read_b128 v[214:217], v145 offset:6144
	ds_read_b128 v[238:241], v145 offset:7168
	global_load_lds_dwordx4 v[158:159], off
	s_add_i32 m0, s29, 0xe000
	v_lshl_add_u64 v[158:159], vcc, 0, v[134:135]
	global_load_lds_dwordx4 v[158:159], off
	s_waitcnt vmcnt(8)
	s_waitcnt lgkmcnt(0)
	s_barrier
	v_mfma_f32_16x16x32_bf16 v[124:127], v[138:141], v[190:193], v[124:127]
	v_mfma_f32_16x16x32_bf16 v[120:123], v[150:153], v[190:193], v[120:123]
	v_mfma_f32_16x16x32_bf16 v[108:111], v[138:141], v[198:201], v[108:111]
	v_mfma_f32_16x16x32_bf16 v[104:107], v[150:153], v[198:201], v[104:107]
	v_mfma_f32_16x16x32_bf16 v[92:95], v[138:141], v[206:209], v[92:95]
	v_mfma_f32_16x16x32_bf16 v[88:91], v[150:153], v[206:209], v[88:91]
	v_mfma_f32_16x16x32_bf16 v[76:79], v[138:141], v[214:217], v[76:79]
	v_mfma_f32_16x16x32_bf16 v[72:75], v[150:153], v[214:217], v[72:75]
	v_mfma_f32_16x16x32_bf16 v[124:127], v[146:149], v[194:197], v[124:127]
	v_mfma_f32_16x16x32_bf16 v[120:123], v[154:157], v[194:197], v[120:123]
	v_mfma_f32_16x16x32_bf16 v[108:111], v[146:149], v[202:205], v[108:111]
	v_mfma_f32_16x16x32_bf16 v[104:107], v[154:157], v[202:205], v[104:107]
	v_mfma_f32_16x16x32_bf16 v[92:95], v[146:149], v[210:213], v[92:95]
	v_mfma_f32_16x16x32_bf16 v[88:91], v[154:157], v[210:213], v[88:91]
	v_mfma_f32_16x16x32_bf16 v[76:79], v[146:149], v[238:241], v[76:79]
	v_mfma_f32_16x16x32_bf16 v[72:75], v[154:157], v[238:241], v[72:75]
	v_mfma_f32_16x16x32_bf16 v[116:119], v[174:177], v[190:193], v[116:119]
	v_mfma_f32_16x16x32_bf16 v[112:115], v[182:185], v[190:193], v[112:115]
	v_mfma_f32_16x16x32_bf16 v[100:103], v[174:177], v[198:201], v[100:103]
	v_mfma_f32_16x16x32_bf16 v[96:99], v[182:185], v[198:201], v[96:99]
	v_mfma_f32_16x16x32_bf16 v[84:87], v[174:177], v[206:209], v[84:87]
	v_mfma_f32_16x16x32_bf16 v[80:83], v[182:185], v[206:209], v[80:83]
	v_mfma_f32_16x16x32_bf16 v[68:71], v[174:177], v[214:217], v[68:71]
	v_mfma_f32_16x16x32_bf16 v[64:67], v[182:185], v[214:217], v[64:67]
	v_mfma_f32_16x16x32_bf16 v[116:119], v[178:181], v[194:197], v[116:119]
	v_mfma_f32_16x16x32_bf16 v[112:115], v[186:189], v[194:197], v[112:115]
	v_mfma_f32_16x16x32_bf16 v[100:103], v[178:181], v[202:205], v[100:103]
	v_mfma_f32_16x16x32_bf16 v[96:99], v[186:189], v[202:205], v[96:99]
	v_mfma_f32_16x16x32_bf16 v[84:87], v[178:181], v[210:213], v[84:87]
	v_mfma_f32_16x16x32_bf16 v[80:83], v[186:189], v[210:213], v[80:83]
	v_mfma_f32_16x16x32_bf16 v[68:71], v[178:181], v[238:241], v[68:71]
	v_mfma_f32_16x16x32_bf16 v[64:67], v[186:189], v[238:241], v[64:67]
	s_barrier
	s_add_i32 s22, s22, s28
	v_lshl_add_u64 v[158:159], s[12:13], 0, v[160:161]
	s_mov_b32 m0, s22
	ds_read_b128 v[190:193], v145 offset:16384
	ds_read_b128 v[194:197], v145 offset:17408
	ds_read_b128 v[198:201], v145 offset:18432
	ds_read_b128 v[202:205], v145 offset:19456
	ds_read_b128 v[206:209], v145 offset:20480
	ds_read_b128 v[210:213], v145 offset:21504
	ds_read_b128 v[214:217], v145 offset:22528
	ds_read_b128 v[238:241], v145 offset:23552
	global_load_lds_dwordx4 v[158:159], off
	s_add_i32 m0, s22, 0x2000
	s_add_u32 s48, s12, 0x40000
	v_lshl_add_u64 v[162:163], s[12:13], 0, v[132:133]
	s_addc_u32 s49, s13, 0
	s_add_i32 s22, s50, s28
	global_load_lds_dwordx4 v[162:163], off
	v_lshl_add_u64 v[164:165], s[48:49], 0, v[160:161]
	s_mov_b32 m0, s22
	v_lshl_add_u64 v[166:167], s[92:93], 0, v[130:131]
	global_load_lds_dwordx4 v[164:165], off
	s_add_i32 m0, s22, 0x2000
	v_lshl_add_u64 v[164:165], s[48:49], 0, v[132:133]
	global_load_lds_dwordx4 v[164:165], off
	s_mov_b32 m0, s29
	v_lshl_add_u64 v[164:165], s[92:93], 0, v[128:129]
	global_load_lds_dwordx4 v[164:165], off
	s_mov_b32 m0, s30
	s_nop 0
	global_load_lds_dwordx4 v[166:167], off
	s_waitcnt vmcnt(8)
	s_waitcnt lgkmcnt(0)
	s_barrier
	v_mfma_f32_16x16x32_bf16 v[60:63], v[138:141], v[190:193], v[60:63]
	v_mfma_f32_16x16x32_bf16 v[56:59], v[150:153], v[190:193], v[56:59]
	v_mfma_f32_16x16x32_bf16 v[44:47], v[138:141], v[198:201], v[44:47]
	v_mfma_f32_16x16x32_bf16 v[40:43], v[150:153], v[198:201], v[40:43]
	v_mfma_f32_16x16x32_bf16 v[28:31], v[138:141], v[206:209], v[28:31]
	v_mfma_f32_16x16x32_bf16 v[24:27], v[150:153], v[206:209], v[24:27]
	v_mfma_f32_16x16x32_bf16 v[12:15], v[138:141], v[214:217], v[12:15]
	v_mfma_f32_16x16x32_bf16 v[8:11], v[150:153], v[214:217], v[8:11]
	v_mfma_f32_16x16x32_bf16 v[60:63], v[146:149], v[194:197], v[60:63]
	v_mfma_f32_16x16x32_bf16 v[56:59], v[154:157], v[194:197], v[56:59]
	v_mfma_f32_16x16x32_bf16 v[44:47], v[146:149], v[202:205], v[44:47]
	v_mfma_f32_16x16x32_bf16 v[40:43], v[154:157], v[202:205], v[40:43]
	v_mfma_f32_16x16x32_bf16 v[28:31], v[146:149], v[210:213], v[28:31]
	v_mfma_f32_16x16x32_bf16 v[24:27], v[154:157], v[210:213], v[24:27]
	v_mfma_f32_16x16x32_bf16 v[12:15], v[146:149], v[238:241], v[12:15]
	v_mfma_f32_16x16x32_bf16 v[8:11], v[154:157], v[238:241], v[8:11]
	v_mfma_f32_16x16x32_bf16 v[52:55], v[174:177], v[190:193], v[52:55]
	v_mfma_f32_16x16x32_bf16 v[48:51], v[182:185], v[190:193], v[48:51]
	v_mfma_f32_16x16x32_bf16 v[36:39], v[174:177], v[198:201], v[36:39]
	v_mfma_f32_16x16x32_bf16 v[32:35], v[182:185], v[198:201], v[32:35]
	v_mfma_f32_16x16x32_bf16 v[20:23], v[174:177], v[206:209], v[20:23]
	v_mfma_f32_16x16x32_bf16 v[16:19], v[182:185], v[206:209], v[16:19]
	v_mfma_f32_16x16x32_bf16 v[4:7], v[174:177], v[214:217], v[4:7]
	v_mfma_f32_16x16x32_bf16 v[0:3], v[182:185], v[214:217], v[0:3]
	v_mfma_f32_16x16x32_bf16 v[52:55], v[178:181], v[194:197], v[52:55]
	v_mfma_f32_16x16x32_bf16 v[48:51], v[186:189], v[194:197], v[48:51]
	v_mfma_f32_16x16x32_bf16 v[36:39], v[178:181], v[202:205], v[36:39]
	v_mfma_f32_16x16x32_bf16 v[32:35], v[186:189], v[202:205], v[32:35]
	v_mfma_f32_16x16x32_bf16 v[20:23], v[178:181], v[210:213], v[20:23]
	v_mfma_f32_16x16x32_bf16 v[16:19], v[186:189], v[210:213], v[16:19]
	v_mfma_f32_16x16x32_bf16 v[4:7], v[178:181], v[238:241], v[4:7]
	v_mfma_f32_16x16x32_bf16 v[0:3], v[186:189], v[238:241], v[0:3]
	s_barrier
	s_add_i32 s22, 0, 0x18000
	s_add_i32 s50, 0, 0x1c000
	v_add_u32_e32 v154, s22, v143
	v_add_u32_e32 v168, s50, v143
	ds_read_b128 v[138:141], v154
	ds_read_b128 v[146:149], v154 offset:1024
	ds_read_b128 v[150:153], v154 offset:2048
	ds_read_b128 v[154:157], v154 offset:3072
	ds_read_b128 v[174:177], v168
	ds_read_b128 v[178:181], v168 offset:1024
	ds_read_b128 v[182:185], v168 offset:2048
	ds_read_b128 v[186:189], v168 offset:3072
	s_add_u32 s48, s92, 0x40000
	s_addc_u32 s49, s93, 0
	s_mov_b32 m0, s31
	v_lshl_add_u64 v[168:169], s[48:49], 0, v[128:129]
	ds_read_b128 v[190:193], v145 offset:32768
	ds_read_b128 v[194:197], v145 offset:33792
	ds_read_b128 v[198:201], v145 offset:34816
	ds_read_b128 v[202:205], v145 offset:35840
	ds_read_b128 v[206:209], v145 offset:36864
	ds_read_b128 v[210:213], v145 offset:37888
	ds_read_b128 v[214:217], v145 offset:38912
	ds_read_b128 v[238:241], v145 offset:39936
	global_load_lds_dwordx4 v[168:169], off
	s_mov_b32 m0, s33
	v_lshl_add_u64 v[168:169], s[48:49], 0, v[130:131]
	global_load_lds_dwordx4 v[168:169], off
	s_waitcnt vmcnt(8)
	s_waitcnt lgkmcnt(0)
	s_barrier
	v_mfma_f32_16x16x32_bf16 v[124:127], v[138:141], v[190:193], v[124:127]
	v_mfma_f32_16x16x32_bf16 v[120:123], v[150:153], v[190:193], v[120:123]
	v_mfma_f32_16x16x32_bf16 v[108:111], v[138:141], v[198:201], v[108:111]
	v_mfma_f32_16x16x32_bf16 v[104:107], v[150:153], v[198:201], v[104:107]
	v_mfma_f32_16x16x32_bf16 v[92:95], v[138:141], v[206:209], v[92:95]
	v_mfma_f32_16x16x32_bf16 v[88:91], v[150:153], v[206:209], v[88:91]
	v_mfma_f32_16x16x32_bf16 v[76:79], v[138:141], v[214:217], v[76:79]
	v_mfma_f32_16x16x32_bf16 v[72:75], v[150:153], v[214:217], v[72:75]
	v_mfma_f32_16x16x32_bf16 v[124:127], v[146:149], v[194:197], v[124:127]
	v_mfma_f32_16x16x32_bf16 v[120:123], v[154:157], v[194:197], v[120:123]
	v_mfma_f32_16x16x32_bf16 v[108:111], v[146:149], v[202:205], v[108:111]
	v_mfma_f32_16x16x32_bf16 v[104:107], v[154:157], v[202:205], v[104:107]
	v_mfma_f32_16x16x32_bf16 v[92:95], v[146:149], v[210:213], v[92:95]
	v_mfma_f32_16x16x32_bf16 v[88:91], v[154:157], v[210:213], v[88:91]
	v_mfma_f32_16x16x32_bf16 v[76:79], v[146:149], v[238:241], v[76:79]
	v_mfma_f32_16x16x32_bf16 v[72:75], v[154:157], v[238:241], v[72:75]
	v_mfma_f32_16x16x32_bf16 v[116:119], v[174:177], v[190:193], v[116:119]
	v_mfma_f32_16x16x32_bf16 v[112:115], v[182:185], v[190:193], v[112:115]
	v_mfma_f32_16x16x32_bf16 v[100:103], v[174:177], v[198:201], v[100:103]
	v_mfma_f32_16x16x32_bf16 v[96:99], v[182:185], v[198:201], v[96:99]
	v_mfma_f32_16x16x32_bf16 v[84:87], v[174:177], v[206:209], v[84:87]
	v_mfma_f32_16x16x32_bf16 v[80:83], v[182:185], v[206:209], v[80:83]
	v_mfma_f32_16x16x32_bf16 v[68:71], v[174:177], v[214:217], v[68:71]
	v_mfma_f32_16x16x32_bf16 v[64:67], v[182:185], v[214:217], v[64:67]
	v_mfma_f32_16x16x32_bf16 v[116:119], v[178:181], v[194:197], v[116:119]
	v_mfma_f32_16x16x32_bf16 v[112:115], v[186:189], v[194:197], v[112:115]
	v_mfma_f32_16x16x32_bf16 v[100:103], v[178:181], v[202:205], v[100:103]
	v_mfma_f32_16x16x32_bf16 v[96:99], v[186:189], v[202:205], v[96:99]
	v_mfma_f32_16x16x32_bf16 v[84:87], v[178:181], v[210:213], v[84:87]
	v_mfma_f32_16x16x32_bf16 v[80:83], v[186:189], v[210:213], v[80:83]
	v_mfma_f32_16x16x32_bf16 v[68:71], v[178:181], v[238:241], v[68:71]
	v_mfma_f32_16x16x32_bf16 v[64:67], v[186:189], v[238:241], v[64:67]
	s_barrier
	s_add_i32 s22, s22, s28
	v_lshl_add_u64 v[158:159], v[158:159], 0, s[88:89]
	s_mov_b32 m0, s22
	ds_read_b128 v[190:193], v145 offset:49152
	ds_read_b128 v[194:197], v145 offset:50176
	ds_read_b128 v[198:201], v145 offset:51200
	ds_read_b128 v[202:205], v145 offset:52224
	ds_read_b128 v[206:209], v145 offset:53248
	ds_read_b128 v[210:213], v145 offset:54272
	ds_read_b128 v[214:217], v145 offset:55296
	ds_read_b128 v[238:241], v145 offset:56320
	global_load_lds_dwordx4 v[158:159], off
	s_add_i32 m0, s22, 0x2000
	s_add_u32 s12, s12, 0x40080
	v_lshl_add_u64 v[158:159], v[162:163], 0, s[88:89]
	s_addc_u32 s13, s13, 0
	s_add_i32 s22, s50, s28
	global_load_lds_dwordx4 v[158:159], off
	s_mov_b32 m0, s22
	v_lshl_add_u64 v[158:159], s[12:13], 0, v[160:161]
	global_load_lds_dwordx4 v[158:159], off
	s_add_i32 m0, s22, 0x2000
	v_lshl_add_u64 v[158:159], s[12:13], 0, v[132:133]
	global_load_lds_dwordx4 v[158:159], off
	s_mov_b32 m0, s34
	v_lshl_add_u64 v[158:159], v[164:165], 0, s[88:89]
	global_load_lds_dwordx4 v[158:159], off
	s_mov_b32 m0, s35
	v_lshl_add_u64 v[158:159], v[166:167], 0, s[88:89]
	global_load_lds_dwordx4 v[158:159], off
	s_waitcnt vmcnt(8)
	s_waitcnt lgkmcnt(0)
	s_barrier
	v_mfma_f32_16x16x32_bf16 v[60:63], v[138:141], v[190:193], v[60:63]
	v_mfma_f32_16x16x32_bf16 v[56:59], v[150:153], v[190:193], v[56:59]
	v_mfma_f32_16x16x32_bf16 v[44:47], v[138:141], v[198:201], v[44:47]
	v_mfma_f32_16x16x32_bf16 v[40:43], v[150:153], v[198:201], v[40:43]
	v_mfma_f32_16x16x32_bf16 v[28:31], v[138:141], v[206:209], v[28:31]
	v_mfma_f32_16x16x32_bf16 v[24:27], v[150:153], v[206:209], v[24:27]
	v_mfma_f32_16x16x32_bf16 v[12:15], v[138:141], v[214:217], v[12:15]
	v_mfma_f32_16x16x32_bf16 v[8:11], v[150:153], v[214:217], v[8:11]
	v_mfma_f32_16x16x32_bf16 v[60:63], v[146:149], v[194:197], v[60:63]
	v_mfma_f32_16x16x32_bf16 v[56:59], v[154:157], v[194:197], v[56:59]
	v_mfma_f32_16x16x32_bf16 v[44:47], v[146:149], v[202:205], v[44:47]
	v_mfma_f32_16x16x32_bf16 v[40:43], v[154:157], v[202:205], v[40:43]
	v_mfma_f32_16x16x32_bf16 v[28:31], v[146:149], v[210:213], v[28:31]
	v_mfma_f32_16x16x32_bf16 v[24:27], v[154:157], v[210:213], v[24:27]
	v_mfma_f32_16x16x32_bf16 v[12:15], v[146:149], v[238:241], v[12:15]
	v_mfma_f32_16x16x32_bf16 v[8:11], v[154:157], v[238:241], v[8:11]
	v_mfma_f32_16x16x32_bf16 v[52:55], v[174:177], v[190:193], v[52:55]
	v_mfma_f32_16x16x32_bf16 v[48:51], v[182:185], v[190:193], v[48:51]
	v_mfma_f32_16x16x32_bf16 v[36:39], v[174:177], v[198:201], v[36:39]
	v_mfma_f32_16x16x32_bf16 v[32:35], v[182:185], v[198:201], v[32:35]
	v_mfma_f32_16x16x32_bf16 v[20:23], v[174:177], v[206:209], v[20:23]
	v_mfma_f32_16x16x32_bf16 v[16:19], v[182:185], v[206:209], v[16:19]
	v_mfma_f32_16x16x32_bf16 v[4:7], v[174:177], v[214:217], v[4:7]
	v_mfma_f32_16x16x32_bf16 v[0:3], v[182:185], v[214:217], v[0:3]
	v_mfma_f32_16x16x32_bf16 v[52:55], v[178:181], v[194:197], v[52:55]
	v_mfma_f32_16x16x32_bf16 v[48:51], v[186:189], v[194:197], v[48:51]
	v_mfma_f32_16x16x32_bf16 v[36:39], v[178:181], v[202:205], v[36:39]
	v_mfma_f32_16x16x32_bf16 v[32:35], v[186:189], v[202:205], v[32:35]
	v_mfma_f32_16x16x32_bf16 v[20:23], v[178:181], v[210:213], v[20:23]
	v_mfma_f32_16x16x32_bf16 v[16:19], v[186:189], v[210:213], v[16:19]
	v_mfma_f32_16x16x32_bf16 v[4:7], v[178:181], v[238:241], v[4:7]
	v_mfma_f32_16x16x32_bf16 v[0:3], v[186:189], v[238:241], v[0:3]
	s_barrier
	s_add_i32 s21, s21, 2
	s_add_u32 s90, s90, 0x100
	s_addc_u32 s91, s91, 0
	s_add_u32 vcc_lo, vcc_lo, 0x100
	s_addc_u32 vcc_hi, vcc_hi, 0
	s_cmp_gt_u32 s21, 13
	s_cbranch_scc0 .LBB0_310
	v_lshl_add_u32 v140, s36, 8, v142
	v_lshl_or_b32 v138, s44, 8, v144
	v_lshlrev_b32_e32 v141, 11, v140
	v_lshl_add_u32 v138, v138, 1, v141
	v_lshlrev_b32_e32 v139, 3, v140
	s_mov_b64 s[12:13], s[2:3]
	global_load_dwordx4 v[146:149], v138, s[12:13]
	global_load_dwordx4 v[150:153], v138, s[12:13] offset:256
	s_add_u32 s12, s12, 0x8000
	s_addc_u32 s13, s13, 0
	global_load_dwordx4 v[154:157], v138, s[12:13]
	global_load_dwordx4 v[162:165], v138, s[12:13] offset:256
	s_add_u32 s12, s12, 0x8000
	s_addc_u32 s13, s13, 0
	global_load_dwordx4 v[166:169], v138, s[12:13]
	global_load_dwordx4 v[174:177], v138, s[12:13] offset:256
	s_add_u32 s12, s12, 0x8000
	s_addc_u32 s13, s13, 0
	global_load_dwordx4 v[178:181], v138, s[12:13]
	global_load_dwordx4 v[182:185], v138, s[12:13] offset:256
	s_add_u32 s12, s12, 0x28000
	s_addc_u32 s13, s13, 0
	global_load_dwordx4 v[186:189], v138, s[12:13]
	global_load_dwordx4 v[190:193], v138, s[12:13] offset:256
	s_add_u32 s12, s12, 0x8000
	s_addc_u32 s13, s13, 0
	global_load_dwordx4 v[194:197], v138, s[12:13]
	global_load_dwordx4 v[198:201], v138, s[12:13] offset:256
	s_add_u32 s12, s12, 0x8000
	s_addc_u32 s13, s13, 0
	global_load_dwordx4 v[202:205], v138, s[12:13]
	global_load_dwordx4 v[206:209], v138, s[12:13] offset:256
	s_add_u32 s12, s12, 0x8000
	s_addc_u32 s13, s13, 0
	global_load_dwordx4 v[210:213], v138, s[12:13]
	global_load_dwordx4 v[214:217], v138, s[12:13] offset:256
	s_and_b64 vcc, exec, s[6:7]
	s_cbranch_vccz .LBB0_313
	s_barrier

.LBB0_399:
	s_add_u32 s8, s0, 0xfffc0080
	s_addc_u32 s9, s1, -1
	s_add_i32 s22, 0, 0x10000
	s_cmp_eq_u32 s21, 12
	s_cselect_b32 s11, s7, s9
	s_cselect_b32 s10, s19, s8
	s_cselect_b32 s9, s20, s91
	s_cselect_b32 s8, s33, s90
	s_add_i32 s48, 0, 0x14000
	v_add_u32_e32 v152, s22, v157
	v_add_u32_e32 v162, s48, v157
	ds_read_b128 v[128:131], v152
	ds_read_b128 v[144:147], v152 offset:1024
	ds_read_b128 v[148:151], v152 offset:2048
	ds_read_b128 v[152:155], v152 offset:3072
	ds_read_b128 v[176:179], v162
	ds_read_b128 v[180:183], v162 offset:1024
	ds_read_b128 v[184:187], v162 offset:2048
	ds_read_b128 v[188:191], v162 offset:3072
	v_lshl_add_u64 v[162:163], s[0:1], 0, v[142:143]
	s_add_i32 m0, s27, 0xc000
	ds_read_b128 v[192:195], v159
	ds_read_b128 v[196:199], v159 offset:1024
	ds_read_b128 v[200:203], v159 offset:2048
	ds_read_b128 v[204:207], v159 offset:3072
	ds_read_b128 v[208:211], v159 offset:4096
	ds_read_b128 v[212:215], v159 offset:5120
	ds_read_b128 v[238:241], v159 offset:6144
	ds_read_b128 v[246:249], v159 offset:7168
	global_load_lds_dwordx4 v[162:163], off
	s_add_i32 m0, s27, 0xe000
	v_lshl_add_u64 v[162:163], s[0:1], 0, v[140:141]
	global_load_lds_dwordx4 v[162:163], off
	s_waitcnt vmcnt(8)
	s_waitcnt lgkmcnt(0)
	s_barrier
	v_mfma_f32_16x16x32_bf16 v[124:127], v[128:131], v[192:195], v[124:127]
	v_mfma_f32_16x16x32_bf16 v[116:119], v[148:151], v[192:195], v[116:119]
	v_mfma_f32_16x16x32_bf16 v[108:111], v[128:131], v[200:203], v[108:111]
	v_mfma_f32_16x16x32_bf16 v[100:103], v[148:151], v[200:203], v[100:103]
	v_mfma_f32_16x16x32_bf16 v[92:95], v[128:131], v[208:211], v[92:95]
	v_mfma_f32_16x16x32_bf16 v[84:87], v[148:151], v[208:211], v[84:87]
	v_mfma_f32_16x16x32_bf16 v[76:79], v[128:131], v[238:241], v[76:79]
	v_mfma_f32_16x16x32_bf16 v[68:71], v[148:151], v[238:241], v[68:71]
	v_mfma_f32_16x16x32_bf16 v[124:127], v[144:147], v[196:199], v[124:127]
	v_mfma_f32_16x16x32_bf16 v[116:119], v[152:155], v[196:199], v[116:119]
	v_mfma_f32_16x16x32_bf16 v[108:111], v[144:147], v[204:207], v[108:111]
	v_mfma_f32_16x16x32_bf16 v[100:103], v[152:155], v[204:207], v[100:103]
	v_mfma_f32_16x16x32_bf16 v[92:95], v[144:147], v[212:215], v[92:95]
	v_mfma_f32_16x16x32_bf16 v[84:87], v[152:155], v[212:215], v[84:87]
	v_mfma_f32_16x16x32_bf16 v[76:79], v[144:147], v[246:249], v[76:79]
	v_mfma_f32_16x16x32_bf16 v[68:71], v[152:155], v[246:249], v[68:71]
	v_mfma_f32_16x16x32_bf16 v[120:123], v[176:179], v[192:195], v[120:123]
	v_mfma_f32_16x16x32_bf16 v[112:115], v[184:187], v[192:195], v[112:115]
	v_mfma_f32_16x16x32_bf16 v[104:107], v[176:179], v[200:203], v[104:107]
	v_mfma_f32_16x16x32_bf16 v[96:99], v[184:187], v[200:203], v[96:99]
	v_mfma_f32_16x16x32_bf16 v[88:91], v[176:179], v[208:211], v[88:91]
	v_mfma_f32_16x16x32_bf16 v[80:83], v[184:187], v[208:211], v[80:83]
	v_mfma_f32_16x16x32_bf16 v[72:75], v[176:179], v[238:241], v[72:75]
	v_mfma_f32_16x16x32_bf16 v[64:67], v[184:187], v[238:241], v[64:67]
	v_mfma_f32_16x16x32_bf16 v[120:123], v[180:183], v[196:199], v[120:123]
	v_mfma_f32_16x16x32_bf16 v[112:115], v[188:191], v[196:199], v[112:115]
	v_mfma_f32_16x16x32_bf16 v[104:107], v[180:183], v[204:207], v[104:107]
	v_mfma_f32_16x16x32_bf16 v[96:99], v[188:191], v[204:207], v[96:99]
	v_mfma_f32_16x16x32_bf16 v[88:91], v[180:183], v[212:215], v[88:91]
	v_mfma_f32_16x16x32_bf16 v[80:83], v[188:191], v[212:215], v[80:83]
	v_mfma_f32_16x16x32_bf16 v[72:75], v[180:183], v[246:249], v[72:75]
	v_mfma_f32_16x16x32_bf16 v[64:67], v[188:191], v[246:249], v[64:67]
	s_barrier
	s_add_i32 s22, s22, s25
	v_lshl_add_u64 v[162:163], s[8:9], 0, v[136:137]
	s_mov_b32 m0, s22
	ds_read_b128 v[192:195], v159 offset:16384
	ds_read_b128 v[196:199], v159 offset:17408
	ds_read_b128 v[200:203], v159 offset:18432
	ds_read_b128 v[204:207], v159 offset:19456
	ds_read_b128 v[208:211], v159 offset:20480
	ds_read_b128 v[212:215], v159 offset:21504
	ds_read_b128 v[238:241], v159 offset:22528
	ds_read_b128 v[246:249], v159 offset:23552
	global_load_lds_dwordx4 v[162:163], off
	s_add_i32 m0, s22, 0x2000
	s_add_u32 vcc_lo, s8, 0x40000
	v_lshl_add_u64 v[164:165], s[8:9], 0, v[132:133]
	s_addc_u32 vcc_hi, s9, 0
	s_add_i32 s22, s48, s25
	global_load_lds_dwordx4 v[164:165], off
	v_lshl_add_u64 v[166:167], vcc, 0, v[136:137]
	s_mov_b32 m0, s22
	v_lshl_add_u64 v[168:169], s[10:11], 0, v[134:135]
	global_load_lds_dwordx4 v[166:167], off
	s_add_i32 m0, s22, 0x2000
	v_lshl_add_u64 v[166:167], vcc, 0, v[132:133]
	global_load_lds_dwordx4 v[166:167], off
	s_mov_b32 m0, s27
	v_lshl_add_u64 v[166:167], s[10:11], 0, v[138:139]
	global_load_lds_dwordx4 v[166:167], off
	s_mov_b32 m0, s45
	s_nop 0
	global_load_lds_dwordx4 v[168:169], off
	s_waitcnt vmcnt(8)
	s_waitcnt lgkmcnt(0)
	s_barrier
	v_mfma_f32_16x16x32_bf16 v[60:63], v[128:131], v[192:195], v[60:63]
	v_mfma_f32_16x16x32_bf16 v[52:55], v[148:151], v[192:195], v[52:55]
	v_mfma_f32_16x16x32_bf16 v[44:47], v[128:131], v[200:203], v[44:47]
	v_mfma_f32_16x16x32_bf16 v[36:39], v[148:151], v[200:203], v[36:39]
	v_mfma_f32_16x16x32_bf16 v[28:31], v[128:131], v[208:211], v[28:31]
	v_mfma_f32_16x16x32_bf16 v[20:23], v[148:151], v[208:211], v[20:23]
	v_mfma_f32_16x16x32_bf16 v[12:15], v[128:131], v[238:241], v[12:15]
	v_mfma_f32_16x16x32_bf16 v[4:7], v[148:151], v[238:241], v[4:7]
	v_mfma_f32_16x16x32_bf16 v[60:63], v[144:147], v[196:199], v[60:63]
	v_mfma_f32_16x16x32_bf16 v[52:55], v[152:155], v[196:199], v[52:55]
	v_mfma_f32_16x16x32_bf16 v[44:47], v[144:147], v[204:207], v[44:47]
	v_mfma_f32_16x16x32_bf16 v[36:39], v[152:155], v[204:207], v[36:39]
	v_mfma_f32_16x16x32_bf16 v[28:31], v[144:147], v[212:215], v[28:31]
	v_mfma_f32_16x16x32_bf16 v[20:23], v[152:155], v[212:215], v[20:23]
	v_mfma_f32_16x16x32_bf16 v[12:15], v[144:147], v[246:249], v[12:15]
	v_mfma_f32_16x16x32_bf16 v[4:7], v[152:155], v[246:249], v[4:7]
	v_mfma_f32_16x16x32_bf16 v[56:59], v[176:179], v[192:195], v[56:59]
	v_mfma_f32_16x16x32_bf16 v[48:51], v[184:187], v[192:195], v[48:51]
	v_mfma_f32_16x16x32_bf16 v[40:43], v[176:179], v[200:203], v[40:43]
	v_mfma_f32_16x16x32_bf16 v[32:35], v[184:187], v[200:203], v[32:35]
	v_mfma_f32_16x16x32_bf16 v[24:27], v[176:179], v[208:211], v[24:27]
	v_mfma_f32_16x16x32_bf16 v[16:19], v[184:187], v[208:211], v[16:19]
	v_mfma_f32_16x16x32_bf16 v[8:11], v[176:179], v[238:241], v[8:11]
	v_mfma_f32_16x16x32_bf16 v[0:3], v[184:187], v[238:241], v[0:3]
	v_mfma_f32_16x16x32_bf16 v[56:59], v[180:183], v[196:199], v[56:59]
	v_mfma_f32_16x16x32_bf16 v[48:51], v[188:191], v[196:199], v[48:51]
	v_mfma_f32_16x16x32_bf16 v[40:43], v[180:183], v[204:207], v[40:43]
	v_mfma_f32_16x16x32_bf16 v[32:35], v[188:191], v[204:207], v[32:35]
	v_mfma_f32_16x16x32_bf16 v[24:27], v[180:183], v[212:215], v[24:27]
	v_mfma_f32_16x16x32_bf16 v[16:19], v[188:191], v[212:215], v[16:19]
	v_mfma_f32_16x16x32_bf16 v[8:11], v[180:183], v[246:249], v[8:11]
	v_mfma_f32_16x16x32_bf16 v[0:3], v[188:191], v[246:249], v[0:3]
	s_barrier
	s_add_i32 s22, 0, 0x18000
	s_add_i32 s48, 0, 0x1c000
	v_add_u32_e32 v152, s22, v157
	v_add_u32_e32 v170, s48, v157
	ds_read_b128 v[128:131], v152
	ds_read_b128 v[144:147], v152 offset:1024
	ds_read_b128 v[148:151], v152 offset:2048
	ds_read_b128 v[152:155], v152 offset:3072
	ds_read_b128 v[176:179], v170
	ds_read_b128 v[180:183], v170 offset:1024
	ds_read_b128 v[184:187], v170 offset:2048
	ds_read_b128 v[188:191], v170 offset:3072
	s_add_u32 s10, s10, 0x40000
	s_addc_u32 s11, s11, 0
	s_mov_b32 m0, s28
	v_lshl_add_u64 v[170:171], s[10:11], 0, v[138:139]
	ds_read_b128 v[192:195], v159 offset:32768
	ds_read_b128 v[196:199], v159 offset:33792
	ds_read_b128 v[200:203], v159 offset:34816
	ds_read_b128 v[204:207], v159 offset:35840
	ds_read_b128 v[208:211], v159 offset:36864
	ds_read_b128 v[212:215], v159 offset:37888
	ds_read_b128 v[238:241], v159 offset:38912
	ds_read_b128 v[246:249], v159 offset:39936
	global_load_lds_dwordx4 v[170:171], off
	s_mov_b32 m0, s29
	v_lshl_add_u64 v[170:171], s[10:11], 0, v[134:135]
	global_load_lds_dwordx4 v[170:171], off
	s_waitcnt vmcnt(8)
	s_waitcnt lgkmcnt(0)
	s_barrier
	v_mfma_f32_16x16x32_bf16 v[124:127], v[128:131], v[192:195], v[124:127]
	v_mfma_f32_16x16x32_bf16 v[116:119], v[148:151], v[192:195], v[116:119]
	v_mfma_f32_16x16x32_bf16 v[108:111], v[128:131], v[200:203], v[108:111]
	v_mfma_f32_16x16x32_bf16 v[100:103], v[148:151], v[200:203], v[100:103]
	v_mfma_f32_16x16x32_bf16 v[92:95], v[128:131], v[208:211], v[92:95]
	v_mfma_f32_16x16x32_bf16 v[84:87], v[148:151], v[208:211], v[84:87]
	v_mfma_f32_16x16x32_bf16 v[76:79], v[128:131], v[238:241], v[76:79]
	v_mfma_f32_16x16x32_bf16 v[68:71], v[148:151], v[238:241], v[68:71]
	v_mfma_f32_16x16x32_bf16 v[124:127], v[144:147], v[196:199], v[124:127]
	v_mfma_f32_16x16x32_bf16 v[116:119], v[152:155], v[196:199], v[116:119]
	v_mfma_f32_16x16x32_bf16 v[108:111], v[144:147], v[204:207], v[108:111]
	v_mfma_f32_16x16x32_bf16 v[100:103], v[152:155], v[204:207], v[100:103]
	v_mfma_f32_16x16x32_bf16 v[92:95], v[144:147], v[212:215], v[92:95]
	v_mfma_f32_16x16x32_bf16 v[84:87], v[152:155], v[212:215], v[84:87]
	v_mfma_f32_16x16x32_bf16 v[76:79], v[144:147], v[246:249], v[76:79]
	v_mfma_f32_16x16x32_bf16 v[68:71], v[152:155], v[246:249], v[68:71]
	v_mfma_f32_16x16x32_bf16 v[120:123], v[176:179], v[192:195], v[120:123]
	v_mfma_f32_16x16x32_bf16 v[112:115], v[184:187], v[192:195], v[112:115]
	v_mfma_f32_16x16x32_bf16 v[104:107], v[176:179], v[200:203], v[104:107]
	v_mfma_f32_16x16x32_bf16 v[96:99], v[184:187], v[200:203], v[96:99]
	v_mfma_f32_16x16x32_bf16 v[88:91], v[176:179], v[208:211], v[88:91]
	v_mfma_f32_16x16x32_bf16 v[80:83], v[184:187], v[208:211], v[80:83]
	v_mfma_f32_16x16x32_bf16 v[72:75], v[176:179], v[238:241], v[72:75]
	v_mfma_f32_16x16x32_bf16 v[64:67], v[184:187], v[238:241], v[64:67]
	v_mfma_f32_16x16x32_bf16 v[120:123], v[180:183], v[196:199], v[120:123]
	v_mfma_f32_16x16x32_bf16 v[112:115], v[188:191], v[196:199], v[112:115]
	v_mfma_f32_16x16x32_bf16 v[104:107], v[180:183], v[204:207], v[104:107]
	v_mfma_f32_16x16x32_bf16 v[96:99], v[188:191], v[204:207], v[96:99]
	v_mfma_f32_16x16x32_bf16 v[88:91], v[180:183], v[212:215], v[88:91]
	v_mfma_f32_16x16x32_bf16 v[80:83], v[188:191], v[212:215], v[80:83]
	v_mfma_f32_16x16x32_bf16 v[72:75], v[180:183], v[246:249], v[72:75]
	v_mfma_f32_16x16x32_bf16 v[64:67], v[188:191], v[246:249], v[64:67]
	s_barrier
	s_add_i32 s10, s22, s25
	v_lshl_add_u64 v[162:163], v[162:163], 0, s[88:89]
	s_mov_b32 m0, s10
	ds_read_b128 v[192:195], v159 offset:49152
	ds_read_b128 v[196:199], v159 offset:50176
	ds_read_b128 v[200:203], v159 offset:51200
	ds_read_b128 v[204:207], v159 offset:52224
	ds_read_b128 v[208:211], v159 offset:53248
	ds_read_b128 v[212:215], v159 offset:54272
	ds_read_b128 v[238:241], v159 offset:55296
	ds_read_b128 v[246:249], v159 offset:56320
	global_load_lds_dwordx4 v[162:163], off
	s_add_i32 m0, s10, 0x2000
	s_add_u32 s8, s8, 0x40080
	v_lshl_add_u64 v[162:163], v[164:165], 0, s[88:89]
	s_addc_u32 s9, s9, 0
	s_add_i32 s10, s48, s25
	global_load_lds_dwordx4 v[162:163], off
	s_mov_b32 m0, s10
	v_lshl_add_u64 v[162:163], s[8:9], 0, v[136:137]
	global_load_lds_dwordx4 v[162:163], off
	s_add_i32 m0, s10, 0x2000
	v_lshl_add_u64 v[162:163], s[8:9], 0, v[132:133]
	global_load_lds_dwordx4 v[162:163], off
	s_mov_b32 m0, s30
	v_lshl_add_u64 v[162:163], v[166:167], 0, s[88:89]
	global_load_lds_dwordx4 v[162:163], off
	s_mov_b32 m0, s31
	v_lshl_add_u64 v[162:163], v[168:169], 0, s[88:89]
	global_load_lds_dwordx4 v[162:163], off
	s_waitcnt vmcnt(8)
	s_waitcnt lgkmcnt(0)
	s_barrier
	v_mfma_f32_16x16x32_bf16 v[60:63], v[128:131], v[192:195], v[60:63]
	v_mfma_f32_16x16x32_bf16 v[52:55], v[148:151], v[192:195], v[52:55]
	v_mfma_f32_16x16x32_bf16 v[44:47], v[128:131], v[200:203], v[44:47]
	v_mfma_f32_16x16x32_bf16 v[36:39], v[148:151], v[200:203], v[36:39]
	v_mfma_f32_16x16x32_bf16 v[28:31], v[128:131], v[208:211], v[28:31]
	v_mfma_f32_16x16x32_bf16 v[20:23], v[148:151], v[208:211], v[20:23]
	v_mfma_f32_16x16x32_bf16 v[12:15], v[128:131], v[238:241], v[12:15]
	v_mfma_f32_16x16x32_bf16 v[4:7], v[148:151], v[238:241], v[4:7]
	v_mfma_f32_16x16x32_bf16 v[60:63], v[144:147], v[196:199], v[60:63]
	v_mfma_f32_16x16x32_bf16 v[52:55], v[152:155], v[196:199], v[52:55]
	v_mfma_f32_16x16x32_bf16 v[44:47], v[144:147], v[204:207], v[44:47]
	v_mfma_f32_16x16x32_bf16 v[36:39], v[152:155], v[204:207], v[36:39]
	v_mfma_f32_16x16x32_bf16 v[28:31], v[144:147], v[212:215], v[28:31]
	v_mfma_f32_16x16x32_bf16 v[20:23], v[152:155], v[212:215], v[20:23]
	v_mfma_f32_16x16x32_bf16 v[12:15], v[144:147], v[246:249], v[12:15]
	v_mfma_f32_16x16x32_bf16 v[4:7], v[152:155], v[246:249], v[4:7]
	v_mfma_f32_16x16x32_bf16 v[56:59], v[176:179], v[192:195], v[56:59]
	v_mfma_f32_16x16x32_bf16 v[48:51], v[184:187], v[192:195], v[48:51]
	v_mfma_f32_16x16x32_bf16 v[40:43], v[176:179], v[200:203], v[40:43]
	v_mfma_f32_16x16x32_bf16 v[32:35], v[184:187], v[200:203], v[32:35]
	v_mfma_f32_16x16x32_bf16 v[24:27], v[176:179], v[208:211], v[24:27]
	v_mfma_f32_16x16x32_bf16 v[16:19], v[184:187], v[208:211], v[16:19]
	v_mfma_f32_16x16x32_bf16 v[8:11], v[176:179], v[238:241], v[8:11]
	v_mfma_f32_16x16x32_bf16 v[0:3], v[184:187], v[238:241], v[0:3]
	v_mfma_f32_16x16x32_bf16 v[56:59], v[180:183], v[196:199], v[56:59]
	v_mfma_f32_16x16x32_bf16 v[48:51], v[188:191], v[196:199], v[48:51]
	v_mfma_f32_16x16x32_bf16 v[40:43], v[180:183], v[204:207], v[40:43]
	v_mfma_f32_16x16x32_bf16 v[32:35], v[188:191], v[204:207], v[32:35]
	v_mfma_f32_16x16x32_bf16 v[24:27], v[180:183], v[212:215], v[24:27]
	v_mfma_f32_16x16x32_bf16 v[16:19], v[188:191], v[212:215], v[16:19]
	v_mfma_f32_16x16x32_bf16 v[8:11], v[180:183], v[246:249], v[8:11]
	v_mfma_f32_16x16x32_bf16 v[0:3], v[188:191], v[246:249], v[0:3]
	s_barrier
	s_add_i32 s21, s21, 2
	s_add_u32 s90, s90, 0x100
	s_addc_u32 s91, s91, 0
	s_add_u32 s0, s0, 0x100
	s_addc_u32 s1, s1, 0
	s_cmp_gt_u32 s21, 13
	s_cbranch_scc0 .LBB0_399
	v_lshl_add_u32 v212, s44, 8, v156
	v_lshlrev_b32_e32 v212, 3, v212
	global_load_dwordx2 v[196:197], v212, s[36:37]
	global_load_dwordx2 v[198:199], v212, s[36:37] offset:128
	global_load_dwordx2 v[200:201], v212, s[36:37] offset:256
	global_load_dwordx2 v[202:203], v212, s[36:37] offset:384
	global_load_dwordx2 v[204:205], v212, s[36:37] offset:1024
	global_load_dwordx2 v[206:207], v212, s[36:37] offset:1152
	global_load_dwordx2 v[208:209], v212, s[36:37] offset:1280
	global_load_dwordx2 v[210:211], v212, s[36:37] offset:1408
	s_and_b64 vcc, exec, s[92:93]
	s_cbranch_vccnz .LBB0_404
	s_cmp_gt_i32 s35, 3
	s_mov_b64 s[0:1], -1
	s_cbranch_scc1 .LBB0_405

.LBB0_439:
	s_add_u32 s10, s8, 0x100
	s_addc_u32 s11, s9, 0
	s_add_i32 s48, 0, 0x10000
	s_cmp_eq_u32 s22, 40
	s_cselect_b32 s15, s1, s11
	s_cselect_b32 s14, s0, s10
	s_cselect_b32 s13, s45, s92
	s_cselect_b32 s12, s44, s21
	s_add_i32 s49, 0, 0x14000
	v_add_u32_e32 v154, s48, v143
	v_add_u32_e32 v158, s49, v143
	ds_read_b128 v[138:141], v154
	ds_read_b128 v[146:149], v154 offset:1024
	ds_read_b128 v[150:153], v154 offset:2048
	ds_read_b128 v[154:157], v154 offset:3072
	ds_read_b128 v[174:177], v158
	ds_read_b128 v[178:181], v158 offset:1024
	ds_read_b128 v[182:185], v158 offset:2048
	ds_read_b128 v[186:189], v158 offset:3072
	v_lshl_add_u64 v[158:159], s[8:9], 0, v[136:137]
	s_add_i32 m0, s29, 0xc000
	ds_read_b128 v[190:193], v145
	ds_read_b128 v[194:197], v145 offset:1024
	ds_read_b128 v[198:201], v145 offset:2048
	ds_read_b128 v[202:205], v145 offset:3072
	ds_read_b128 v[206:209], v145 offset:4096
	ds_read_b128 v[210:213], v145 offset:5120
	ds_read_b128 v[214:217], v145 offset:6144
	ds_read_b128 v[238:241], v145 offset:7168
	global_load_lds_dwordx4 v[158:159], off
	s_add_i32 m0, s29, 0xe000
	v_lshl_add_u64 v[158:159], s[8:9], 0, v[134:135]
	global_load_lds_dwordx4 v[158:159], off
	s_waitcnt vmcnt(8)
	s_waitcnt lgkmcnt(0)
	s_barrier
	v_mfma_f32_16x16x32_bf16 v[124:127], v[138:141], v[190:193], v[124:127]
	v_mfma_f32_16x16x32_bf16 v[120:123], v[150:153], v[190:193], v[120:123]
	v_mfma_f32_16x16x32_bf16 v[108:111], v[138:141], v[198:201], v[108:111]
	v_mfma_f32_16x16x32_bf16 v[104:107], v[150:153], v[198:201], v[104:107]
	v_mfma_f32_16x16x32_bf16 v[92:95], v[138:141], v[206:209], v[92:95]
	v_mfma_f32_16x16x32_bf16 v[88:91], v[150:153], v[206:209], v[88:91]
	v_mfma_f32_16x16x32_bf16 v[76:79], v[138:141], v[214:217], v[76:79]
	v_mfma_f32_16x16x32_bf16 v[72:75], v[150:153], v[214:217], v[72:75]
	v_mfma_f32_16x16x32_bf16 v[124:127], v[146:149], v[194:197], v[124:127]
	v_mfma_f32_16x16x32_bf16 v[120:123], v[154:157], v[194:197], v[120:123]
	v_mfma_f32_16x16x32_bf16 v[108:111], v[146:149], v[202:205], v[108:111]
	v_mfma_f32_16x16x32_bf16 v[104:107], v[154:157], v[202:205], v[104:107]
	v_mfma_f32_16x16x32_bf16 v[92:95], v[146:149], v[210:213], v[92:95]
	v_mfma_f32_16x16x32_bf16 v[88:91], v[154:157], v[210:213], v[88:91]
	v_mfma_f32_16x16x32_bf16 v[76:79], v[146:149], v[238:241], v[76:79]
	v_mfma_f32_16x16x32_bf16 v[72:75], v[154:157], v[238:241], v[72:75]
	v_mfma_f32_16x16x32_bf16 v[116:119], v[174:177], v[190:193], v[116:119]
	v_mfma_f32_16x16x32_bf16 v[112:115], v[182:185], v[190:193], v[112:115]
	v_mfma_f32_16x16x32_bf16 v[100:103], v[174:177], v[198:201], v[100:103]
	v_mfma_f32_16x16x32_bf16 v[96:99], v[182:185], v[198:201], v[96:99]
	v_mfma_f32_16x16x32_bf16 v[84:87], v[174:177], v[206:209], v[84:87]
	v_mfma_f32_16x16x32_bf16 v[80:83], v[182:185], v[206:209], v[80:83]
	v_mfma_f32_16x16x32_bf16 v[68:71], v[174:177], v[214:217], v[68:71]
	v_mfma_f32_16x16x32_bf16 v[64:67], v[182:185], v[214:217], v[64:67]
	v_mfma_f32_16x16x32_bf16 v[116:119], v[178:181], v[194:197], v[116:119]
	v_mfma_f32_16x16x32_bf16 v[112:115], v[186:189], v[194:197], v[112:115]
	v_mfma_f32_16x16x32_bf16 v[100:103], v[178:181], v[202:205], v[100:103]
	v_mfma_f32_16x16x32_bf16 v[96:99], v[186:189], v[202:205], v[96:99]
	v_mfma_f32_16x16x32_bf16 v[84:87], v[178:181], v[210:213], v[84:87]
	v_mfma_f32_16x16x32_bf16 v[80:83], v[186:189], v[210:213], v[80:83]
	v_mfma_f32_16x16x32_bf16 v[68:71], v[178:181], v[238:241], v[68:71]
	v_mfma_f32_16x16x32_bf16 v[64:67], v[186:189], v[238:241], v[64:67]
	s_barrier
	s_add_i32 s8, s48, s28
	v_lshl_add_u64 v[158:159], s[12:13], 0, v[160:161]
	s_mov_b32 m0, s8
	ds_read_b128 v[190:193], v145 offset:16384
	ds_read_b128 v[194:197], v145 offset:17408
	ds_read_b128 v[198:201], v145 offset:18432
	ds_read_b128 v[202:205], v145 offset:19456
	ds_read_b128 v[206:209], v145 offset:20480
	ds_read_b128 v[210:213], v145 offset:21504
	ds_read_b128 v[214:217], v145 offset:22528
	ds_read_b128 v[238:241], v145 offset:23552
	global_load_lds_dwordx4 v[158:159], off
	s_add_i32 m0, s8, 0x2000
	s_add_u32 s8, s12, 0xb0000
	v_lshl_add_u64 v[162:163], s[12:13], 0, v[132:133]
	s_addc_u32 s9, s13, 0
	s_add_i32 s48, s49, s28
	global_load_lds_dwordx4 v[162:163], off
	v_lshl_add_u64 v[164:165], s[8:9], 0, v[160:161]
	s_mov_b32 m0, s48
	v_lshl_add_u64 v[166:167], s[14:15], 0, v[130:131]
	global_load_lds_dwordx4 v[164:165], off
	s_add_i32 m0, s48, 0x2000
	v_lshl_add_u64 v[164:165], s[8:9], 0, v[132:133]
	global_load_lds_dwordx4 v[164:165], off
	s_mov_b32 m0, s29
	v_lshl_add_u64 v[164:165], s[14:15], 0, v[128:129]
	global_load_lds_dwordx4 v[164:165], off
	s_mov_b32 m0, s30
	s_nop 0
	global_load_lds_dwordx4 v[166:167], off
	s_waitcnt vmcnt(8)
	s_waitcnt lgkmcnt(0)
	s_barrier
	v_mfma_f32_16x16x32_bf16 v[60:63], v[138:141], v[190:193], v[60:63]
	v_mfma_f32_16x16x32_bf16 v[56:59], v[150:153], v[190:193], v[56:59]
	v_mfma_f32_16x16x32_bf16 v[44:47], v[138:141], v[198:201], v[44:47]
	v_mfma_f32_16x16x32_bf16 v[40:43], v[150:153], v[198:201], v[40:43]
	v_mfma_f32_16x16x32_bf16 v[28:31], v[138:141], v[206:209], v[28:31]
	v_mfma_f32_16x16x32_bf16 v[24:27], v[150:153], v[206:209], v[24:27]
	v_mfma_f32_16x16x32_bf16 v[12:15], v[138:141], v[214:217], v[12:15]
	v_mfma_f32_16x16x32_bf16 v[8:11], v[150:153], v[214:217], v[8:11]
	v_mfma_f32_16x16x32_bf16 v[60:63], v[146:149], v[194:197], v[60:63]
	v_mfma_f32_16x16x32_bf16 v[56:59], v[154:157], v[194:197], v[56:59]
	v_mfma_f32_16x16x32_bf16 v[44:47], v[146:149], v[202:205], v[44:47]
	v_mfma_f32_16x16x32_bf16 v[40:43], v[154:157], v[202:205], v[40:43]
	v_mfma_f32_16x16x32_bf16 v[28:31], v[146:149], v[210:213], v[28:31]
	v_mfma_f32_16x16x32_bf16 v[24:27], v[154:157], v[210:213], v[24:27]
	v_mfma_f32_16x16x32_bf16 v[12:15], v[146:149], v[238:241], v[12:15]
	v_mfma_f32_16x16x32_bf16 v[8:11], v[154:157], v[238:241], v[8:11]
	v_mfma_f32_16x16x32_bf16 v[52:55], v[174:177], v[190:193], v[52:55]
	v_mfma_f32_16x16x32_bf16 v[48:51], v[182:185], v[190:193], v[48:51]
	v_mfma_f32_16x16x32_bf16 v[36:39], v[174:177], v[198:201], v[36:39]
	v_mfma_f32_16x16x32_bf16 v[32:35], v[182:185], v[198:201], v[32:35]
	v_mfma_f32_16x16x32_bf16 v[20:23], v[174:177], v[206:209], v[20:23]
	v_mfma_f32_16x16x32_bf16 v[16:19], v[182:185], v[206:209], v[16:19]
	v_mfma_f32_16x16x32_bf16 v[4:7], v[174:177], v[214:217], v[4:7]
	v_mfma_f32_16x16x32_bf16 v[0:3], v[182:185], v[214:217], v[0:3]
	v_mfma_f32_16x16x32_bf16 v[52:55], v[178:181], v[194:197], v[52:55]
	v_mfma_f32_16x16x32_bf16 v[48:51], v[186:189], v[194:197], v[48:51]
	v_mfma_f32_16x16x32_bf16 v[36:39], v[178:181], v[202:205], v[36:39]
	v_mfma_f32_16x16x32_bf16 v[32:35], v[186:189], v[202:205], v[32:35]
	v_mfma_f32_16x16x32_bf16 v[20:23], v[178:181], v[210:213], v[20:23]
	v_mfma_f32_16x16x32_bf16 v[16:19], v[186:189], v[210:213], v[16:19]
	v_mfma_f32_16x16x32_bf16 v[4:7], v[178:181], v[238:241], v[4:7]
	v_mfma_f32_16x16x32_bf16 v[0:3], v[186:189], v[238:241], v[0:3]
	s_barrier
	s_add_i32 s48, 0, 0x18000
	s_add_i32 s49, 0, 0x1c000
	v_add_u32_e32 v154, s48, v143
	v_add_u32_e32 v168, s49, v143
	ds_read_b128 v[138:141], v154
	ds_read_b128 v[146:149], v154 offset:1024
	ds_read_b128 v[150:153], v154 offset:2048
	ds_read_b128 v[154:157], v154 offset:3072
	ds_read_b128 v[174:177], v168
	ds_read_b128 v[178:181], v168 offset:1024
	ds_read_b128 v[182:185], v168 offset:2048
	ds_read_b128 v[186:189], v168 offset:3072
	s_add_u32 s8, s14, 0xb0000
	s_addc_u32 s9, s15, 0
	s_mov_b32 m0, s31
	v_lshl_add_u64 v[168:169], s[8:9], 0, v[128:129]
	ds_read_b128 v[190:193], v145 offset:32768
	ds_read_b128 v[194:197], v145 offset:33792
	ds_read_b128 v[198:201], v145 offset:34816
	ds_read_b128 v[202:205], v145 offset:35840
	ds_read_b128 v[206:209], v145 offset:36864
	ds_read_b128 v[210:213], v145 offset:37888
	ds_read_b128 v[214:217], v145 offset:38912
	ds_read_b128 v[238:241], v145 offset:39936
	global_load_lds_dwordx4 v[168:169], off
	s_mov_b32 m0, s33
	v_lshl_add_u64 v[168:169], s[8:9], 0, v[130:131]
	global_load_lds_dwordx4 v[168:169], off
	s_waitcnt vmcnt(8)
	s_waitcnt lgkmcnt(0)
	s_barrier
	v_mfma_f32_16x16x32_bf16 v[124:127], v[138:141], v[190:193], v[124:127]
	v_mfma_f32_16x16x32_bf16 v[120:123], v[150:153], v[190:193], v[120:123]
	v_mfma_f32_16x16x32_bf16 v[108:111], v[138:141], v[198:201], v[108:111]
	v_mfma_f32_16x16x32_bf16 v[104:107], v[150:153], v[198:201], v[104:107]
	v_mfma_f32_16x16x32_bf16 v[92:95], v[138:141], v[206:209], v[92:95]
	v_mfma_f32_16x16x32_bf16 v[88:91], v[150:153], v[206:209], v[88:91]
	v_mfma_f32_16x16x32_bf16 v[76:79], v[138:141], v[214:217], v[76:79]
	v_mfma_f32_16x16x32_bf16 v[72:75], v[150:153], v[214:217], v[72:75]
	v_mfma_f32_16x16x32_bf16 v[124:127], v[146:149], v[194:197], v[124:127]
	v_mfma_f32_16x16x32_bf16 v[120:123], v[154:157], v[194:197], v[120:123]
	v_mfma_f32_16x16x32_bf16 v[108:111], v[146:149], v[202:205], v[108:111]
	v_mfma_f32_16x16x32_bf16 v[104:107], v[154:157], v[202:205], v[104:107]
	v_mfma_f32_16x16x32_bf16 v[92:95], v[146:149], v[210:213], v[92:95]
	v_mfma_f32_16x16x32_bf16 v[88:91], v[154:157], v[210:213], v[88:91]
	v_mfma_f32_16x16x32_bf16 v[76:79], v[146:149], v[238:241], v[76:79]
	v_mfma_f32_16x16x32_bf16 v[72:75], v[154:157], v[238:241], v[72:75]
	v_mfma_f32_16x16x32_bf16 v[116:119], v[174:177], v[190:193], v[116:119]
	v_mfma_f32_16x16x32_bf16 v[112:115], v[182:185], v[190:193], v[112:115]
	v_mfma_f32_16x16x32_bf16 v[100:103], v[174:177], v[198:201], v[100:103]
	v_mfma_f32_16x16x32_bf16 v[96:99], v[182:185], v[198:201], v[96:99]
	v_mfma_f32_16x16x32_bf16 v[84:87], v[174:177], v[206:209], v[84:87]
	v_mfma_f32_16x16x32_bf16 v[80:83], v[182:185], v[206:209], v[80:83]
	v_mfma_f32_16x16x32_bf16 v[68:71], v[174:177], v[214:217], v[68:71]
	v_mfma_f32_16x16x32_bf16 v[64:67], v[182:185], v[214:217], v[64:67]
	v_mfma_f32_16x16x32_bf16 v[116:119], v[178:181], v[194:197], v[116:119]
	v_mfma_f32_16x16x32_bf16 v[112:115], v[186:189], v[194:197], v[112:115]
	v_mfma_f32_16x16x32_bf16 v[100:103], v[178:181], v[202:205], v[100:103]
	v_mfma_f32_16x16x32_bf16 v[96:99], v[186:189], v[202:205], v[96:99]
	v_mfma_f32_16x16x32_bf16 v[84:87], v[178:181], v[210:213], v[84:87]
	v_mfma_f32_16x16x32_bf16 v[80:83], v[186:189], v[210:213], v[80:83]
	v_mfma_f32_16x16x32_bf16 v[68:71], v[178:181], v[238:241], v[68:71]
	v_mfma_f32_16x16x32_bf16 v[64:67], v[186:189], v[238:241], v[64:67]
	s_barrier
	s_add_i32 s8, s48, s28
	v_lshl_add_u64 v[158:159], v[158:159], 0, s[88:89]
	s_mov_b32 m0, s8
	ds_read_b128 v[190:193], v145 offset:49152
	ds_read_b128 v[194:197], v145 offset:50176
	ds_read_b128 v[198:201], v145 offset:51200
	ds_read_b128 v[202:205], v145 offset:52224
	ds_read_b128 v[206:209], v145 offset:53248
	ds_read_b128 v[210:213], v145 offset:54272
	ds_read_b128 v[214:217], v145 offset:55296
	ds_read_b128 v[238:241], v145 offset:56320
	global_load_lds_dwordx4 v[158:159], off
	s_add_i32 m0, s8, 0x2000
	s_add_u32 s8, s12, 0xb0080
	v_lshl_add_u64 v[158:159], v[162:163], 0, s[88:89]
	s_addc_u32 s9, s13, 0
	s_add_i32 s12, s49, s28
	global_load_lds_dwordx4 v[158:159], off
	s_mov_b32 m0, s12
	v_lshl_add_u64 v[158:159], s[8:9], 0, v[160:161]
	global_load_lds_dwordx4 v[158:159], off
	s_add_i32 m0, s12, 0x2000
	v_lshl_add_u64 v[158:159], s[8:9], 0, v[132:133]
	global_load_lds_dwordx4 v[158:159], off
	s_mov_b32 m0, s34
	v_lshl_add_u64 v[158:159], v[164:165], 0, s[88:89]
	global_load_lds_dwordx4 v[158:159], off
	s_mov_b32 m0, s35
	v_lshl_add_u64 v[158:159], v[166:167], 0, s[88:89]
	global_load_lds_dwordx4 v[158:159], off
	s_waitcnt vmcnt(8)
	s_waitcnt lgkmcnt(0)
	s_barrier
	v_mfma_f32_16x16x32_bf16 v[60:63], v[138:141], v[190:193], v[60:63]
	v_mfma_f32_16x16x32_bf16 v[56:59], v[150:153], v[190:193], v[56:59]
	v_mfma_f32_16x16x32_bf16 v[44:47], v[138:141], v[198:201], v[44:47]
	v_mfma_f32_16x16x32_bf16 v[40:43], v[150:153], v[198:201], v[40:43]
	v_mfma_f32_16x16x32_bf16 v[28:31], v[138:141], v[206:209], v[28:31]
	v_mfma_f32_16x16x32_bf16 v[24:27], v[150:153], v[206:209], v[24:27]
	v_mfma_f32_16x16x32_bf16 v[12:15], v[138:141], v[214:217], v[12:15]
	v_mfma_f32_16x16x32_bf16 v[8:11], v[150:153], v[214:217], v[8:11]
	v_mfma_f32_16x16x32_bf16 v[60:63], v[146:149], v[194:197], v[60:63]
	v_mfma_f32_16x16x32_bf16 v[56:59], v[154:157], v[194:197], v[56:59]
	v_mfma_f32_16x16x32_bf16 v[44:47], v[146:149], v[202:205], v[44:47]
	v_mfma_f32_16x16x32_bf16 v[40:43], v[154:157], v[202:205], v[40:43]
	v_mfma_f32_16x16x32_bf16 v[28:31], v[146:149], v[210:213], v[28:31]
	v_mfma_f32_16x16x32_bf16 v[24:27], v[154:157], v[210:213], v[24:27]
	v_mfma_f32_16x16x32_bf16 v[12:15], v[146:149], v[238:241], v[12:15]
	v_mfma_f32_16x16x32_bf16 v[8:11], v[154:157], v[238:241], v[8:11]
	v_mfma_f32_16x16x32_bf16 v[52:55], v[174:177], v[190:193], v[52:55]
	v_mfma_f32_16x16x32_bf16 v[48:51], v[182:185], v[190:193], v[48:51]
	v_mfma_f32_16x16x32_bf16 v[36:39], v[174:177], v[198:201], v[36:39]
	v_mfma_f32_16x16x32_bf16 v[32:35], v[182:185], v[198:201], v[32:35]
	v_mfma_f32_16x16x32_bf16 v[20:23], v[174:177], v[206:209], v[20:23]
	v_mfma_f32_16x16x32_bf16 v[16:19], v[182:185], v[206:209], v[16:19]
	v_mfma_f32_16x16x32_bf16 v[4:7], v[174:177], v[214:217], v[4:7]
	v_mfma_f32_16x16x32_bf16 v[0:3], v[182:185], v[214:217], v[0:3]
	v_mfma_f32_16x16x32_bf16 v[52:55], v[178:181], v[194:197], v[52:55]
	v_mfma_f32_16x16x32_bf16 v[48:51], v[186:189], v[194:197], v[48:51]
	v_mfma_f32_16x16x32_bf16 v[36:39], v[178:181], v[202:205], v[36:39]
	v_mfma_f32_16x16x32_bf16 v[32:35], v[186:189], v[202:205], v[32:35]
	v_mfma_f32_16x16x32_bf16 v[20:23], v[178:181], v[210:213], v[20:23]
	v_mfma_f32_16x16x32_bf16 v[16:19], v[186:189], v[210:213], v[16:19]
	v_mfma_f32_16x16x32_bf16 v[4:7], v[178:181], v[238:241], v[4:7]
	v_mfma_f32_16x16x32_bf16 v[0:3], v[186:189], v[238:241], v[0:3]
	s_barrier
	s_add_i32 s22, s22, 2
	s_add_u32 s21, s21, 0x100
	s_addc_u32 s92, s92, 0
	s_cmp_gt_u32 s22, 41
	s_mov_b64 s[8:9], s[10:11]
	s_cbranch_scc0 .LBB0_439
	v_lshl_add_u32 v140, s20, 8, v142
	v_lshl_or_b32 v138, s91, 8, v144
	v_lshlrev_b32_e32 v141, 11, v140
	v_lshl_add_u32 v138, v138, 1, v141
	v_lshlrev_b32_e32 v139, 3, v140
	s_mov_b64 s[8:9], s[4:5]
	global_load_dwordx4 v[146:149], v138, s[8:9]
	global_load_dwordx4 v[150:153], v138, s[8:9] offset:256
	s_add_u32 s8, s8, 0x8000
	s_addc_u32 s9, s9, 0
	global_load_dwordx4 v[154:157], v138, s[8:9]
	global_load_dwordx4 v[162:165], v138, s[8:9] offset:256
	s_add_u32 s8, s8, 0x8000
	s_addc_u32 s9, s9, 0
	global_load_dwordx4 v[166:169], v138, s[8:9]
	global_load_dwordx4 v[174:177], v138, s[8:9] offset:256
	s_add_u32 s8, s8, 0x8000
	s_addc_u32 s9, s9, 0
	global_load_dwordx4 v[178:181], v138, s[8:9]
	global_load_dwordx4 v[182:185], v138, s[8:9] offset:256
	s_add_u32 s8, s8, 0x28000
	s_addc_u32 s9, s9, 0
	global_load_dwordx4 v[186:189], v138, s[8:9]
	global_load_dwordx4 v[190:193], v138, s[8:9] offset:256
	s_add_u32 s8, s8, 0x8000
	s_addc_u32 s9, s9, 0
	global_load_dwordx4 v[194:197], v138, s[8:9]
	global_load_dwordx4 v[198:201], v138, s[8:9] offset:256
	s_add_u32 s8, s8, 0x8000
	s_addc_u32 s9, s9, 0
	global_load_dwordx4 v[202:205], v138, s[8:9]
	global_load_dwordx4 v[206:209], v138, s[8:9] offset:256
	s_add_u32 s8, s8, 0x8000
	s_addc_u32 s9, s9, 0
	global_load_dwordx4 v[210:213], v138, s[8:9]
	global_load_dwordx4 v[214:217], v138, s[8:9] offset:256
	s_and_b64 vcc, exec, s[36:37]
	s_cbranch_vccz .LBB0_442
	s_barrier

.LBB0_474:
	s_add_u32 s12, s10, 0xfffc0080
	s_addc_u32 s13, s11, -1
	s_add_i32 s22, 0, 0x10000
	s_cmp_eq_u32 s21, 12
	s_cselect_b32 s15, s20, s13
	s_cselect_b32 s14, s37, s12
	s_cselect_b32 s13, s41, s93
	s_cselect_b32 s12, s91, s92
	s_add_i32 s48, 0, 0x14000
	v_add_u32_e32 v154, s22, v147
	v_add_u32_e32 v158, s48, v147
	ds_read_b128 v[138:141], v154
	ds_read_b128 v[142:145], v154 offset:1024
	ds_read_b128 v[150:153], v154 offset:2048
	ds_read_b128 v[154:157], v154 offset:3072
	ds_read_b128 v[174:177], v158
	ds_read_b128 v[178:181], v158 offset:1024
	ds_read_b128 v[182:185], v158 offset:2048
	ds_read_b128 v[186:189], v158 offset:3072
	v_lshl_add_u64 v[158:159], s[10:11], 0, v[136:137]
	s_add_i32 m0, s30, 0xc000
	ds_read_b128 v[190:193], v149
	ds_read_b128 v[194:197], v149 offset:1024
	ds_read_b128 v[198:201], v149 offset:2048
	ds_read_b128 v[202:205], v149 offset:3072
	ds_read_b128 v[206:209], v149 offset:4096
	ds_read_b128 v[210:213], v149 offset:5120
	ds_read_b128 v[214:217], v149 offset:6144
	ds_read_b128 v[238:241], v149 offset:7168
	global_load_lds_dwordx4 v[158:159], off
	s_add_i32 m0, s30, 0xe000
	v_lshl_add_u64 v[158:159], s[10:11], 0, v[134:135]
	global_load_lds_dwordx4 v[158:159], off
	s_waitcnt vmcnt(8)
	s_waitcnt lgkmcnt(0)
	s_barrier
	v_mfma_f32_16x16x32_bf16 v[124:127], v[138:141], v[190:193], v[124:127]
	v_mfma_f32_16x16x32_bf16 v[116:119], v[150:153], v[190:193], v[116:119]
	v_mfma_f32_16x16x32_bf16 v[108:111], v[138:141], v[198:201], v[108:111]
	v_mfma_f32_16x16x32_bf16 v[100:103], v[150:153], v[198:201], v[100:103]
	v_mfma_f32_16x16x32_bf16 v[92:95], v[138:141], v[206:209], v[92:95]
	v_mfma_f32_16x16x32_bf16 v[84:87], v[150:153], v[206:209], v[84:87]
	v_mfma_f32_16x16x32_bf16 v[76:79], v[138:141], v[214:217], v[76:79]
	v_mfma_f32_16x16x32_bf16 v[64:67], v[150:153], v[214:217], v[64:67]
	v_mfma_f32_16x16x32_bf16 v[124:127], v[142:145], v[194:197], v[124:127]
	v_mfma_f32_16x16x32_bf16 v[116:119], v[154:157], v[194:197], v[116:119]
	v_mfma_f32_16x16x32_bf16 v[108:111], v[142:145], v[202:205], v[108:111]
	v_mfma_f32_16x16x32_bf16 v[100:103], v[154:157], v[202:205], v[100:103]
	v_mfma_f32_16x16x32_bf16 v[92:95], v[142:145], v[210:213], v[92:95]
	v_mfma_f32_16x16x32_bf16 v[84:87], v[154:157], v[210:213], v[84:87]
	v_mfma_f32_16x16x32_bf16 v[76:79], v[142:145], v[238:241], v[76:79]
	v_mfma_f32_16x16x32_bf16 v[64:67], v[154:157], v[238:241], v[64:67]
	v_mfma_f32_16x16x32_bf16 v[120:123], v[174:177], v[190:193], v[120:123]
	v_mfma_f32_16x16x32_bf16 v[112:115], v[182:185], v[190:193], v[112:115]
	v_mfma_f32_16x16x32_bf16 v[104:107], v[174:177], v[198:201], v[104:107]
	v_mfma_f32_16x16x32_bf16 v[96:99], v[182:185], v[198:201], v[96:99]
	v_mfma_f32_16x16x32_bf16 v[88:91], v[174:177], v[206:209], v[88:91]
	v_mfma_f32_16x16x32_bf16 v[80:83], v[182:185], v[206:209], v[80:83]
	v_mfma_f32_16x16x32_bf16 v[72:75], v[174:177], v[214:217], v[72:75]
	v_mfma_f32_16x16x32_bf16 v[68:71], v[182:185], v[214:217], v[68:71]
	v_mfma_f32_16x16x32_bf16 v[120:123], v[178:181], v[194:197], v[120:123]
	v_mfma_f32_16x16x32_bf16 v[112:115], v[186:189], v[194:197], v[112:115]
	v_mfma_f32_16x16x32_bf16 v[104:107], v[178:181], v[202:205], v[104:107]
	v_mfma_f32_16x16x32_bf16 v[96:99], v[186:189], v[202:205], v[96:99]
	v_mfma_f32_16x16x32_bf16 v[88:91], v[178:181], v[210:213], v[88:91]
	v_mfma_f32_16x16x32_bf16 v[80:83], v[186:189], v[210:213], v[80:83]
	v_mfma_f32_16x16x32_bf16 v[72:75], v[178:181], v[238:241], v[72:75]
	v_mfma_f32_16x16x32_bf16 v[68:71], v[186:189], v[238:241], v[68:71]
	s_barrier
	s_add_i32 s22, s22, s28
	v_lshl_add_u64 v[158:159], s[12:13], 0, v[160:161]
	s_mov_b32 m0, s22
	ds_read_b128 v[190:193], v149 offset:16384
	ds_read_b128 v[194:197], v149 offset:17408
	ds_read_b128 v[198:201], v149 offset:18432
	ds_read_b128 v[202:205], v149 offset:19456
	ds_read_b128 v[206:209], v149 offset:20480
	ds_read_b128 v[210:213], v149 offset:21504
	ds_read_b128 v[214:217], v149 offset:22528
	ds_read_b128 v[238:241], v149 offset:23552
	global_load_lds_dwordx4 v[158:159], off
	s_add_i32 m0, s22, 0x2000
	s_add_u32 s96, s12, 0x40000
	v_lshl_add_u64 v[162:163], s[12:13], 0, v[128:129]
	s_addc_u32 s97, s13, 0
	s_add_i32 s22, s48, s28
	global_load_lds_dwordx4 v[162:163], off
	v_lshl_add_u64 v[164:165], s[96:97], 0, v[160:161]
	s_mov_b32 m0, s22
	v_lshl_add_u64 v[166:167], s[14:15], 0, v[130:131]
	global_load_lds_dwordx4 v[164:165], off
	s_add_i32 m0, s22, 0x2000
	v_lshl_add_u64 v[164:165], s[96:97], 0, v[128:129]
	global_load_lds_dwordx4 v[164:165], off
	s_mov_b32 m0, s30
	v_lshl_add_u64 v[164:165], s[14:15], 0, v[132:133]
	global_load_lds_dwordx4 v[164:165], off
	s_mov_b32 m0, s31
	s_nop 0
	global_load_lds_dwordx4 v[166:167], off
	s_waitcnt vmcnt(8)
	s_waitcnt lgkmcnt(0)
	s_barrier
	v_mfma_f32_16x16x32_bf16 v[60:63], v[138:141], v[190:193], v[60:63]
	v_mfma_f32_16x16x32_bf16 v[48:51], v[150:153], v[190:193], v[48:51]
	v_mfma_f32_16x16x32_bf16 v[44:47], v[138:141], v[198:201], v[44:47]
	v_mfma_f32_16x16x32_bf16 v[32:35], v[150:153], v[198:201], v[32:35]
	v_mfma_f32_16x16x32_bf16 v[28:31], v[138:141], v[206:209], v[28:31]
	v_mfma_f32_16x16x32_bf16 v[16:19], v[150:153], v[206:209], v[16:19]
	v_mfma_f32_16x16x32_bf16 v[12:15], v[138:141], v[214:217], v[12:15]
	v_mfma_f32_16x16x32_bf16 v[0:3], v[150:153], v[214:217], v[0:3]
	v_mfma_f32_16x16x32_bf16 v[60:63], v[142:145], v[194:197], v[60:63]
	v_mfma_f32_16x16x32_bf16 v[48:51], v[154:157], v[194:197], v[48:51]
	v_mfma_f32_16x16x32_bf16 v[44:47], v[142:145], v[202:205], v[44:47]
	v_mfma_f32_16x16x32_bf16 v[32:35], v[154:157], v[202:205], v[32:35]
	v_mfma_f32_16x16x32_bf16 v[28:31], v[142:145], v[210:213], v[28:31]
	v_mfma_f32_16x16x32_bf16 v[16:19], v[154:157], v[210:213], v[16:19]
	v_mfma_f32_16x16x32_bf16 v[12:15], v[142:145], v[238:241], v[12:15]
	v_mfma_f32_16x16x32_bf16 v[0:3], v[154:157], v[238:241], v[0:3]
	v_mfma_f32_16x16x32_bf16 v[56:59], v[174:177], v[190:193], v[56:59]
	v_mfma_f32_16x16x32_bf16 v[52:55], v[182:185], v[190:193], v[52:55]
	v_mfma_f32_16x16x32_bf16 v[40:43], v[174:177], v[198:201], v[40:43]
	v_mfma_f32_16x16x32_bf16 v[36:39], v[182:185], v[198:201], v[36:39]
	v_mfma_f32_16x16x32_bf16 v[24:27], v[174:177], v[206:209], v[24:27]
	v_mfma_f32_16x16x32_bf16 v[20:23], v[182:185], v[206:209], v[20:23]
	v_mfma_f32_16x16x32_bf16 v[8:11], v[174:177], v[214:217], v[8:11]
	v_mfma_f32_16x16x32_bf16 v[4:7], v[182:185], v[214:217], v[4:7]
	v_mfma_f32_16x16x32_bf16 v[56:59], v[178:181], v[194:197], v[56:59]
	v_mfma_f32_16x16x32_bf16 v[52:55], v[186:189], v[194:197], v[52:55]
	v_mfma_f32_16x16x32_bf16 v[40:43], v[178:181], v[202:205], v[40:43]
	v_mfma_f32_16x16x32_bf16 v[36:39], v[186:189], v[202:205], v[36:39]
	v_mfma_f32_16x16x32_bf16 v[24:27], v[178:181], v[210:213], v[24:27]
	v_mfma_f32_16x16x32_bf16 v[20:23], v[186:189], v[210:213], v[20:23]
	v_mfma_f32_16x16x32_bf16 v[8:11], v[178:181], v[238:241], v[8:11]
	v_mfma_f32_16x16x32_bf16 v[4:7], v[186:189], v[238:241], v[4:7]
	s_barrier
	s_add_i32 s22, 0, 0x18000
	s_add_i32 s48, 0, 0x1c000
	v_add_u32_e32 v154, s22, v147
	v_add_u32_e32 v168, s48, v147
	ds_read_b128 v[138:141], v154
	ds_read_b128 v[142:145], v154 offset:1024
	ds_read_b128 v[150:153], v154 offset:2048
	ds_read_b128 v[154:157], v154 offset:3072
	ds_read_b128 v[174:177], v168
	ds_read_b128 v[178:181], v168 offset:1024
	ds_read_b128 v[182:185], v168 offset:2048
	ds_read_b128 v[186:189], v168 offset:3072
	s_add_u32 s14, s14, 0x40000
	s_addc_u32 s15, s15, 0
	s_mov_b32 m0, s33
	v_lshl_add_u64 v[168:169], s[14:15], 0, v[132:133]
	ds_read_b128 v[190:193], v149 offset:32768
	ds_read_b128 v[194:197], v149 offset:33792
	ds_read_b128 v[198:201], v149 offset:34816
	ds_read_b128 v[202:205], v149 offset:35840
	ds_read_b128 v[206:209], v149 offset:36864
	ds_read_b128 v[210:213], v149 offset:37888
	ds_read_b128 v[214:217], v149 offset:38912
	ds_read_b128 v[238:241], v149 offset:39936
	global_load_lds_dwordx4 v[168:169], off
	s_mov_b32 m0, s34
	v_lshl_add_u64 v[168:169], s[14:15], 0, v[130:131]
	global_load_lds_dwordx4 v[168:169], off
	s_waitcnt vmcnt(8)
	s_waitcnt lgkmcnt(0)
	s_barrier
	v_mfma_f32_16x16x32_bf16 v[124:127], v[138:141], v[190:193], v[124:127]
	v_mfma_f32_16x16x32_bf16 v[116:119], v[150:153], v[190:193], v[116:119]
	v_mfma_f32_16x16x32_bf16 v[108:111], v[138:141], v[198:201], v[108:111]
	v_mfma_f32_16x16x32_bf16 v[100:103], v[150:153], v[198:201], v[100:103]
	v_mfma_f32_16x16x32_bf16 v[92:95], v[138:141], v[206:209], v[92:95]
	v_mfma_f32_16x16x32_bf16 v[84:87], v[150:153], v[206:209], v[84:87]
	v_mfma_f32_16x16x32_bf16 v[76:79], v[138:141], v[214:217], v[76:79]
	v_mfma_f32_16x16x32_bf16 v[64:67], v[150:153], v[214:217], v[64:67]
	v_mfma_f32_16x16x32_bf16 v[124:127], v[142:145], v[194:197], v[124:127]
	v_mfma_f32_16x16x32_bf16 v[116:119], v[154:157], v[194:197], v[116:119]
	v_mfma_f32_16x16x32_bf16 v[108:111], v[142:145], v[202:205], v[108:111]
	v_mfma_f32_16x16x32_bf16 v[100:103], v[154:157], v[202:205], v[100:103]
	v_mfma_f32_16x16x32_bf16 v[92:95], v[142:145], v[210:213], v[92:95]
	v_mfma_f32_16x16x32_bf16 v[84:87], v[154:157], v[210:213], v[84:87]
	v_mfma_f32_16x16x32_bf16 v[76:79], v[142:145], v[238:241], v[76:79]
	v_mfma_f32_16x16x32_bf16 v[64:67], v[154:157], v[238:241], v[64:67]
	v_mfma_f32_16x16x32_bf16 v[120:123], v[174:177], v[190:193], v[120:123]
	v_mfma_f32_16x16x32_bf16 v[112:115], v[182:185], v[190:193], v[112:115]
	v_mfma_f32_16x16x32_bf16 v[104:107], v[174:177], v[198:201], v[104:107]
	v_mfma_f32_16x16x32_bf16 v[96:99], v[182:185], v[198:201], v[96:99]
	v_mfma_f32_16x16x32_bf16 v[88:91], v[174:177], v[206:209], v[88:91]
	v_mfma_f32_16x16x32_bf16 v[80:83], v[182:185], v[206:209], v[80:83]
	v_mfma_f32_16x16x32_bf16 v[72:75], v[174:177], v[214:217], v[72:75]
	v_mfma_f32_16x16x32_bf16 v[68:71], v[182:185], v[214:217], v[68:71]
	v_mfma_f32_16x16x32_bf16 v[120:123], v[178:181], v[194:197], v[120:123]
	v_mfma_f32_16x16x32_bf16 v[112:115], v[186:189], v[194:197], v[112:115]
	v_mfma_f32_16x16x32_bf16 v[104:107], v[178:181], v[202:205], v[104:107]
	v_mfma_f32_16x16x32_bf16 v[96:99], v[186:189], v[202:205], v[96:99]
	v_mfma_f32_16x16x32_bf16 v[88:91], v[178:181], v[210:213], v[88:91]
	v_mfma_f32_16x16x32_bf16 v[80:83], v[186:189], v[210:213], v[80:83]
	v_mfma_f32_16x16x32_bf16 v[72:75], v[178:181], v[238:241], v[72:75]
	v_mfma_f32_16x16x32_bf16 v[68:71], v[186:189], v[238:241], v[68:71]
	s_barrier
	s_add_i32 s14, s22, s28
	v_lshl_add_u64 v[158:159], v[158:159], 0, s[88:89]
	s_mov_b32 m0, s14
	ds_read_b128 v[190:193], v149 offset:49152
	ds_read_b128 v[194:197], v149 offset:50176
	ds_read_b128 v[198:201], v149 offset:51200
	ds_read_b128 v[202:205], v149 offset:52224
	ds_read_b128 v[206:209], v149 offset:53248
	ds_read_b128 v[210:213], v149 offset:54272
	ds_read_b128 v[214:217], v149 offset:55296
	ds_read_b128 v[238:241], v149 offset:56320
	global_load_lds_dwordx4 v[158:159], off
	s_add_i32 m0, s14, 0x2000
	s_add_u32 s12, s12, 0x40080
	v_lshl_add_u64 v[158:159], v[162:163], 0, s[88:89]
	s_addc_u32 s13, s13, 0
	s_add_i32 s14, s48, s28
	global_load_lds_dwordx4 v[158:159], off
	s_mov_b32 m0, s14
	v_lshl_add_u64 v[158:159], s[12:13], 0, v[160:161]
	global_load_lds_dwordx4 v[158:159], off
	s_add_i32 m0, s14, 0x2000
	v_lshl_add_u64 v[158:159], s[12:13], 0, v[128:129]
	global_load_lds_dwordx4 v[158:159], off
	s_mov_b32 m0, s35
	v_lshl_add_u64 v[158:159], v[164:165], 0, s[88:89]
	global_load_lds_dwordx4 v[158:159], off
	s_mov_b32 m0, s90
	v_lshl_add_u64 v[158:159], v[166:167], 0, s[88:89]
	global_load_lds_dwordx4 v[158:159], off
	s_waitcnt vmcnt(8)
	s_waitcnt lgkmcnt(0)
	s_barrier
	v_mfma_f32_16x16x32_bf16 v[60:63], v[138:141], v[190:193], v[60:63]
	v_mfma_f32_16x16x32_bf16 v[48:51], v[150:153], v[190:193], v[48:51]
	v_mfma_f32_16x16x32_bf16 v[44:47], v[138:141], v[198:201], v[44:47]
	v_mfma_f32_16x16x32_bf16 v[32:35], v[150:153], v[198:201], v[32:35]
	v_mfma_f32_16x16x32_bf16 v[28:31], v[138:141], v[206:209], v[28:31]
	v_mfma_f32_16x16x32_bf16 v[16:19], v[150:153], v[206:209], v[16:19]
	v_mfma_f32_16x16x32_bf16 v[12:15], v[138:141], v[214:217], v[12:15]
	v_mfma_f32_16x16x32_bf16 v[0:3], v[150:153], v[214:217], v[0:3]
	v_mfma_f32_16x16x32_bf16 v[60:63], v[142:145], v[194:197], v[60:63]
	v_mfma_f32_16x16x32_bf16 v[48:51], v[154:157], v[194:197], v[48:51]
	v_mfma_f32_16x16x32_bf16 v[44:47], v[142:145], v[202:205], v[44:47]
	v_mfma_f32_16x16x32_bf16 v[32:35], v[154:157], v[202:205], v[32:35]
	v_mfma_f32_16x16x32_bf16 v[28:31], v[142:145], v[210:213], v[28:31]
	v_mfma_f32_16x16x32_bf16 v[16:19], v[154:157], v[210:213], v[16:19]
	v_mfma_f32_16x16x32_bf16 v[12:15], v[142:145], v[238:241], v[12:15]
	v_mfma_f32_16x16x32_bf16 v[0:3], v[154:157], v[238:241], v[0:3]
	v_mfma_f32_16x16x32_bf16 v[56:59], v[174:177], v[190:193], v[56:59]
	v_mfma_f32_16x16x32_bf16 v[52:55], v[182:185], v[190:193], v[52:55]
	v_mfma_f32_16x16x32_bf16 v[40:43], v[174:177], v[198:201], v[40:43]
	v_mfma_f32_16x16x32_bf16 v[36:39], v[182:185], v[198:201], v[36:39]
	v_mfma_f32_16x16x32_bf16 v[24:27], v[174:177], v[206:209], v[24:27]
	v_mfma_f32_16x16x32_bf16 v[20:23], v[182:185], v[206:209], v[20:23]
	v_mfma_f32_16x16x32_bf16 v[8:11], v[174:177], v[214:217], v[8:11]
	v_mfma_f32_16x16x32_bf16 v[4:7], v[182:185], v[214:217], v[4:7]
	v_mfma_f32_16x16x32_bf16 v[56:59], v[178:181], v[194:197], v[56:59]
	v_mfma_f32_16x16x32_bf16 v[52:55], v[186:189], v[194:197], v[52:55]
	v_mfma_f32_16x16x32_bf16 v[40:43], v[178:181], v[202:205], v[40:43]
	v_mfma_f32_16x16x32_bf16 v[36:39], v[186:189], v[202:205], v[36:39]
	v_mfma_f32_16x16x32_bf16 v[24:27], v[178:181], v[210:213], v[24:27]
	v_mfma_f32_16x16x32_bf16 v[20:23], v[186:189], v[210:213], v[20:23]
	v_mfma_f32_16x16x32_bf16 v[8:11], v[178:181], v[238:241], v[8:11]
	v_mfma_f32_16x16x32_bf16 v[4:7], v[186:189], v[238:241], v[4:7]
	s_barrier
	s_add_i32 s21, s21, 2
	s_add_u32 s92, s92, 0x100
	s_addc_u32 s93, s93, 0
	s_add_u32 s10, s10, 0x100
	s_addc_u32 s11, s11, 0
	s_cmp_gt_u32 s21, 13
	s_cbranch_scc0 .LBB0_474
	v_lshl_add_u32 v192, s8, 8, v146
	v_lshlrev_b32_e32 v192, 3, v192
	global_load_dwordx2 v[176:177], v192, s[4:5]
	global_load_dwordx2 v[178:179], v192, s[4:5] offset:128
	global_load_dwordx2 v[180:181], v192, s[4:5] offset:256
	global_load_dwordx2 v[182:183], v192, s[4:5] offset:384
	global_load_dwordx2 v[184:185], v192, s[4:5] offset:1024
	global_load_dwordx2 v[186:187], v192, s[4:5] offset:1152
	global_load_dwordx2 v[188:189], v192, s[4:5] offset:1280
	global_load_dwordx2 v[190:191], v192, s[4:5] offset:1408
	s_and_b64 vcc, exec, s[6:7]
	s_cbranch_vccz .LBB0_477
	s_barrier
